# phase-1 conversion tail: last 21% of weight-conversion work claimed dynamically by all waves incl. GEMM workgroups after their tiles
# baseline (speedup 1.0000x reference)
; #define LAS __attribute__((address_space(3)))
; template <class F, bool NT = true> __device__ __forceinline__ void tr_run(F item, int first, int step, int n, LAS float* scr, int lane) {
;     if (first >= n) return;
;     TrDesc da = item(first), db = da, dc = da; f32x4 va[8], vb[8], vc[8];
;     tr_load<NT>(da, va, lane);
;     if (first + step < n) { db = item(first + step); tr_load<NT>(db, vb, lane); }
;     for (int it = first; it < n; it += 3 * step) {
;         const bool h1 = it + step < n, h2 = it + 2 * step < n, h3 = it + 3 * step < n, h4 = it + 4 * step < n;
;         if (h2) { dc = item(it + 2 * step); tr_load<NT>(dc, vc, lane); }
;         tr_finish<NT>(da, va, scr, lane);
;         if (h3) { da = item(it + 3 * step); tr_load<NT>(da, va, lane); }
;         if (h1) tr_finish<NT>(db, vb, scr, lane);
;         if (h4) { db = item(it + 4 * step); tr_load<NT>(db, vb, lane); }
;         if (h2) tr_finish<NT>(dc, vc, scr, lane);
;     }
; }
; __device__ __forceinline__ void p0b_convert(const Params& p, LAS unsigned char* lds, int tw, int ntw, int wave, int lane) {
;     P0Item pi{&p, P0A_ITEMS}; tr_run(pi, tw, ntw, P0_NITEMS - P0A_ITEMS, (LAS float*)(lds + wave * 8704), lane);
; }
; template <int layer>
; __device__ __forceinline__ void layer_phases(const Params& p, LAS unsigned char* lds, const XcdBarrier& bar, int lo, int hi, int G, int gw, int ngw, int wave, int lane) {
;     ...
;                     if ((int)blockIdx.x < NG) { pg8::StaticOrder S; S.init(MTOK, AB_MAIN, NG, (int)blockIdx.x); pg8::gemm_phase<pg8::EpiBf16<true>, pg8::StaticOrder, true, true>(lds, g, S, E); }
;                     else p0b_convert(p, lds, ((int)blockIdx.x - NG) * NWAVES + wave, (G - NG) * NWAVES, wave, lane);
.LBB0_443:
.LBB0_444:
.Lpost_getpc10:
.LBB0_446:
.Lpost_getpc2:
.LBB0_447:
.LBB0_448:
.Lpost_getpc11:
.LBB0_450:
.Lpost_getpc3:
.LBB0_451:
.LBB0_452:
.LBB0_453:
.LBB0_454:
.LBB0_455:
.LBB0_456:
.LBB0_457:
.LBB0_460:
.LBB0_461:
.LBB0_462:
.LBB0_463:
.LBB0_465:
.LBB0_467:
.LBB0_468:
.LBB0_469:
.LBB0_471:
.LBB0_472:
.LBB0_474:
.LBB0_475:
.LBB0_476:
.LBB0_478:
.LBB0_479:
.LBB0_480:
.LBB0_481:
.LBB0_483:
.LBB0_485:
.LBB0_486:
.LBB0_487:
.LBB0_489:
.LBB0_490:
.LBB0_491:
.LBB0_493:
.LBB0_494:
.LBB0_495:
.LBB0_496:
.LBB0_498:
.LBB0_500:
.LBB0_501:
.LBB0_502:
.LBB0_504:
.LBB0_505:
.LBB0_507:
.LBB0_509:
.LBB0_510:
.LBB0_512:
.LBB0_514:
.LBB0_515:
.LBB0_517:
.LBB0_519:
.LBB0_520:
.LBB0_522:
.LBB0_524:
.LBB0_525:
.LBB0_527:
.LBB0_529:
.LBB0_530:
.LBB0_532:
.LBB0_534:
.LBB0_535:
.LBB0_537:
.LBB0_539:
.LBB0_540:
.LBB0_542:
.LBB0_544:
.LBB0_545:
.LBB0_547:
.LBB0_549:
.LBB0_550:
.LBB0_553:
.LBB0_555:
.LBB0_556:
.LBB0_559:
.LBB0_561:
.LBB0_562:
.LBB0_565:
.LBB0_567:
.LBB0_568:
.LBB0_571:
.LBB0_573:
.LBB0_574:
.LBB0_577:
.LBB0_579:
.LBB0_580:
.LBB0_583:
.LBB0_585:
.LBB0_586:
.LBB0_589:
.LBB0_591:
.LBB0_592:
.LBB0_595:
.LBB0_597:
.LBB0_598:
.LBB0_601:
.LBB0_603:
.LBB0_604:
.LBB0_607:
.LBB0_609:
.LBB0_610:
.LBB0_613:
.LBB0_615:
.LBB0_616:
.LBB0_619:
.LBB0_621:
.LBB0_622:
.LBB0_625:
.LBB0_627:
.LBB0_628:
.LBB0_631:
.LBB0_633:
.LBB0_634:
.LBB0_637:
.LBB0_639:
.LBB0_640:
.LBB0_642:
.LBB0_643:
.LBB0_644:
.LBB0_645:
.LBB0_646:
.LBB0_647:
.LBB0_648:
.LBB0_650:
.LBB0_651:
.LBB0_652:
.LBB0_653:
.LBB0_654:
.LBB0_655:
.LBB0_656:
.LBB0_658:
.LBB0_659:
.LBB0_660:
.LBB0_661:
.LBB0_662:
.Lcv_entry:
	s_mov_b64 exec, -1
	v_readlane_b32 s9, v240, 0
	v_readlane_b32 s10, v240, 1
	v_readlane_b32 s24, v240, 2
	v_readlane_b32 s25, v240, 3
	s_sub_i32 s9, s9, 0xc0
	s_lshr_b32 s10, s10, 6
	s_lshl_b32 s9, s9, 3
	s_add_i32 s18, s9, s10
	s_sub_u32 s24, s24, 0xd0
	s_subb_u32 s25, s25, 0
	v_mbcnt_lo_u32_b32 v188, -1, 0
	v_mbcnt_hi_u32_b32 v188, -1, v188
	v_lshrrev_b32_e32 v3, 3, v188
	v_and_b32_e32 v132, 7, v188
	v_lshlrev_b32_e32 v186, 5, v3

; #define LAS __attribute__((address_space(3)))
; __device__ __forceinline__ unsigned cvt_pk_bf16(float lo, float hi) { unsigned r; asm volatile("v_cvt_pk_bf16_f32 %0, %1, %2" : "=v"(r) : "v"(lo), "v"(hi)); return r; }
; #define LDS_WAIT() asm volatile("s_waitcnt lgkmcnt(0)" ::: "memory")
; __device__ __forceinline__ unsigned cvt_pk_bf16(float lo, float hi) { unsigned r; asm volatile("v_cvt_pk_bf16_f32 %0, %1, %2" : "=v"(r) : "v"(lo), "v"(hi)); return r; }
; template <bool NT = true> __device__ __forceinline__ void tr_load(const TrDesc& d, f32x4 (&v)[8], int lane) {
;     const float* sp = d.src + (size_t)(lane >> 3) * d.ldn + 4 * (lane & 7);
; #pragma unroll
;     for (int i = 0; i < 8; ++i) v[i] = NT ? __builtin_nontemporal_load((const f32x4*)(sp + (size_t)(8 * i) * d.ldn)) : *(const f32x4*)(sp + (size_t)(8 * i) * d.ldn);
; }
; template <bool NT = true> __device__ __forceinline__ void tr_finish(const TrDesc& d, const f32x4 (&v)[8], LAS float* scr, int lane) {
;     const int c = lane & 7;
;     f32x4 g0 = {1.f, 1.f, 1.f, 1.f}, g1 = {1.f, 1.f, 1.f, 1.f};
;     if (d.gain) { g0 = *(const f32x4*)(d.gain + 8 * c); g1 = *(const f32x4*)(d.gain + 8 * c + 4); }
; #pragma unroll
;     for (int i = 0; i < 8; ++i) { LAS float* w = scr + (8 * i + (lane >> 3)) * 33 + 4 * c; w[0] = v[i].x; w[1] = v[i].y; w[2] = v[i].z; w[3] = v[i].w; }
;     LDS_WAIT(); asm volatile("" ::: "memory");
; #pragma unroll
;     for (int j = 0; j < 4; ++j) { const int n = (lane >> 3) + 8 * j; const LAS float* s = scr + (8 * c) * 33 + n;
;         u32x4 o; o.x = cvt_pk_bf16(s[0 * 33] * g0.x, s[1 * 33] * g0.y); o.y = cvt_pk_bf16(s[2 * 33] * g0.z, s[3 * 33] * g0.w); o.z = cvt_pk_bf16(s[4 * 33] * g1.x, s[5 * 33] * g1.y); o.w = cvt_pk_bf16(s[6 * 33] * g1.z, s[7 * 33] * g1.w);
;         if (NT) __builtin_nontemporal_store(o, (u32x4*)(d.dst + (size_t)n * d.K + 8 * c)); else *(u32x4*)(d.dst + (size_t)n * d.K + 8 * c) = o; }
.Lcv_back_4:
.Lcv_job_g1:
	s_load_dwordx2 s[60:61], s[24:25], 0x18
	s_load_dwordx2 s[62:63], s[24:25], 0xb8
	s_load_dwordx2 s[4:5], s[24:25], 0x10
	s_mov_b32 s6, 0xac00
	s_mov_b32 s7, 0x2000
	s_mov_b32 s75, 5
	s_and_b32 s9, s18, 63
	s_lshr_b32 s10, s18, 6
	s_add_i32 s10, s10, 4
	s_and_b32 s10, s10, 7
	s_sub_i32 s74, 85, s10
	s_lshr_b32 s74, s74, 3
	s_add_i32 s74, s74, 1
	s_lshl_b32 s11, s9, 6
	s_mul_i32 s11, s11, s6
	s_lshl_b32 s21, s10, 9
	s_add_u32 s11, s11, s21
	s_mul_i32 s23, s10, 256
	s_mul_i32 s23, s23, s7
	s_lshl_b32 s26, s9, 7
	s_add_u32 s23, s23, s26
	s_mov_b32 s70, 0x1000
	s_mov_b32 s71, 0
	s_mov_b32 s72, 0x1000000
	s_mov_b32 s73, 0
	s_waitcnt lgkmcnt(0)
	s_add_u32 s60, s60, 0xac00000
	s_addc_u32 s61, s61, 0
	s_add_u32 s60, s60, s11
	s_addc_u32 s61, s61, 0
	s_add_u32 s62, s62, 0x1f300000
	s_addc_u32 s63, s63, 0
	s_add_u32 s62, s62, s23
	s_addc_u32 s63, s63, 0
	s_lshl_b32 s26, s7, 5
	s_add_u32 s64, s62, s26
	s_addc_u32 s65, s63, 0
	s_add_u32 s66, s64, s26
	s_addc_u32 s67, s65, 0
	s_add_u32 s68, s66, s26
	s_addc_u32 s69, s67, 0
	s_add_u32 s4, s4, 0x4000
	s_addc_u32 s5, s5, 0
	s_lshl_b32 s26, s9, 8
	s_add_u32 s4, s4, s26
	s_addc_u32 s5, s5, 0
	s_mov_b32 s8, 1
	s_branch .Lcv_run
.Lcv_back_5:
	s_branch .Lcv_done
.Lcv_run:
	s_cmp_eq_u32 s74, 0
	s_cbranch_scc1 .Lcv_ret
	v_mul_lo_u32 v189, v3, s6
	v_lshlrev_b32_e32 v189, 3, v189
	v_lshl_add_u32 v174, v132, 4, v189
	v_add_u32_e32 v175, s6, v174
	v_add_u32_e32 v176, s6, v175
	v_add_u32_e32 v177, s6, v176
	v_add_u32_e32 v178, s6, v177
	v_add_u32_e32 v179, s6, v178
	v_add_u32_e32 v180, s6, v179
	v_add_u32_e32 v181, s6, v180
	v_lshlrev_b32_e32 v190, 2, v132
	v_mul_lo_u32 v190, v190, s7
	v_lshl_add_u32 v182, v3, 4, v190
	v_add_u32_e32 v183, s7, v182
	v_add_u32_e32 v184, s7, v183
	v_add_u32_e32 v185, s7, v184
	s_cmp_eq_u32 s8, 0
	s_cbranch_scc1 .Lcv_nogain
	global_load_dwordx4 v[166:169], v186, s[4:5]
	global_load_dwordx4 v[170:173], v186, s[4:5] offset:16
	global_load_dwordx4 v[4:7], v174, s[60:61] offset:0 nt
	global_load_dwordx4 v[8:11], v175, s[60:61] offset:0 nt
	global_load_dwordx4 v[12:15], v176, s[60:61] offset:0 nt
	global_load_dwordx4 v[16:19], v177, s[60:61] offset:0 nt
	global_load_dwordx4 v[20:23], v178, s[60:61] offset:0 nt
	global_load_dwordx4 v[24:27], v179, s[60:61] offset:0 nt
	global_load_dwordx4 v[28:31], v180, s[60:61] offset:0 nt
	global_load_dwordx4 v[32:35], v181, s[60:61] offset:0 nt
	global_load_dwordx4 v[36:39], v174, s[60:61] offset:128 nt
	global_load_dwordx4 v[40:43], v175, s[60:61] offset:128 nt
	global_load_dwordx4 v[44:47], v176, s[60:61] offset:128 nt
	global_load_dwordx4 v[48:51], v177, s[60:61] offset:128 nt
	global_load_dwordx4 v[52:55], v178, s[60:61] offset:128 nt
	global_load_dwordx4 v[56:59], v179, s[60:61] offset:128 nt
	global_load_dwordx4 v[60:63], v180, s[60:61] offset:128 nt
	global_load_dwordx4 v[64:67], v181, s[60:61] offset:128 nt
	global_load_dwordx4 v[68:71], v174, s[60:61] offset:256 nt
	global_load_dwordx4 v[72:75], v175, s[60:61] offset:256 nt
	global_load_dwordx4 v[76:79], v176, s[60:61] offset:256 nt
	global_load_dwordx4 v[80:83], v177, s[60:61] offset:256 nt
	global_load_dwordx4 v[84:87], v178, s[60:61] offset:256 nt
	global_load_dwordx4 v[88:91], v179, s[60:61] offset:256 nt
	global_load_dwordx4 v[92:95], v180, s[60:61] offset:256 nt
	global_load_dwordx4 v[96:99], v181, s[60:61] offset:256 nt
	global_load_dwordx4 v[100:103], v174, s[60:61] offset:384 nt
	global_load_dwordx4 v[104:107], v175, s[60:61] offset:384 nt
	global_load_dwordx4 v[108:111], v176, s[60:61] offset:384 nt
	global_load_dwordx4 v[112:115], v177, s[60:61] offset:384 nt
	global_load_dwordx4 v[116:119], v178, s[60:61] offset:384 nt
	global_load_dwordx4 v[120:123], v179, s[60:61] offset:384 nt
	global_load_dwordx4 v[124:127], v180, s[60:61] offset:384 nt
	global_load_dwordx4 v[128:131], v181, s[60:61] offset:384 nt
	s_add_u32 s60, s60, s70
	s_addc_u32 s61, s61, s71
	s_cmp_eq_u32 s74, 1
	s_cbranch_scc1 .Lcv_g_last
	s_waitcnt vmcnt(24)
	v_mul_f32_e32 v4, v166, v4
	v_mul_f32_e32 v5, v166, v5
	v_mul_f32_e32 v6, v166, v6
	v_mul_f32_e32 v7, v166, v7
	v_mul_f32_e32 v8, v167, v8
	v_mul_f32_e32 v9, v167, v9
	v_mul_f32_e32 v10, v167, v10
	v_mul_f32_e32 v11, v167, v11
	v_mul_f32_e32 v12, v168, v12
	v_mul_f32_e32 v13, v168, v13
	v_mul_f32_e32 v14, v168, v14
	v_mul_f32_e32 v15, v168, v15
	v_mul_f32_e32 v16, v169, v16
	v_mul_f32_e32 v17, v169, v17
	v_mul_f32_e32 v18, v169, v18
	v_mul_f32_e32 v19, v169, v19
	v_mul_f32_e32 v20, v170, v20
	v_mul_f32_e32 v21, v170, v21
	v_mul_f32_e32 v22, v170, v22
	v_mul_f32_e32 v23, v170, v23
	v_mul_f32_e32 v24, v171, v24
	v_mul_f32_e32 v25, v171, v25
	v_mul_f32_e32 v26, v171, v26
	v_mul_f32_e32 v27, v171, v27
	v_mul_f32_e32 v28, v172, v28
	v_mul_f32_e32 v29, v172, v29
	v_mul_f32_e32 v30, v172, v30
	v_mul_f32_e32 v31, v172, v31
	v_mul_f32_e32 v32, v173, v32
	v_mul_f32_e32 v33, v173, v33
	v_mul_f32_e32 v34, v173, v34
	v_mul_f32_e32 v35, v173, v35
	v_cvt_pk_bf16_f32 v188, v4, v8
	v_cvt_pk_bf16_f32 v189, v12, v16
	v_cvt_pk_bf16_f32 v190, v20, v24
	v_cvt_pk_bf16_f32 v191, v28, v32
	global_store_dwordx4 v182, v[188:191], s[62:63] nt
	v_cvt_pk_bf16_f32 v192, v5, v9
	v_cvt_pk_bf16_f32 v193, v13, v17
	v_cvt_pk_bf16_f32 v194, v21, v25
	v_cvt_pk_bf16_f32 v195, v29, v33
	global_store_dwordx4 v183, v[192:195], s[62:63] nt
	v_cvt_pk_bf16_f32 v196, v6, v10
	v_cvt_pk_bf16_f32 v197, v14, v18
	v_cvt_pk_bf16_f32 v198, v22, v26
	v_cvt_pk_bf16_f32 v199, v30, v34
	global_store_dwordx4 v184, v[196:199], s[62:63] nt
	v_cvt_pk_bf16_f32 v200, v7, v11
	v_cvt_pk_bf16_f32 v201, v15, v19
	v_cvt_pk_bf16_f32 v202, v23, v27
	v_cvt_pk_bf16_f32 v203, v31, v35
	global_store_dwordx4 v185, v[200:203], s[62:63] nt
	global_load_dwordx4 v[4:7], v174, s[60:61] offset:0 nt
	global_load_dwordx4 v[8:11], v175, s[60:61] offset:0 nt
	global_load_dwordx4 v[12:15], v176, s[60:61] offset:0 nt
	global_load_dwordx4 v[16:19], v177, s[60:61] offset:0 nt
	global_load_dwordx4 v[20:23], v178, s[60:61] offset:0 nt
	global_load_dwordx4 v[24:27], v179, s[60:61] offset:0 nt
	global_load_dwordx4 v[28:31], v180, s[60:61] offset:0 nt
	global_load_dwordx4 v[32:35], v181, s[60:61] offset:0 nt
	s_add_u32 s62, s62, s72
	s_addc_u32 s63, s63, s73
	s_waitcnt vmcnt(28)
; #define LAS __attribute__((address_space(3)))
; __device__ __forceinline__ unsigned cvt_pk_bf16(float lo, float hi) { unsigned r; asm volatile("v_cvt_pk_bf16_f32 %0, %1, %2" : "=v"(r) : "v"(lo), "v"(hi)); return r; }
; #define LDS_WAIT() asm volatile("s_waitcnt lgkmcnt(0)" ::: "memory")
; __device__ __forceinline__ unsigned cvt_pk_bf16(float lo, float hi) { unsigned r; asm volatile("v_cvt_pk_bf16_f32 %0, %1, %2" : "=v"(r) : "v"(lo), "v"(hi)); return r; }
; template <bool NT = true> __device__ __forceinline__ void tr_load(const TrDesc& d, f32x4 (&v)[8], int lane) {
;     const float* sp = d.src + (size_t)(lane >> 3) * d.ldn + 4 * (lane & 7);
; #pragma unroll
;     for (int i = 0; i < 8; ++i) v[i] = NT ? __builtin_nontemporal_load((const f32x4*)(sp + (size_t)(8 * i) * d.ldn)) : *(const f32x4*)(sp + (size_t)(8 * i) * d.ldn);
; }
; template <bool NT = true> __device__ __forceinline__ void tr_finish(const TrDesc& d, const f32x4 (&v)[8], LAS float* scr, int lane) {
;     const int c = lane & 7;
;     f32x4 g0 = {1.f, 1.f, 1.f, 1.f}, g1 = {1.f, 1.f, 1.f, 1.f};
;     if (d.gain) { g0 = *(const f32x4*)(d.gain + 8 * c); g1 = *(const f32x4*)(d.gain + 8 * c + 4); }
; #pragma unroll
;     for (int i = 0; i < 8; ++i) { LAS float* w = scr + (8 * i + (lane >> 3)) * 33 + 4 * c; w[0] = v[i].x; w[1] = v[i].y; w[2] = v[i].z; w[3] = v[i].w; }
;     LDS_WAIT(); asm volatile("" ::: "memory");
; #pragma unroll
;     for (int j = 0; j < 4; ++j) { const int n = (lane >> 3) + 8 * j; const LAS float* s = scr + (8 * c) * 33 + n;
;         u32x4 o; o.x = cvt_pk_bf16(s[0 * 33] * g0.x, s[1 * 33] * g0.y); o.y = cvt_pk_bf16(s[2 * 33] * g0.z, s[3 * 33] * g0.w); o.z = cvt_pk_bf16(s[4 * 33] * g1.x, s[5 * 33] * g1.y); o.w = cvt_pk_bf16(s[6 * 33] * g1.z, s[7 * 33] * g1.w);
;         if (NT) __builtin_nontemporal_store(o, (u32x4*)(d.dst + (size_t)n * d.K + 8 * c)); else *(u32x4*)(d.dst + (size_t)n * d.K + 8 * c) = o; }
	v_mul_f32_e32 v36, v166, v36
	v_mul_f32_e32 v37, v166, v37
	v_mul_f32_e32 v38, v166, v38
	v_mul_f32_e32 v39, v166, v39
	v_mul_f32_e32 v40, v167, v40
	v_mul_f32_e32 v41, v167, v41
	v_mul_f32_e32 v42, v167, v42
	v_mul_f32_e32 v43, v167, v43
	v_mul_f32_e32 v44, v168, v44
	v_mul_f32_e32 v45, v168, v45
	v_mul_f32_e32 v46, v168, v46
	v_mul_f32_e32 v47, v168, v47
	v_mul_f32_e32 v48, v169, v48
	v_mul_f32_e32 v49, v169, v49
	v_mul_f32_e32 v50, v169, v50
	v_mul_f32_e32 v51, v169, v51
	v_mul_f32_e32 v52, v170, v52
	v_mul_f32_e32 v53, v170, v53
	v_mul_f32_e32 v54, v170, v54
	v_mul_f32_e32 v55, v170, v55
	v_mul_f32_e32 v56, v171, v56
	v_mul_f32_e32 v57, v171, v57
	v_mul_f32_e32 v58, v171, v58
	v_mul_f32_e32 v59, v171, v59
	v_mul_f32_e32 v60, v172, v60
	v_mul_f32_e32 v61, v172, v61
	v_mul_f32_e32 v62, v172, v62
	v_mul_f32_e32 v63, v172, v63
	v_mul_f32_e32 v64, v173, v64
	v_mul_f32_e32 v65, v173, v65
	v_mul_f32_e32 v66, v173, v66
	v_mul_f32_e32 v67, v173, v67
	v_cvt_pk_bf16_f32 v188, v36, v40
	v_cvt_pk_bf16_f32 v189, v44, v48
	v_cvt_pk_bf16_f32 v190, v52, v56
	v_cvt_pk_bf16_f32 v191, v60, v64
	global_store_dwordx4 v182, v[188:191], s[64:65] nt
	v_cvt_pk_bf16_f32 v192, v37, v41
	v_cvt_pk_bf16_f32 v193, v45, v49
	v_cvt_pk_bf16_f32 v194, v53, v57
	v_cvt_pk_bf16_f32 v195, v61, v65
	global_store_dwordx4 v183, v[192:195], s[64:65] nt
	v_cvt_pk_bf16_f32 v196, v38, v42
	v_cvt_pk_bf16_f32 v197, v46, v50
	v_cvt_pk_bf16_f32 v198, v54, v58
	v_cvt_pk_bf16_f32 v199, v62, v66
	global_store_dwordx4 v184, v[196:199], s[64:65] nt
	v_cvt_pk_bf16_f32 v200, v39, v43
	v_cvt_pk_bf16_f32 v201, v47, v51
	v_cvt_pk_bf16_f32 v202, v55, v59
	v_cvt_pk_bf16_f32 v203, v63, v67
	global_store_dwordx4 v185, v[200:203], s[64:65] nt
	global_load_dwordx4 v[36:39], v174, s[60:61] offset:128 nt
	global_load_dwordx4 v[40:43], v175, s[60:61] offset:128 nt
	global_load_dwordx4 v[44:47], v176, s[60:61] offset:128 nt
	global_load_dwordx4 v[48:51], v177, s[60:61] offset:128 nt
	global_load_dwordx4 v[52:55], v178, s[60:61] offset:128 nt
	global_load_dwordx4 v[56:59], v179, s[60:61] offset:128 nt
	global_load_dwordx4 v[60:63], v180, s[60:61] offset:128 nt
	global_load_dwordx4 v[64:67], v181, s[60:61] offset:128 nt
	s_add_u32 s64, s64, s72
	s_addc_u32 s65, s65, s73
	s_waitcnt vmcnt(32)
	v_mul_f32_e32 v68, v166, v68
	v_mul_f32_e32 v69, v166, v69
	v_mul_f32_e32 v70, v166, v70
	v_mul_f32_e32 v71, v166, v71
	v_mul_f32_e32 v72, v167, v72
	v_mul_f32_e32 v73, v167, v73
	v_mul_f32_e32 v74, v167, v74
	v_mul_f32_e32 v75, v167, v75
	v_mul_f32_e32 v76, v168, v76
	v_mul_f32_e32 v77, v168, v77
	v_mul_f32_e32 v78, v168, v78
	v_mul_f32_e32 v79, v168, v79
	v_mul_f32_e32 v80, v169, v80
	v_mul_f32_e32 v81, v169, v81
	v_mul_f32_e32 v82, v169, v82
	v_mul_f32_e32 v83, v169, v83
	v_mul_f32_e32 v84, v170, v84
	v_mul_f32_e32 v85, v170, v85
	v_mul_f32_e32 v86, v170, v86
	v_mul_f32_e32 v87, v170, v87
	v_mul_f32_e32 v88, v171, v88
	v_mul_f32_e32 v89, v171, v89
	v_mul_f32_e32 v90, v171, v90
	v_mul_f32_e32 v91, v171, v91
	v_mul_f32_e32 v92, v172, v92
	v_mul_f32_e32 v93, v172, v93
	v_mul_f32_e32 v94, v172, v94
	v_mul_f32_e32 v95, v172, v95
	v_mul_f32_e32 v96, v173, v96
	v_mul_f32_e32 v97, v173, v97
	v_mul_f32_e32 v98, v173, v98
	v_mul_f32_e32 v99, v173, v99
	v_cvt_pk_bf16_f32 v188, v68, v72
	v_cvt_pk_bf16_f32 v189, v76, v80
	v_cvt_pk_bf16_f32 v190, v84, v88
	v_cvt_pk_bf16_f32 v191, v92, v96
	global_store_dwordx4 v182, v[188:191], s[66:67] nt
	v_cvt_pk_bf16_f32 v192, v69, v73
	v_cvt_pk_bf16_f32 v193, v77, v81
	v_cvt_pk_bf16_f32 v194, v85, v89
	v_cvt_pk_bf16_f32 v195, v93, v97
	global_store_dwordx4 v183, v[192:195], s[66:67] nt
	v_cvt_pk_bf16_f32 v196, v70, v74
	v_cvt_pk_bf16_f32 v197, v78, v82
	v_cvt_pk_bf16_f32 v198, v86, v90
	v_cvt_pk_bf16_f32 v199, v94, v98
	global_store_dwordx4 v184, v[196:199], s[66:67] nt
	v_cvt_pk_bf16_f32 v200, v71, v75
	v_cvt_pk_bf16_f32 v201, v79, v83
	v_cvt_pk_bf16_f32 v202, v87, v91
	v_cvt_pk_bf16_f32 v203, v95, v99
	global_store_dwordx4 v185, v[200:203], s[66:67] nt
	global_load_dwordx4 v[68:71], v174, s[60:61] offset:256 nt
	global_load_dwordx4 v[72:75], v175, s[60:61] offset:256 nt
	global_load_dwordx4 v[76:79], v176, s[60:61] offset:256 nt
	global_load_dwordx4 v[80:83], v177, s[60:61] offset:256 nt
	global_load_dwordx4 v[84:87], v178, s[60:61] offset:256 nt
	global_load_dwordx4 v[88:91], v179, s[60:61] offset:256 nt
	global_load_dwordx4 v[92:95], v180, s[60:61] offset:256 nt
	global_load_dwordx4 v[96:99], v181, s[60:61] offset:256 nt
	s_add_u32 s66, s66, s72
	s_addc_u32 s67, s67, s73
	s_waitcnt vmcnt(36)
	v_mul_f32_e32 v100, v166, v100
	v_mul_f32_e32 v101, v166, v101
	v_mul_f32_e32 v102, v166, v102
	v_mul_f32_e32 v103, v166, v103
	v_mul_f32_e32 v104, v167, v104
	v_mul_f32_e32 v105, v167, v105
	v_mul_f32_e32 v106, v167, v106
	v_mul_f32_e32 v107, v167, v107
	v_mul_f32_e32 v108, v168, v108
	v_mul_f32_e32 v109, v168, v109
	v_mul_f32_e32 v110, v168, v110
	v_mul_f32_e32 v111, v168, v111
	v_mul_f32_e32 v112, v169, v112
	v_mul_f32_e32 v113, v169, v113
	v_mul_f32_e32 v114, v169, v114
	v_mul_f32_e32 v115, v169, v115
	v_mul_f32_e32 v116, v170, v116
	v_mul_f32_e32 v117, v170, v117
	v_mul_f32_e32 v118, v170, v118
	v_mul_f32_e32 v119, v170, v119
	v_mul_f32_e32 v120, v171, v120
	v_mul_f32_e32 v121, v171, v121
	v_mul_f32_e32 v122, v171, v122
	v_mul_f32_e32 v123, v171, v123
	v_mul_f32_e32 v124, v172, v124
	v_mul_f32_e32 v125, v172, v125
	v_mul_f32_e32 v126, v172, v126
	v_mul_f32_e32 v127, v172, v127
	v_mul_f32_e32 v128, v173, v128
	v_mul_f32_e32 v129, v173, v129
	v_mul_f32_e32 v130, v173, v130
	v_mul_f32_e32 v131, v173, v131
	v_cvt_pk_bf16_f32 v188, v100, v104
	v_cvt_pk_bf16_f32 v189, v108, v112
	v_cvt_pk_bf16_f32 v190, v116, v120
	v_cvt_pk_bf16_f32 v191, v124, v128
	global_store_dwordx4 v182, v[188:191], s[68:69] nt
	v_cvt_pk_bf16_f32 v192, v101, v105
	v_cvt_pk_bf16_f32 v193, v109, v113
	v_cvt_pk_bf16_f32 v194, v117, v121
	v_cvt_pk_bf16_f32 v195, v125, v129
	global_store_dwordx4 v183, v[192:195], s[68:69] nt
	v_cvt_pk_bf16_f32 v196, v102, v106
	v_cvt_pk_bf16_f32 v197, v110, v114
	v_cvt_pk_bf16_f32 v198, v118, v122
	v_cvt_pk_bf16_f32 v199, v126, v130
	global_store_dwordx4 v184, v[196:199], s[68:69] nt
	v_cvt_pk_bf16_f32 v200, v103, v107
	v_cvt_pk_bf16_f32 v201, v111, v115
	v_cvt_pk_bf16_f32 v202, v119, v123
	v_cvt_pk_bf16_f32 v203, v127, v131
	global_store_dwordx4 v185, v[200:203], s[68:69] nt
	global_load_dwordx4 v[100:103], v174, s[60:61] offset:384 nt
	global_load_dwordx4 v[104:107], v175, s[60:61] offset:384 nt
	global_load_dwordx4 v[108:111], v176, s[60:61] offset:384 nt
	global_load_dwordx4 v[112:115], v177, s[60:61] offset:384 nt
	global_load_dwordx4 v[116:119], v178, s[60:61] offset:384 nt
	global_load_dwordx4 v[120:123], v179, s[60:61] offset:384 nt
	global_load_dwordx4 v[124:127], v180, s[60:61] offset:384 nt
	global_load_dwordx4 v[128:131], v181, s[60:61] offset:384 nt
	s_add_u32 s68, s68, s72
	s_addc_u32 s69, s69, s73
	s_add_u32 s60, s60, s70
	s_addc_u32 s61, s61, s71
	s_sub_i32 s74, s74, 1
	s_cmp_eq_u32 s74, 1
	s_cbranch_scc1 .Lcv_g_last

; #define LAS __attribute__((address_space(3)))
; template <class F, bool NT = true> __device__ __forceinline__ void tr_run(F item, int first, int step, int n, LAS float* scr, int lane) {
;     if (first >= n) return;
;     TrDesc da = item(first), db = da, dc = da; f32x4 va[8], vb[8], vc[8];
;     tr_load<NT>(da, va, lane);
;     if (first + step < n) { db = item(first + step); tr_load<NT>(db, vb, lane); }
;     for (int it = first; it < n; it += 3 * step) {
.Lcv_ret:
	s_cmp_eq_u32 s75, 0
	s_cbranch_scc1 .Lcv_back_0
	s_cmp_eq_u32 s75, 1
	s_cbranch_scc1 .Lcv_back_1
	s_cmp_eq_u32 s75, 2
	s_cbranch_scc1 .Lcv_back_2
	s_cmp_eq_u32 s75, 3
	s_cbranch_scc1 .Lcv_back_3
	s_cmp_eq_u32 s75, 4
	s_cbranch_scc1 .Lcv_back_4
	s_cmp_eq_u32 s75, 5
	s_cbranch_scc1 .Lcv_back_5
.Lcv_done:
	s_branch .LBB0_663

; #define PG8_STAGE(bufoff, gbase, voff) do { _Pragma("unroll") for (int _i = 0; _i < 2; ++_i) \
;         __builtin_amdgcn_global_load_lds((const unsigned*)((const char*)(gbase) + (voff)[_i]), (PG8_LAS unsigned*)(lds + (bufoff) + ldsw + _i * 8192), 16, 0, 0); } while (0)
; #define PG8_LDA(dst, b, h) do { _Pragma("unroll") for (int m = 0; m < 4; ++m) _Pragma("unroll") for (int k = 0; k < 2; ++k) dst[m][k] = *(const PG8_LAS bf16x8*)(lds + PG8_SA(b, h) + aoff + m * 2048 + k * 1024); } while (0)
; #define PG8_LDB(dst, b, h) do { _Pragma("unroll") for (int n = 0; n < 2; ++n) _Pragma("unroll") for (int k = 0; k < 2; ++k) dst[n][k] = *(const PG8_LAS bf16x8*)(lds + PG8_SB(b, h) + boff + n * 2048 + k * 1024); } while (0)
; #define PG8_MMA(ai, bj, At, Bt) do { __builtin_amdgcn_s_setprio(1); _Pragma("unroll") for (int m = 0; m < 4; ++m) _Pragma("unroll") for (int n = 0; n < 2; ++n) _Pragma("unroll") for (int k = 0; k < 2; ++k) \
;         acc[ai][bj][m][n] = __builtin_amdgcn_mfma_f32_16x16x32_bf16(Bt[n][k], At[m][k], acc[ai][bj][m][n], 0, 0, 0); __builtin_amdgcn_s_setprio(0); } while (0)
; #define PG8_WAIT_V(n) asm volatile("s_waitcnt vmcnt(" #n ")" ::: "memory")
; #define PG8_WAIT_L(n) asm volatile("s_waitcnt lgkmcnt(" #n ")" ::: "memory")
; template <class Epi, class Sched, bool ALIGN_EPI = false, bool SP2 = false>
; __device__ __forceinline__ void gemm_phase(PG8_LAS unsigned char* lds, const Gemm g, const Sched& S, const Epi& E) {
;     ...
;             const bool last = (t == nt - 2);
;             const char* a1 = cA + (size_t)(t + 1) * kstep;
;             const char* a2 = last ? nA : cA + (size_t)(t + 2) * kstep; const char* b2 = last ? nB : cB + (size_t)(t + 2) * kstep;
;             const char* a3 = a2 + kstep; const char* b3 = b2 + kstep;
;             if (last && has_next) S.a_ready(nxt);
;             if constexpr (SP2) {
;             PG8_LDB(B0, 0, 0); PG8_LDB(B1, 0, 1); PG8_SCHED; PG8_LDA(At, 0, 0); PG8_STAGE(PG8_SA(1, 1), a1 + hstep, voffA);
;             PG8_WAIT_V(8); PG8_WAIT_L(0); PG8_BAR; PG8_MMA(0, 0, At, B0); PG8_MMA(0, 1, At, B1); PG8_BAR; PG8_SCHED;
;             PG8_LDA(At, 0, 1); PG8_STAGE(PG8_SB(0, 0), b2, voffB); PG8_STAGE(PG8_SB(0, 1), b2 + hstep, voffB); PG8_STAGE(PG8_SA(0, 0), a2, voffA);
;             PG8_WAIT_V(8); PG8_WAIT_L(0); PG8_BAR; PG8_MMA(1, 0, At, B0); PG8_MMA(1, 1, At, B1); PG8_BAR; PG8_SCHED;
.LBB0_673:
	ds_read_b128 v[148:151], v241 offset:0
	ds_read_b128 v[156:159], v241 offset:1024
	ds_read_b128 v[166:169], v241 offset:2048
	ds_read_b128 v[170:173], v241 offset:3072
	ds_read_b128 v[174:177], v241 offset:16384
	ds_read_b128 v[178:181], v241 offset:17408
	ds_read_b128 v[182:185], v241 offset:18432
	ds_read_b128 v[186:189], v241 offset:19456
	s_add_u32 s20, s22, 0xfff00080
	s_addc_u32 s21, s23, -1
	s_cmp_eq_u32 s35, 60
	s_cselect_b32 s25, s11, s21
	s_cselect_b32 s24, s52, s20
	s_cselect_b32 s21, s13, s34
	s_cselect_b32 s20, s53, s62
	s_add_i32 m0, s19, 0xc000
	ds_read_b128 v[190:193], v161
	ds_read_b128 v[194:197], v161 offset:1024
	ds_read_b128 v[198:201], v161 offset:2048
	ds_read_b128 v[202:205], v161 offset:3072
	ds_read_b128 v[206:209], v161 offset:4096
	ds_read_b128 v[210:213], v161 offset:5120
	ds_read_b128 v[214:217], v161 offset:6144
	ds_read_b128 v[218:221], v161 offset:7168
	global_load_lds_dwordx4 v138, s[22:23]
	s_add_i32 m0, s19, 0xe000
	s_nop 0
	global_load_lds_dwordx4 v140, s[22:23]
	s_waitcnt vmcnt(8)
	s_waitcnt lgkmcnt(0)
	s_barrier
	s_waitcnt lgkmcnt(0)
	v_mfma_f32_16x16x32_bf16 v[118:121], v[148:151], v[190:193], v[118:121]
	v_mfma_f32_16x16x32_bf16 v[114:117], v[166:169], v[190:193], v[114:117]
	v_mfma_f32_16x16x32_bf16 v[102:105], v[148:151], v[198:201], v[102:105]
	v_mfma_f32_16x16x32_bf16 v[98:101], v[166:169], v[198:201], v[98:101]
	v_mfma_f32_16x16x32_bf16 v[86:89], v[148:151], v[206:209], v[86:89]
	v_mfma_f32_16x16x32_bf16 v[82:85], v[166:169], v[206:209], v[82:85]
	v_mfma_f32_16x16x32_bf16 v[70:73], v[148:151], v[214:217], v[70:73]
	v_mfma_f32_16x16x32_bf16 v[66:69], v[166:169], v[214:217], v[66:69]
	v_mfma_f32_16x16x32_bf16 v[118:121], v[156:159], v[194:197], v[118:121]
	v_mfma_f32_16x16x32_bf16 v[114:117], v[170:173], v[194:197], v[114:117]
	v_mfma_f32_16x16x32_bf16 v[102:105], v[156:159], v[202:205], v[102:105]
	v_mfma_f32_16x16x32_bf16 v[98:101], v[170:173], v[202:205], v[98:101]
	v_mfma_f32_16x16x32_bf16 v[86:89], v[156:159], v[210:213], v[86:89]
	v_mfma_f32_16x16x32_bf16 v[82:85], v[170:173], v[210:213], v[82:85]
	v_mfma_f32_16x16x32_bf16 v[70:73], v[156:159], v[218:221], v[70:73]
	v_mfma_f32_16x16x32_bf16 v[66:69], v[170:173], v[218:221], v[66:69]
	v_mfma_f32_16x16x32_bf16 v[126:129], v[174:177], v[190:193], v[126:129]
	v_mfma_f32_16x16x32_bf16 v[122:125], v[182:185], v[190:193], v[122:125]
	v_mfma_f32_16x16x32_bf16 v[110:113], v[174:177], v[198:201], v[110:113]
	v_mfma_f32_16x16x32_bf16 v[106:109], v[182:185], v[198:201], v[106:109]
	v_mfma_f32_16x16x32_bf16 v[94:97], v[174:177], v[206:209], v[94:97]
	v_mfma_f32_16x16x32_bf16 v[90:93], v[182:185], v[206:209], v[90:93]
	v_mfma_f32_16x16x32_bf16 v[78:81], v[174:177], v[214:217], v[78:81]
	v_mfma_f32_16x16x32_bf16 v[74:77], v[182:185], v[214:217], v[74:77]
	v_mfma_f32_16x16x32_bf16 v[126:129], v[178:181], v[194:197], v[126:129]
	v_mfma_f32_16x16x32_bf16 v[122:125], v[186:189], v[194:197], v[122:125]
	v_mfma_f32_16x16x32_bf16 v[110:113], v[178:181], v[202:205], v[110:113]
	v_mfma_f32_16x16x32_bf16 v[106:109], v[186:189], v[202:205], v[106:109]
	v_mfma_f32_16x16x32_bf16 v[94:97], v[178:181], v[210:213], v[94:97]
	v_mfma_f32_16x16x32_bf16 v[90:93], v[186:189], v[210:213], v[90:93]
	v_mfma_f32_16x16x32_bf16 v[78:81], v[178:181], v[218:221], v[78:81]
	v_mfma_f32_16x16x32_bf16 v[74:77], v[186:189], v[218:221], v[74:77]
	s_barrier
	s_add_i32 s63, s43, s26
	s_mov_b32 m0, s63
	ds_read_b128 v[190:193], v161 offset:16384
	ds_read_b128 v[194:197], v161 offset:17408
	ds_read_b128 v[198:201], v161 offset:18432
	ds_read_b128 v[202:205], v161 offset:19456
	ds_read_b128 v[206:209], v161 offset:20480
	ds_read_b128 v[210:213], v161 offset:21504
	ds_read_b128 v[214:217], v161 offset:22528
	ds_read_b128 v[218:221], v161 offset:23552
	global_load_lds_dwordx4 v132, s[20:21]
	s_add_i32 m0, s63, 0x2000
	s_add_u32 s64, s20, 0x100000
	s_addc_u32 s65, s21, 0
	s_add_i32 s63, s46, s26
	global_load_lds_dwordx4 v136, s[20:21]
	s_mov_b32 m0, s63
	s_add_u32 s100, s24, 0x80
	s_addc_u32 s101, s25, 0
	global_load_lds_dwordx4 v132, s[64:65]
	s_add_i32 m0, s63, 0x2000
	s_nop 0
	global_load_lds_dwordx4 v136, s[64:65]
	s_mov_b32 m0, s19
	s_nop 0
	global_load_lds_dwordx4 v130, s[24:25]
	s_mov_b32 m0, s29
	s_nop 0
	global_load_lds_dwordx4 v134, s[24:25]
	s_waitcnt vmcnt(8)
	s_waitcnt lgkmcnt(0)
	s_barrier
	s_waitcnt lgkmcnt(0)
	v_mfma_f32_16x16x32_bf16 v[54:57], v[148:151], v[190:193], v[54:57]
	v_mfma_f32_16x16x32_bf16 v[50:53], v[166:169], v[190:193], v[50:53]
	v_mfma_f32_16x16x32_bf16 v[38:41], v[148:151], v[198:201], v[38:41]
	v_mfma_f32_16x16x32_bf16 v[34:37], v[166:169], v[198:201], v[34:37]
	v_mfma_f32_16x16x32_bf16 v[22:25], v[148:151], v[206:209], v[22:25]
	v_mfma_f32_16x16x32_bf16 v[18:21], v[166:169], v[206:209], v[18:21]
	v_mfma_f32_16x16x32_bf16 v[6:9], v[148:151], v[214:217], v[6:9]
	v_mfma_f32_16x16x32_bf16 v[2:5], v[166:169], v[214:217], v[2:5]
	v_mfma_f32_16x16x32_bf16 v[54:57], v[156:159], v[194:197], v[54:57]
	v_mfma_f32_16x16x32_bf16 v[50:53], v[170:173], v[194:197], v[50:53]
	v_mfma_f32_16x16x32_bf16 v[38:41], v[156:159], v[202:205], v[38:41]
	v_mfma_f32_16x16x32_bf16 v[34:37], v[170:173], v[202:205], v[34:37]
	v_mfma_f32_16x16x32_bf16 v[22:25], v[156:159], v[210:213], v[22:25]
	v_mfma_f32_16x16x32_bf16 v[18:21], v[170:173], v[210:213], v[18:21]
	v_mfma_f32_16x16x32_bf16 v[6:9], v[156:159], v[218:221], v[6:9]
	v_mfma_f32_16x16x32_bf16 v[2:5], v[170:173], v[218:221], v[2:5]
	v_mfma_f32_16x16x32_bf16 v[62:65], v[174:177], v[190:193], v[62:65]
	v_mfma_f32_16x16x32_bf16 v[58:61], v[182:185], v[190:193], v[58:61]
	v_mfma_f32_16x16x32_bf16 v[46:49], v[174:177], v[198:201], v[46:49]
	v_mfma_f32_16x16x32_bf16 v[42:45], v[182:185], v[198:201], v[42:45]
	v_mfma_f32_16x16x32_bf16 v[30:33], v[174:177], v[206:209], v[30:33]
	v_mfma_f32_16x16x32_bf16 v[26:29], v[182:185], v[206:209], v[26:29]
	v_mfma_f32_16x16x32_bf16 v[10:13], v[174:177], v[214:217], v[10:13]
	v_mfma_f32_16x16x32_bf16 v[14:17], v[182:185], v[214:217], v[14:17]
	v_mfma_f32_16x16x32_bf16 v[62:65], v[178:181], v[194:197], v[62:65]
	v_mfma_f32_16x16x32_bf16 v[58:61], v[186:189], v[194:197], v[58:61]
	v_mfma_f32_16x16x32_bf16 v[46:49], v[178:181], v[202:205], v[46:49]
	v_mfma_f32_16x16x32_bf16 v[42:45], v[186:189], v[202:205], v[42:45]
	v_mfma_f32_16x16x32_bf16 v[30:33], v[178:181], v[210:213], v[30:33]
	v_mfma_f32_16x16x32_bf16 v[26:29], v[186:189], v[210:213], v[26:29]
	v_mfma_f32_16x16x32_bf16 v[10:13], v[178:181], v[218:221], v[10:13]
	v_mfma_f32_16x16x32_bf16 v[14:17], v[186:189], v[218:221], v[14:17]
	s_barrier
; #define PG8_STAGE(bufoff, gbase, voff) do { _Pragma("unroll") for (int _i = 0; _i < 2; ++_i) \
;         __builtin_amdgcn_global_load_lds((const unsigned*)((const char*)(gbase) + (voff)[_i]), (PG8_LAS unsigned*)(lds + (bufoff) + ldsw + _i * 8192), 16, 0, 0); } while (0)
; #define PG8_LDA(dst, b, h) do { _Pragma("unroll") for (int m = 0; m < 4; ++m) _Pragma("unroll") for (int k = 0; k < 2; ++k) dst[m][k] = *(const PG8_LAS bf16x8*)(lds + PG8_SA(b, h) + aoff + m * 2048 + k * 1024); } while (0)
; #define PG8_LDB(dst, b, h) do { _Pragma("unroll") for (int n = 0; n < 2; ++n) _Pragma("unroll") for (int k = 0; k < 2; ++k) dst[n][k] = *(const PG8_LAS bf16x8*)(lds + PG8_SB(b, h) + boff + n * 2048 + k * 1024); } while (0)
; #define PG8_MMA(ai, bj, At, Bt) do { __builtin_amdgcn_s_setprio(1); _Pragma("unroll") for (int m = 0; m < 4; ++m) _Pragma("unroll") for (int n = 0; n < 2; ++n) _Pragma("unroll") for (int k = 0; k < 2; ++k) \
;         acc[ai][bj][m][n] = __builtin_amdgcn_mfma_f32_16x16x32_bf16(Bt[n][k], At[m][k], acc[ai][bj][m][n], 0, 0, 0); __builtin_amdgcn_s_setprio(0); } while (0)
; #define PG8_WAIT_V(n) asm volatile("s_waitcnt vmcnt(" #n ")" ::: "memory")
; #define PG8_WAIT_L(n) asm volatile("s_waitcnt lgkmcnt(" #n ")" ::: "memory")
; #define PG8_BAR __builtin_amdgcn_s_barrier()
; #define PG8_SCHED __builtin_amdgcn_sched_barrier(0)
; template <class Epi, class Sched, bool ALIGN_EPI = false, bool SP2 = false>
; __device__ __forceinline__ void gemm_phase(PG8_LAS unsigned char* lds, const Gemm g, const Sched& S, const Epi& E) {
;     ...
;             PG8_LDB(B0, 1, 0); PG8_LDB(B1, 1, 1); PG8_SCHED; PG8_LDA(At, 1, 0); PG8_STAGE(PG8_SA(0, 1), a2 + hstep, voffA);
;             PG8_WAIT_V(8); PG8_WAIT_L(0); PG8_BAR; PG8_MMA(0, 0, At, B0); PG8_MMA(0, 1, At, B1); PG8_BAR; PG8_SCHED;
;             PG8_LDA(At, 1, 1); PG8_STAGE(PG8_SB(1, 0), b3, voffB); PG8_STAGE(PG8_SB(1, 1), b3 + hstep, voffB); PG8_STAGE(PG8_SA(1, 0), a3, voffA);
;             PG8_WAIT_V(8); PG8_WAIT_L(0); PG8_BAR; PG8_MMA(1, 0, At, B0); PG8_MMA(1, 1, At, B1); PG8_BAR; PG8_SCHED;
	s_add_i32 s63, 0, 0x18000
	s_add_i32 s64, 0, 0x1c000
	ds_read_b128 v[148:151], v241 offset:32768
	ds_read_b128 v[156:159], v241 offset:33792
	ds_read_b128 v[166:169], v241 offset:34816
	ds_read_b128 v[170:173], v241 offset:35840
	ds_read_b128 v[174:177], v241 offset:49152
	ds_read_b128 v[178:181], v241 offset:50176
	ds_read_b128 v[182:185], v241 offset:51200
	ds_read_b128 v[186:189], v241 offset:52224
	s_add_u32 s24, s24, 0x100000
	s_addc_u32 s25, s25, 0
	s_mov_b32 m0, s30
	ds_read_b128 v[190:193], v161 offset:32768
	ds_read_b128 v[194:197], v161 offset:33792
	ds_read_b128 v[198:201], v161 offset:34816
	ds_read_b128 v[202:205], v161 offset:35840
	ds_read_b128 v[206:209], v161 offset:36864
	ds_read_b128 v[210:213], v161 offset:37888
	ds_read_b128 v[214:217], v161 offset:38912
	ds_read_b128 v[218:221], v161 offset:39936
	global_load_lds_dwordx4 v130, s[24:25]
	s_mov_b32 m0, s31
	s_nop 0
	global_load_lds_dwordx4 v134, s[24:25]
	s_waitcnt vmcnt(8)
	s_waitcnt lgkmcnt(0)
	s_barrier
	s_waitcnt lgkmcnt(0)
	v_mfma_f32_16x16x32_bf16 v[118:121], v[148:151], v[190:193], v[118:121]
	v_mfma_f32_16x16x32_bf16 v[114:117], v[166:169], v[190:193], v[114:117]
	v_mfma_f32_16x16x32_bf16 v[102:105], v[148:151], v[198:201], v[102:105]
	v_mfma_f32_16x16x32_bf16 v[98:101], v[166:169], v[198:201], v[98:101]
	v_mfma_f32_16x16x32_bf16 v[86:89], v[148:151], v[206:209], v[86:89]
	v_mfma_f32_16x16x32_bf16 v[82:85], v[166:169], v[206:209], v[82:85]
	v_mfma_f32_16x16x32_bf16 v[70:73], v[148:151], v[214:217], v[70:73]
	v_mfma_f32_16x16x32_bf16 v[66:69], v[166:169], v[214:217], v[66:69]
	v_mfma_f32_16x16x32_bf16 v[118:121], v[156:159], v[194:197], v[118:121]
	v_mfma_f32_16x16x32_bf16 v[114:117], v[170:173], v[194:197], v[114:117]
	v_mfma_f32_16x16x32_bf16 v[102:105], v[156:159], v[202:205], v[102:105]
	v_mfma_f32_16x16x32_bf16 v[98:101], v[170:173], v[202:205], v[98:101]
	v_mfma_f32_16x16x32_bf16 v[86:89], v[156:159], v[210:213], v[86:89]
	v_mfma_f32_16x16x32_bf16 v[82:85], v[170:173], v[210:213], v[82:85]
	v_mfma_f32_16x16x32_bf16 v[70:73], v[156:159], v[218:221], v[70:73]
	v_mfma_f32_16x16x32_bf16 v[66:69], v[170:173], v[218:221], v[66:69]
	v_mfma_f32_16x16x32_bf16 v[126:129], v[174:177], v[190:193], v[126:129]
	v_mfma_f32_16x16x32_bf16 v[122:125], v[182:185], v[190:193], v[122:125]
	v_mfma_f32_16x16x32_bf16 v[110:113], v[174:177], v[198:201], v[110:113]
	v_mfma_f32_16x16x32_bf16 v[106:109], v[182:185], v[198:201], v[106:109]
	v_mfma_f32_16x16x32_bf16 v[94:97], v[174:177], v[206:209], v[94:97]
	v_mfma_f32_16x16x32_bf16 v[90:93], v[182:185], v[206:209], v[90:93]
	v_mfma_f32_16x16x32_bf16 v[78:81], v[174:177], v[214:217], v[78:81]
	v_mfma_f32_16x16x32_bf16 v[74:77], v[182:185], v[214:217], v[74:77]
	v_mfma_f32_16x16x32_bf16 v[126:129], v[178:181], v[194:197], v[126:129]
	v_mfma_f32_16x16x32_bf16 v[122:125], v[186:189], v[194:197], v[122:125]
	v_mfma_f32_16x16x32_bf16 v[110:113], v[178:181], v[202:205], v[110:113]
	v_mfma_f32_16x16x32_bf16 v[106:109], v[186:189], v[202:205], v[106:109]
	v_mfma_f32_16x16x32_bf16 v[94:97], v[178:181], v[210:213], v[94:97]
	v_mfma_f32_16x16x32_bf16 v[90:93], v[186:189], v[210:213], v[90:93]
	v_mfma_f32_16x16x32_bf16 v[78:81], v[178:181], v[218:221], v[78:81]
	v_mfma_f32_16x16x32_bf16 v[74:77], v[186:189], v[218:221], v[74:77]
	s_barrier
	s_add_i32 s24, s63, s26
	s_add_i32 m0, s24, 0xffffff80
	ds_read_b128 v[190:193], v161 offset:49152
	ds_read_b128 v[194:197], v161 offset:50176
	ds_read_b128 v[198:201], v161 offset:51200
	ds_read_b128 v[202:205], v161 offset:52224
	ds_read_b128 v[206:209], v161 offset:53248
	ds_read_b128 v[210:213], v161 offset:54272
	ds_read_b128 v[214:217], v161 offset:55296
	ds_read_b128 v[218:221], v161 offset:56320
	global_load_lds_dwordx4 v132, s[20:21] offset:128
	s_add_i32 m0, s24, 0x1f80
	s_add_i32 s24, s64, s26
	global_load_lds_dwordx4 v136, s[20:21] offset:128
	s_add_u32 s20, s20, 0x100080
	s_addc_u32 s21, s21, 0
	s_mov_b32 m0, s24
	s_nop 0
	global_load_lds_dwordx4 v132, s[20:21]
	s_add_i32 m0, s24, 0x2000
	s_nop 0
	global_load_lds_dwordx4 v136, s[20:21]
	s_mov_b32 m0, s40
	s_nop 0
	global_load_lds_dwordx4 v130, s[100:101]
	s_mov_b32 m0, s41
	s_nop 0
	global_load_lds_dwordx4 v134, s[100:101]
	s_waitcnt vmcnt(8)
	s_waitcnt lgkmcnt(0)
	s_barrier
	s_waitcnt lgkmcnt(0)
	v_mfma_f32_16x16x32_bf16 v[54:57], v[148:151], v[190:193], v[54:57]
	v_mfma_f32_16x16x32_bf16 v[50:53], v[166:169], v[190:193], v[50:53]
	v_mfma_f32_16x16x32_bf16 v[38:41], v[148:151], v[198:201], v[38:41]
	v_mfma_f32_16x16x32_bf16 v[34:37], v[166:169], v[198:201], v[34:37]
	v_mfma_f32_16x16x32_bf16 v[22:25], v[148:151], v[206:209], v[22:25]
	v_mfma_f32_16x16x32_bf16 v[18:21], v[166:169], v[206:209], v[18:21]
	v_mfma_f32_16x16x32_bf16 v[6:9], v[148:151], v[214:217], v[6:9]
	v_mfma_f32_16x16x32_bf16 v[2:5], v[166:169], v[214:217], v[2:5]
	v_mfma_f32_16x16x32_bf16 v[54:57], v[156:159], v[194:197], v[54:57]
	v_mfma_f32_16x16x32_bf16 v[50:53], v[170:173], v[194:197], v[50:53]
	v_mfma_f32_16x16x32_bf16 v[38:41], v[156:159], v[202:205], v[38:41]
	v_mfma_f32_16x16x32_bf16 v[34:37], v[170:173], v[202:205], v[34:37]
	v_mfma_f32_16x16x32_bf16 v[22:25], v[156:159], v[210:213], v[22:25]
	v_mfma_f32_16x16x32_bf16 v[18:21], v[170:173], v[210:213], v[18:21]
	v_mfma_f32_16x16x32_bf16 v[6:9], v[156:159], v[218:221], v[6:9]
	v_mfma_f32_16x16x32_bf16 v[2:5], v[170:173], v[218:221], v[2:5]
	v_mfma_f32_16x16x32_bf16 v[62:65], v[174:177], v[190:193], v[62:65]
	v_mfma_f32_16x16x32_bf16 v[58:61], v[182:185], v[190:193], v[58:61]
	v_mfma_f32_16x16x32_bf16 v[46:49], v[174:177], v[198:201], v[46:49]
	v_mfma_f32_16x16x32_bf16 v[42:45], v[182:185], v[198:201], v[42:45]
	v_mfma_f32_16x16x32_bf16 v[30:33], v[174:177], v[206:209], v[30:33]
	v_mfma_f32_16x16x32_bf16 v[26:29], v[182:185], v[206:209], v[26:29]
	v_mfma_f32_16x16x32_bf16 v[10:13], v[174:177], v[214:217], v[10:13]
	v_mfma_f32_16x16x32_bf16 v[14:17], v[182:185], v[214:217], v[14:17]
	v_mfma_f32_16x16x32_bf16 v[62:65], v[178:181], v[194:197], v[62:65]
	v_mfma_f32_16x16x32_bf16 v[58:61], v[186:189], v[194:197], v[58:61]
	v_mfma_f32_16x16x32_bf16 v[46:49], v[178:181], v[202:205], v[46:49]
	v_mfma_f32_16x16x32_bf16 v[42:45], v[186:189], v[202:205], v[42:45]
	v_mfma_f32_16x16x32_bf16 v[30:33], v[178:181], v[210:213], v[30:33]
	v_mfma_f32_16x16x32_bf16 v[26:29], v[186:189], v[210:213], v[26:29]
	v_mfma_f32_16x16x32_bf16 v[10:13], v[178:181], v[218:221], v[10:13]
	v_mfma_f32_16x16x32_bf16 v[14:17], v[186:189], v[218:221], v[14:17]
	s_barrier
	s_add_i32 s35, s35, 2
	s_add_u32 s22, s22, 0x100
	s_addc_u32 s23, s23, 0
	s_add_u32 s62, s62, 0x100
	s_addc_u32 s34, s34, 0
	s_cmp_gt_u32 s35, 61
	s_cbranch_scc0 .LBB0_673
	s_and_b64 vcc, exec, s[8:9]
	s_cbranch_vccz .LBB0_676
	s_barrier

; #define TR_JOB_GU(W_, WT_, off_, gain_) { constexpr int nnb_ = DFF / 32, nit_ = (DM / 64) * nnb_; \
;     if (r < nit_) { const int kb_ = r / nnb_, nb_ = r % nnb_, c0_ = 32 * nb_; \
;         return TrDesc{(W_) + (size_t)(64 * kb_) * DFF + c0_, (WT_) + (size_t)(256 * (c0_ / 128) + (c0_ % 128) + (off_)) * DM + 64 * kb_, (gain_) + 64 * kb_, DFF, DM}; } r -= nit_; }
; __device__ __forceinline__ TrDesc p0_item(const Params& p, int it) {
;     ...
;     TR_JOB_GU(p.ffn_w_up + (size_t)DM * DFF, WGU1, 128, p.norm_ffn + DM)
.LBB0_680:
.Ldy_entry:
	s_mov_b64 exec, -1
	v_readlane_b32 s24, v240, 2
	v_readlane_b32 s25, v240, 3
	s_sub_u32 s24, s24, 0xd0
	s_subb_u32 s25, s25, 0
	v_mbcnt_lo_u32_b32 v188, -1, 0
	v_mbcnt_hi_u32_b32 v188, -1, v188
	v_lshrrev_b32_e32 v3, 3, v188
	v_and_b32_e32 v132, 7, v188
	v_lshlrev_b32_e32 v186, 5, v3
.Ldy_job_u1:
.Ldy_claim_0:
	s_load_dwordx2 s[62:63], s[24:25], 0xb8
	v_mov_b32_e32 v189, 0
	v_mov_b32_e32 v190, 1
	s_waitcnt lgkmcnt(0)
	s_add_u32 s62, s62, 0xf0000
	s_addc_u32 s63, s63, 0
	s_mov_b64 exec, 1
	global_atomic_add v189, v189, v190, s[62:63] offset:0 sc0
	s_waitcnt vmcnt(0)
	s_mov_b64 exec, -1
	v_readfirstlane_b32 s18, v189
	s_cmp_ge_u32 s18, 2048
	s_cbranch_scc1 .Ldy_skip_0
	s_load_dwordx2 s[60:61], s[24:25], 0x20
	s_load_dwordx2 s[62:63], s[24:25], 0xb8
	s_load_dwordx2 s[4:5], s[24:25], 0x10
	s_mov_b32 s6, 0xac00
	s_mov_b32 s7, 0x2000
	s_mov_b32 s75, 0
	s_and_b32 s9, s18, 63
	s_lshr_b32 s10, s18, 6
	s_add_i32 s10, s10, 0
	s_and_b32 s10, s10, 31
	s_sub_i32 s74, 85, s10
	s_lshr_b32 s74, s74, 5
	s_add_i32 s74, s74, 1
	s_lshl_b32 s11, s9, 6
	s_mul_i32 s11, s11, s6
	s_lshl_b32 s21, s10, 9
	s_add_u32 s11, s11, s21
	s_mul_i32 s23, s10, 256
	s_add_i32 s23, s23, 128
	s_mul_i32 s23, s23, s7
	s_lshl_b32 s26, s9, 7
	s_add_u32 s23, s23, s26
	s_mov_b32 s70, 0x4000
	s_mov_b32 s71, 0
	s_mov_b32 s72, 0x4000000
	s_mov_b32 s73, 0
	s_waitcnt lgkmcnt(0)
	s_add_u32 s60, s60, 0xac00000
	s_addc_u32 s61, s61, 0
	s_add_u32 s60, s60, s11
	s_addc_u32 s61, s61, 0
	s_add_u32 s62, s62, 0x1f300000
	s_addc_u32 s63, s63, 0
	s_add_u32 s62, s62, s23
	s_addc_u32 s63, s63, 0
	s_lshl_b32 s26, s7, 5
	s_add_u32 s64, s62, s26
	s_addc_u32 s65, s63, 0
	s_add_u32 s66, s64, s26
	s_addc_u32 s67, s65, 0
	s_add_u32 s68, s66, s26
	s_addc_u32 s69, s67, 0
	s_add_u32 s4, s4, 0x4000
	s_addc_u32 s5, s5, 0
	s_lshl_b32 s26, s9, 8
	s_add_u32 s4, s4, s26
	s_addc_u32 s5, s5, 0
	s_mov_b32 s8, 1
	s_branch .Ldy_run

; __device__ __forceinline__ TrDesc p0_item(const Params& p, int it) {
;     ...
;     TR_JOB(p.cd_w_out, DM, DM, 0, DM, (bf16_t*)(ws + WS_WCD_OUT), 0, (const float*)nullptr)
.Ldy_skip_0:
.Ldy_job_cdo:
.Ldy_claim_1:
	s_load_dwordx2 s[62:63], s[24:25], 0xb8
	v_mov_b32_e32 v189, 0
	v_mov_b32_e32 v190, 1
	s_waitcnt lgkmcnt(0)
	s_add_u32 s62, s62, 0xf0000
	s_addc_u32 s63, s63, 0
	s_mov_b64 exec, 1
	global_atomic_add v189, v189, v190, s[62:63] offset:4 sc0
	s_waitcnt vmcnt(0)
	s_mov_b64 exec, -1
	v_readfirstlane_b32 s18, v189
	s_cmp_ge_u32 s18, 2048
	s_cbranch_scc1 .Ldy_skip_1
	s_load_dwordx2 s[60:61], s[24:25], 0xa0
	s_load_dwordx2 s[62:63], s[24:25], 0xb8
	s_mov_b32 s6, 0x4000
	s_mov_b32 s7, 0x2000
	s_mov_b32 s75, 1
	s_and_b32 s9, s18, 63
	s_lshr_b32 s10, s18, 6
	s_add_i32 s10, s10, 0
	s_and_b32 s10, s10, 31
	s_sub_i32 s74, 31, s10
	s_lshr_b32 s74, s74, 5
	s_add_i32 s74, s74, 1
	s_lshl_b32 s11, s9, 6
	s_mul_i32 s11, s11, s6
	s_lshl_b32 s21, s10, 9
	s_add_u32 s11, s11, s21
	s_mul_i32 s23, s10, 128
	s_mul_i32 s23, s23, s7
	s_lshl_b32 s26, s9, 7
	s_add_u32 s23, s23, s26
	s_mov_b32 s70, 0x4000
	s_mov_b32 s71, 0
	s_mov_b32 s72, 0x2000000
	s_mov_b32 s73, 0
	s_waitcnt lgkmcnt(0)
	s_add_u32 s60, s60, s11
	s_addc_u32 s61, s61, 0
	s_add_u32 s62, s62, 0x1d300000
	s_addc_u32 s63, s63, 0
	s_add_u32 s62, s62, s23
	s_addc_u32 s63, s63, 0
	s_lshl_b32 s26, s7, 5
	s_add_u32 s64, s62, s26
	s_addc_u32 s65, s63, 0
	s_add_u32 s66, s64, s26
	s_addc_u32 s67, s65, 0
	s_add_u32 s68, s66, s26
	s_addc_u32 s69, s67, 0
	s_mov_b32 s8, 0
	s_branch .Ldy_run

; __device__ __forceinline__ TrDesc p0_item(const Params& p, int it) {
;     ...
;     const int mat = r / 32, rr = r % 32, kb_ = rr / 8, nb_ = rr % 8;
;     const float* W = (mat < 8 ? p.rg_w_x : p.rg_w_a) + (size_t)(mat & 7) * 65536;
;     return TrDesc{W + (size_t)(64 * kb_) * 256 + 32 * nb_, WRG + (size_t)mat * 65536 + (size_t)(32 * nb_) * 256 + 64 * kb_, nullptr, 256, 256};
.Ldy_skip_1:
.Ldy_job_rgx:
.Ldy_claim_2:
	s_load_dwordx2 s[62:63], s[24:25], 0xb8
	v_mov_b32_e32 v189, 0
	v_mov_b32_e32 v190, 1
	s_waitcnt lgkmcnt(0)
	s_add_u32 s62, s62, 0xf0000
	s_addc_u32 s63, s63, 0
	s_mov_b64 exec, 1
	global_atomic_add v189, v189, v190, s[62:63] offset:8 sc0
	s_waitcnt vmcnt(0)
	s_mov_b64 exec, -1
	v_readfirstlane_b32 s18, v189
	s_cmp_ge_u32 s18, 64
	s_cbranch_scc1 .Ldy_skip_2
	s_load_dwordx2 s[60:61], s[24:25], 0x78
	s_load_dwordx2 s[62:63], s[24:25], 0xb8
	s_mov_b32 s6, 0x400
	s_mov_b32 s7, 0x200
	s_mov_b32 s75, 2
	s_sub_i32 s9, s18, 0
	s_cmp_lt_u32 s9, 64
	s_cselect_b32 s74, 1, 0
	s_and_b32 s9, s9, 63
	s_lshr_b32 s10, s9, 3
	s_bfe_u32 s21, s9, 0x20001
	s_and_b32 s26, s9, 1
	s_lshl_b32 s11, s10, 18
	s_lshl_b32 s27, s21, 16
	s_add_u32 s11, s11, s27
	s_lshl_b32 s27, s26, 9
	s_add_u32 s11, s11, s27
	s_lshl_b32 s23, s10, 17
	s_lshl_b32 s27, s26, 16
	s_add_u32 s23, s23, s27
	s_lshl_b32 s27, s21, 7
	s_add_u32 s23, s23, s27
	s_mov_b32 s70, 0
	s_mov_b32 s71, 0
	s_mov_b32 s72, 0
	s_mov_b32 s73, 0
	s_waitcnt lgkmcnt(0)
	s_add_u32 s60, s60, s11
	s_addc_u32 s61, s61, 0
	s_add_u32 s62, s62, 0x2f600000
	s_addc_u32 s63, s63, 0
	s_add_u32 s62, s62, s23
	s_addc_u32 s63, s63, 0
	s_lshl_b32 s26, s7, 5
	s_add_u32 s64, s62, s26
	s_addc_u32 s65, s63, 0
	s_add_u32 s66, s64, s26
	s_addc_u32 s67, s65, 0
	s_add_u32 s68, s66, s26
	s_addc_u32 s69, s67, 0
	s_mov_b32 s8, 0
	s_branch .Ldy_run

; __device__ __forceinline__ TrDesc p0_item(const Params& p, int it) {
;     ...
;     const int mat = r / 32, rr = r % 32, kb_ = rr / 8, nb_ = rr % 8;
;     const float* W = (mat < 8 ? p.rg_w_x : p.rg_w_a) + (size_t)(mat & 7) * 65536;
;     return TrDesc{W + (size_t)(64 * kb_) * 256 + 32 * nb_, WRG + (size_t)mat * 65536 + (size_t)(32 * nb_) * 256 + 64 * kb_, nullptr, 256, 256};
.Ldy_skip_2:
.Ldy_job_rga:
.Ldy_claim_3:
	s_load_dwordx2 s[62:63], s[24:25], 0xb8
	v_mov_b32_e32 v189, 0
	v_mov_b32_e32 v190, 1
	s_waitcnt lgkmcnt(0)
	s_add_u32 s62, s62, 0xf0000
	s_addc_u32 s63, s63, 0
	s_mov_b64 exec, 1
	global_atomic_add v189, v189, v190, s[62:63] offset:12 sc0
	s_waitcnt vmcnt(0)
	s_mov_b64 exec, -1
	v_readfirstlane_b32 s18, v189
	s_cmp_ge_u32 s18, 64
	s_cbranch_scc1 .Ldy_skip_3
	s_load_dwordx2 s[60:61], s[24:25], 0x88
	s_load_dwordx2 s[62:63], s[24:25], 0xb8
	s_mov_b32 s6, 0x400
	s_mov_b32 s7, 0x200
	s_mov_b32 s75, 3
	s_sub_i32 s9, s18, 0
	s_cmp_lt_u32 s9, 64
	s_cselect_b32 s74, 1, 0
	s_and_b32 s9, s9, 63
	s_lshr_b32 s10, s9, 3
	s_bfe_u32 s21, s9, 0x20001
	s_and_b32 s26, s9, 1
	s_lshl_b32 s11, s10, 18
	s_lshl_b32 s27, s21, 16
	s_add_u32 s11, s11, s27
	s_lshl_b32 s27, s26, 9
	s_add_u32 s11, s11, s27
	s_lshl_b32 s23, s10, 17
	s_lshl_b32 s27, s26, 16
	s_add_u32 s23, s23, s27
	s_lshl_b32 s27, s21, 7
	s_add_u32 s23, s23, s27
	s_mov_b32 s70, 0
	s_mov_b32 s71, 0
	s_mov_b32 s72, 0
	s_mov_b32 s73, 0
	s_waitcnt lgkmcnt(0)
	s_add_u32 s60, s60, s11
	s_addc_u32 s61, s61, 0
	s_add_u32 s62, s62, 0x2f700000
	s_addc_u32 s63, s63, 0
	s_add_u32 s62, s62, s23
	s_addc_u32 s63, s63, 0
	s_lshl_b32 s26, s7, 5
	s_add_u32 s64, s62, s26
	s_addc_u32 s65, s63, 0
	s_add_u32 s66, s64, s26
	s_addc_u32 s67, s65, 0
	s_add_u32 s68, s66, s26
	s_addc_u32 s69, s67, 0
	s_mov_b32 s8, 0
	s_branch .Ldy_run
.Ldy_back_3:
	s_branch .Ldy_claim_3
.Ldy_skip_3:
	s_branch .Ldy_done

; __device__ __forceinline__ unsigned xb_ld(unsigned* p)              { return __hip_atomic_load(p, __ATOMIC_RELAXED, __HIP_MEMORY_SCOPE_AGENT); }
; __device__ __forceinline__ void xcd_barrier_complete(unsigned* bar, unsigned x, unsigned& nloc, unsigned& nx) {
;     const unsigned G = gridDim.x * gridDim.y * gridDim.z;
;     unsigned sum, cnt, mine, sp = 0u;
;     for (;;) {
;         sum = 0u; cnt = 0u; mine = 0u;
; #pragma unroll
;         for (unsigned j = 0; j < 16; ++j) { const unsigned c = xb_ld(&bar[XB_XCNT(j)]); sum += c; cnt += (c > 0u) ? 1u : 0u; mine = (j == x) ? c : mine; }
; __device__ __forceinline__ void xcd_barrier(const XcdBarrier& b) {
;     asm volatile("s_waitcnt vmcnt(0)" ::: "memory");
;     __syncthreads();
;     if (threadIdx.x == 0) {
;         unsigned* bar = b.bar;
;         __builtin_amdgcn_s_waitcnt(0);
;         unsigned nloc = b.st[0], nx = b.st[1];
;         if (nloc == 0u) { xcd_barrier_complete(bar, b.x, nloc, nx); b.st[0] = nloc; b.st[1] = nx; }
.Ldy_ret:
	s_cmp_eq_u32 s75, 0
	s_cbranch_scc1 .Ldy_back_0
	s_cmp_eq_u32 s75, 1
	s_cbranch_scc1 .Ldy_back_1
	s_cmp_eq_u32 s75, 2
	s_cbranch_scc1 .Ldy_back_2
	s_cmp_eq_u32 s75, 3
	s_cbranch_scc1 .Ldy_back_3
.Ldy_done:
	v_readlane_b32 s40, v240, 31
	v_readlane_b32 s41, v240, 32
	s_cmp_lt_i32 s41, 3
	v_readlane_b32 s42, v240, 33
	v_readlane_b32 s43, v240, 34
	s_cbranch_scc1 .LBB0_734
	s_waitcnt vmcnt(0)
	s_barrier
	s_mov_b64 s[0:1], exec
	v_readlane_b32 s2, v240, 23
	v_readlane_b32 s3, v240, 24
	s_and_b64 s[2:3], s[0:1], s[2:3]
	s_mov_b64 exec, s[2:3]
	s_cbranch_execz .LBB0_733
	s_add_i32 s2, 0, 0x20160
	s_waitcnt vmcnt(7)
	v_mov_b32_e32 v2, s2
	s_waitcnt vmcnt(0) expcnt(0) lgkmcnt(0)
	ds_read_b32 v4, v2
	s_add_i32 s2, 0, 0x20164
	v_mov_b32_e32 v2, s2
	ds_read_b32 v2, v2
	s_waitcnt lgkmcnt(1)
	v_cmp_ne_u32_e32 vcc, 0, v4
	s_cbranch_vccnz .LBB0_697
	v_readlane_b32 s2, v240, 2
	v_readlane_b32 s3, v240, 3
	s_load_dwordx2 s[6:7], s[2:3], 0x4
	v_readlane_b32 s8, v240, 20
	v_readlane_b32 s9, v240, 21
	s_add_u32 s2, s8, 0x1000
	s_addc_u32 s3, s9, 0
	s_add_u32 s4, s8, 0x1100
	s_addc_u32 s5, s9, 0
	s_waitcnt lgkmcnt(0)
	s_mul_i32 s16, s6, s92
	s_add_u32 s6, s8, 0x1200
	s_mul_i32 s16, s16, s7
	s_addc_u32 s7, s9, 0
	s_add_u32 s8, s8, 0x1300
	s_addc_u32 s9, s9, 0
	s_mov_b32 s17, 1
	v_mov_b32_e32 v18, 0
	s_branch .LBB0_685

; #define PG8_STAGE(bufoff, gbase, voff) do { _Pragma("unroll") for (int _i = 0; _i < 2; ++_i) \
;         __builtin_amdgcn_global_load_lds((const unsigned*)((const char*)(gbase) + (voff)[_i]), (PG8_LAS unsigned*)(lds + (bufoff) + ldsw + _i * 8192), 16, 0, 0); } while (0)
; #define PG8_LDA(dst, b, h) do { _Pragma("unroll") for (int m = 0; m < 4; ++m) _Pragma("unroll") for (int k = 0; k < 2; ++k) dst[m][k] = *(const PG8_LAS bf16x8*)(lds + PG8_SA(b, h) + aoff + m * 2048 + k * 1024); } while (0)
; #define PG8_LDB(dst, b, h) do { _Pragma("unroll") for (int n = 0; n < 2; ++n) _Pragma("unroll") for (int k = 0; k < 2; ++k) dst[n][k] = *(const PG8_LAS bf16x8*)(lds + PG8_SB(b, h) + boff + n * 2048 + k * 1024); } while (0)
; #define PG8_MMA(ai, bj, At, Bt) do { __builtin_amdgcn_s_setprio(1); _Pragma("unroll") for (int m = 0; m < 4; ++m) _Pragma("unroll") for (int n = 0; n < 2; ++n) _Pragma("unroll") for (int k = 0; k < 2; ++k) \
;         acc[ai][bj][m][n] = __builtin_amdgcn_mfma_f32_16x16x32_bf16(Bt[n][k], At[m][k], acc[ai][bj][m][n], 0, 0, 0); __builtin_amdgcn_s_setprio(0); } while (0)
; #define PG8_WAIT_V(n) asm volatile("s_waitcnt vmcnt(" #n ")" ::: "memory")
; #define PG8_WAIT_L(n) asm volatile("s_waitcnt lgkmcnt(" #n ")" ::: "memory")
; template <class Epi, class Sched, bool ALIGN_EPI = false, bool SP2 = false>
; __device__ __forceinline__ void gemm_phase(PG8_LAS unsigned char* lds, const Gemm g, const Sched& S, const Epi& E) {
;     ...
;             const bool last = (t == nt - 2);
;             const char* a1 = cA + (size_t)(t + 1) * kstep;
;             const char* a2 = last ? nA : cA + (size_t)(t + 2) * kstep; const char* b2 = last ? nB : cB + (size_t)(t + 2) * kstep;
;             const char* a3 = a2 + kstep; const char* b3 = b2 + kstep;
;             if (last && has_next) S.a_ready(nxt);
;             if constexpr (SP2) {
;             PG8_LDB(B0, 0, 0); PG8_LDB(B1, 0, 1); PG8_SCHED; PG8_LDA(At, 0, 0); PG8_STAGE(PG8_SA(1, 1), a1 + hstep, voffA);
;             PG8_WAIT_V(8); PG8_WAIT_L(0); PG8_BAR; PG8_MMA(0, 0, At, B0); PG8_MMA(0, 1, At, B1); PG8_BAR; PG8_SCHED;
;             PG8_LDA(At, 0, 1); PG8_STAGE(PG8_SB(0, 0), b2, voffB); PG8_STAGE(PG8_SB(0, 1), b2 + hstep, voffB); PG8_STAGE(PG8_SA(0, 0), a2, voffA);
;             PG8_WAIT_V(8); PG8_WAIT_L(0); PG8_BAR; PG8_MMA(1, 0, At, B0); PG8_MMA(1, 1, At, B1); PG8_BAR; PG8_SCHED;
.LBB0_1039:
	ds_read_b128 v[130:133], v241 offset:0
	ds_read_b128 v[134:137], v241 offset:1024
	ds_read_b128 v[138:141], v241 offset:2048
	ds_read_b128 v[142:145], v241 offset:3072
	ds_read_b128 v[146:149], v241 offset:16384
	ds_read_b128 v[150:153], v241 offset:17408
	ds_read_b128 v[172:175], v241 offset:18432
	ds_read_b128 v[176:179], v241 offset:19456
	s_add_u32 s24, s26, 0xfff00080
	s_addc_u32 s25, s27, -1
	s_cmp_eq_u32 s68, 60
	s_cselect_b32 s29, s15, s25
	s_cselect_b32 s28, s21, s24
	s_cselect_b32 s25, s13, s67
	s_cselect_b32 s24, s65, s66
	s_add_i32 m0, s23, 0xc000
	ds_read_b128 v[180:183], v185
	ds_read_b128 v[188:191], v185 offset:1024
	ds_read_b128 v[192:195], v185 offset:2048
	ds_read_b128 v[196:199], v185 offset:3072
	ds_read_b128 v[200:203], v185 offset:4096
	ds_read_b128 v[204:207], v185 offset:5120
	ds_read_b128 v[208:211], v185 offset:6144
	ds_read_b128 v[212:215], v185 offset:7168
	global_load_lds_dwordx4 v162, s[26:27]
	s_add_i32 m0, s23, 0xe000
	s_nop 0
	global_load_lds_dwordx4 v166, s[26:27]
	s_waitcnt vmcnt(8)
	s_waitcnt lgkmcnt(0)
	s_barrier
	s_waitcnt lgkmcnt(0)
	v_mfma_f32_16x16x32_bf16 v[114:117], v[130:133], v[180:183], v[114:117]
	v_mfma_f32_16x16x32_bf16 v[118:121], v[138:141], v[180:183], v[118:121]
	v_mfma_f32_16x16x32_bf16 v[106:109], v[130:133], v[192:195], v[106:109]
	v_mfma_f32_16x16x32_bf16 v[98:101], v[138:141], v[192:195], v[98:101]
	v_mfma_f32_16x16x32_bf16 v[90:93], v[130:133], v[200:203], v[90:93]
	v_mfma_f32_16x16x32_bf16 v[82:85], v[138:141], v[200:203], v[82:85]
	v_mfma_f32_16x16x32_bf16 v[74:77], v[130:133], v[208:211], v[74:77]
	v_mfma_f32_16x16x32_bf16 v[66:69], v[138:141], v[208:211], v[66:69]
	v_mfma_f32_16x16x32_bf16 v[114:117], v[134:137], v[188:191], v[114:117]
	v_mfma_f32_16x16x32_bf16 v[118:121], v[142:145], v[188:191], v[118:121]
	v_mfma_f32_16x16x32_bf16 v[106:109], v[134:137], v[196:199], v[106:109]
	v_mfma_f32_16x16x32_bf16 v[98:101], v[142:145], v[196:199], v[98:101]
	v_mfma_f32_16x16x32_bf16 v[90:93], v[134:137], v[204:207], v[90:93]
	v_mfma_f32_16x16x32_bf16 v[82:85], v[142:145], v[204:207], v[82:85]
	v_mfma_f32_16x16x32_bf16 v[74:77], v[134:137], v[212:215], v[74:77]
	v_mfma_f32_16x16x32_bf16 v[66:69], v[142:145], v[212:215], v[66:69]
	v_mfma_f32_16x16x32_bf16 v[122:125], v[146:149], v[180:183], v[122:125]
	v_mfma_f32_16x16x32_bf16 v[126:129], v[172:175], v[180:183], v[126:129]
	v_mfma_f32_16x16x32_bf16 v[110:113], v[146:149], v[192:195], v[110:113]
	v_mfma_f32_16x16x32_bf16 v[102:105], v[172:175], v[192:195], v[102:105]
	v_mfma_f32_16x16x32_bf16 v[94:97], v[146:149], v[200:203], v[94:97]
	v_mfma_f32_16x16x32_bf16 v[86:89], v[172:175], v[200:203], v[86:89]
	v_mfma_f32_16x16x32_bf16 v[78:81], v[146:149], v[208:211], v[78:81]
	v_mfma_f32_16x16x32_bf16 v[70:73], v[172:175], v[208:211], v[70:73]
	v_mfma_f32_16x16x32_bf16 v[122:125], v[150:153], v[188:191], v[122:125]
	v_mfma_f32_16x16x32_bf16 v[126:129], v[176:179], v[188:191], v[126:129]
	v_mfma_f32_16x16x32_bf16 v[110:113], v[150:153], v[196:199], v[110:113]
	v_mfma_f32_16x16x32_bf16 v[102:105], v[176:179], v[196:199], v[102:105]
	v_mfma_f32_16x16x32_bf16 v[94:97], v[150:153], v[204:207], v[94:97]
	v_mfma_f32_16x16x32_bf16 v[86:89], v[176:179], v[204:207], v[86:89]
	v_mfma_f32_16x16x32_bf16 v[78:81], v[150:153], v[212:215], v[78:81]
	v_mfma_f32_16x16x32_bf16 v[70:73], v[176:179], v[212:215], v[70:73]
	s_barrier
	s_add_i32 s33, s62, s36
	s_mov_b32 m0, s33
	ds_read_b128 v[180:183], v185 offset:16384
	ds_read_b128 v[188:191], v185 offset:17408
	ds_read_b128 v[192:195], v185 offset:18432
	ds_read_b128 v[196:199], v185 offset:19456
	ds_read_b128 v[200:203], v185 offset:20480
	ds_read_b128 v[204:207], v185 offset:21504
	ds_read_b128 v[208:211], v185 offset:22528
	ds_read_b128 v[212:215], v185 offset:23552
	global_load_lds_dwordx4 v156, s[24:25]
	s_add_i32 m0, s33, 0x2000
	s_add_u32 s72, s24, 0x100000
	s_addc_u32 s73, s25, 0
	s_add_i32 s33, s63, s36
	global_load_lds_dwordx4 v160, s[24:25]
	s_mov_b32 m0, s33
	s_add_u32 s100, s28, 0x80
	s_addc_u32 s101, s29, 0
	global_load_lds_dwordx4 v156, s[72:73]
	s_add_i32 m0, s33, 0x2000
	s_nop 0
	global_load_lds_dwordx4 v160, s[72:73]
	s_mov_b32 m0, s23
	s_nop 0
	global_load_lds_dwordx4 v154, s[28:29]
	s_mov_b32 m0, s37
	s_nop 0
	global_load_lds_dwordx4 v158, s[28:29]
	s_waitcnt vmcnt(8)
	s_waitcnt lgkmcnt(0)
	s_barrier
	s_waitcnt lgkmcnt(0)
	v_mfma_f32_16x16x32_bf16 v[58:61], v[130:133], v[180:183], v[58:61]
	v_mfma_f32_16x16x32_bf16 v[54:57], v[138:141], v[180:183], v[54:57]
	v_mfma_f32_16x16x32_bf16 v[42:45], v[130:133], v[192:195], v[42:45]
	v_mfma_f32_16x16x32_bf16 v[34:37], v[138:141], v[192:195], v[34:37]
	v_mfma_f32_16x16x32_bf16 v[26:29], v[130:133], v[200:203], v[26:29]
	v_mfma_f32_16x16x32_bf16 v[18:21], v[138:141], v[200:203], v[18:21]
	v_mfma_f32_16x16x32_bf16 v[6:9], v[130:133], v[208:211], v[6:9]
	v_mfma_f32_16x16x32_bf16 v[2:5], v[138:141], v[208:211], v[2:5]
	v_mfma_f32_16x16x32_bf16 v[58:61], v[134:137], v[188:191], v[58:61]
	v_mfma_f32_16x16x32_bf16 v[54:57], v[142:145], v[188:191], v[54:57]
	v_mfma_f32_16x16x32_bf16 v[42:45], v[134:137], v[196:199], v[42:45]
	v_mfma_f32_16x16x32_bf16 v[34:37], v[142:145], v[196:199], v[34:37]
	v_mfma_f32_16x16x32_bf16 v[26:29], v[134:137], v[204:207], v[26:29]
	v_mfma_f32_16x16x32_bf16 v[18:21], v[142:145], v[204:207], v[18:21]
	v_mfma_f32_16x16x32_bf16 v[6:9], v[134:137], v[212:215], v[6:9]
	v_mfma_f32_16x16x32_bf16 v[2:5], v[142:145], v[212:215], v[2:5]
	v_mfma_f32_16x16x32_bf16 v[62:65], v[146:149], v[180:183], v[62:65]
	v_mfma_f32_16x16x32_bf16 v[50:53], v[172:175], v[180:183], v[50:53]
	v_mfma_f32_16x16x32_bf16 v[46:49], v[146:149], v[192:195], v[46:49]
	v_mfma_f32_16x16x32_bf16 v[38:41], v[172:175], v[192:195], v[38:41]
	v_mfma_f32_16x16x32_bf16 v[30:33], v[146:149], v[200:203], v[30:33]
	v_mfma_f32_16x16x32_bf16 v[22:25], v[172:175], v[200:203], v[22:25]
	v_mfma_f32_16x16x32_bf16 v[10:13], v[146:149], v[208:211], v[10:13]
	v_mfma_f32_16x16x32_bf16 v[14:17], v[172:175], v[208:211], v[14:17]
	v_mfma_f32_16x16x32_bf16 v[62:65], v[150:153], v[188:191], v[62:65]
	v_mfma_f32_16x16x32_bf16 v[50:53], v[176:179], v[188:191], v[50:53]
	v_mfma_f32_16x16x32_bf16 v[46:49], v[150:153], v[196:199], v[46:49]
	v_mfma_f32_16x16x32_bf16 v[38:41], v[176:179], v[196:199], v[38:41]
	v_mfma_f32_16x16x32_bf16 v[30:33], v[150:153], v[204:207], v[30:33]
	v_mfma_f32_16x16x32_bf16 v[22:25], v[176:179], v[204:207], v[22:25]
	v_mfma_f32_16x16x32_bf16 v[10:13], v[150:153], v[212:215], v[10:13]
	v_mfma_f32_16x16x32_bf16 v[14:17], v[176:179], v[212:215], v[14:17]
	s_barrier
; #define PG8_STAGE(bufoff, gbase, voff) do { _Pragma("unroll") for (int _i = 0; _i < 2; ++_i) \
;         __builtin_amdgcn_global_load_lds((const unsigned*)((const char*)(gbase) + (voff)[_i]), (PG8_LAS unsigned*)(lds + (bufoff) + ldsw + _i * 8192), 16, 0, 0); } while (0)
; #define PG8_LDA(dst, b, h) do { _Pragma("unroll") for (int m = 0; m < 4; ++m) _Pragma("unroll") for (int k = 0; k < 2; ++k) dst[m][k] = *(const PG8_LAS bf16x8*)(lds + PG8_SA(b, h) + aoff + m * 2048 + k * 1024); } while (0)
; #define PG8_LDB(dst, b, h) do { _Pragma("unroll") for (int n = 0; n < 2; ++n) _Pragma("unroll") for (int k = 0; k < 2; ++k) dst[n][k] = *(const PG8_LAS bf16x8*)(lds + PG8_SB(b, h) + boff + n * 2048 + k * 1024); } while (0)
; #define PG8_MMA(ai, bj, At, Bt) do { __builtin_amdgcn_s_setprio(1); _Pragma("unroll") for (int m = 0; m < 4; ++m) _Pragma("unroll") for (int n = 0; n < 2; ++n) _Pragma("unroll") for (int k = 0; k < 2; ++k) \
;         acc[ai][bj][m][n] = __builtin_amdgcn_mfma_f32_16x16x32_bf16(Bt[n][k], At[m][k], acc[ai][bj][m][n], 0, 0, 0); __builtin_amdgcn_s_setprio(0); } while (0)
; #define PG8_WAIT_V(n) asm volatile("s_waitcnt vmcnt(" #n ")" ::: "memory")
; #define PG8_WAIT_L(n) asm volatile("s_waitcnt lgkmcnt(" #n ")" ::: "memory")
; #define PG8_BAR __builtin_amdgcn_s_barrier()
; #define PG8_SCHED __builtin_amdgcn_sched_barrier(0)
; template <class Epi, class Sched, bool ALIGN_EPI = false, bool SP2 = false>
; __device__ __forceinline__ void gemm_phase(PG8_LAS unsigned char* lds, const Gemm g, const Sched& S, const Epi& E) {
;     ...
;             PG8_LDB(B0, 1, 0); PG8_LDB(B1, 1, 1); PG8_SCHED; PG8_LDA(At, 1, 0); PG8_STAGE(PG8_SA(0, 1), a2 + hstep, voffA);
;             PG8_WAIT_V(8); PG8_WAIT_L(0); PG8_BAR; PG8_MMA(0, 0, At, B0); PG8_MMA(0, 1, At, B1); PG8_BAR; PG8_SCHED;
;             PG8_LDA(At, 1, 1); PG8_STAGE(PG8_SB(1, 0), b3, voffB); PG8_STAGE(PG8_SB(1, 1), b3 + hstep, voffB); PG8_STAGE(PG8_SA(1, 0), a3, voffA);
;             PG8_WAIT_V(8); PG8_WAIT_L(0); PG8_BAR; PG8_MMA(1, 0, At, B0); PG8_MMA(1, 1, At, B1); PG8_BAR; PG8_SCHED;
	s_add_i32 s33, 0, 0x18000
	s_add_i32 s42, 0, 0x1c000
	ds_read_b128 v[130:133], v241 offset:32768
	ds_read_b128 v[134:137], v241 offset:33792
	ds_read_b128 v[138:141], v241 offset:34816
	ds_read_b128 v[142:145], v241 offset:35840
	ds_read_b128 v[146:149], v241 offset:49152
	ds_read_b128 v[150:153], v241 offset:50176
	ds_read_b128 v[172:175], v241 offset:51200
	ds_read_b128 v[176:179], v241 offset:52224
	s_add_u32 s28, s28, 0x100000
	s_addc_u32 s29, s29, 0
	s_mov_b32 m0, s40
	ds_read_b128 v[180:183], v185 offset:32768
	ds_read_b128 v[188:191], v185 offset:33792
	ds_read_b128 v[192:195], v185 offset:34816
	ds_read_b128 v[196:199], v185 offset:35840
	ds_read_b128 v[200:203], v185 offset:36864
	ds_read_b128 v[204:207], v185 offset:37888
	ds_read_b128 v[208:211], v185 offset:38912
	ds_read_b128 v[212:215], v185 offset:39936
	global_load_lds_dwordx4 v154, s[28:29]
	s_mov_b32 m0, s41
	s_nop 0
	global_load_lds_dwordx4 v158, s[28:29]
	s_waitcnt vmcnt(8)
	s_waitcnt lgkmcnt(0)
	s_barrier
	s_waitcnt lgkmcnt(0)
	v_mfma_f32_16x16x32_bf16 v[114:117], v[130:133], v[180:183], v[114:117]
	v_mfma_f32_16x16x32_bf16 v[118:121], v[138:141], v[180:183], v[118:121]
	v_mfma_f32_16x16x32_bf16 v[106:109], v[130:133], v[192:195], v[106:109]
	v_mfma_f32_16x16x32_bf16 v[98:101], v[138:141], v[192:195], v[98:101]
	v_mfma_f32_16x16x32_bf16 v[90:93], v[130:133], v[200:203], v[90:93]
	v_mfma_f32_16x16x32_bf16 v[82:85], v[138:141], v[200:203], v[82:85]
	v_mfma_f32_16x16x32_bf16 v[74:77], v[130:133], v[208:211], v[74:77]
	v_mfma_f32_16x16x32_bf16 v[66:69], v[138:141], v[208:211], v[66:69]
	v_mfma_f32_16x16x32_bf16 v[114:117], v[134:137], v[188:191], v[114:117]
	v_mfma_f32_16x16x32_bf16 v[118:121], v[142:145], v[188:191], v[118:121]
	v_mfma_f32_16x16x32_bf16 v[106:109], v[134:137], v[196:199], v[106:109]
	v_mfma_f32_16x16x32_bf16 v[98:101], v[142:145], v[196:199], v[98:101]
	v_mfma_f32_16x16x32_bf16 v[90:93], v[134:137], v[204:207], v[90:93]
	v_mfma_f32_16x16x32_bf16 v[82:85], v[142:145], v[204:207], v[82:85]
	v_mfma_f32_16x16x32_bf16 v[74:77], v[134:137], v[212:215], v[74:77]
	v_mfma_f32_16x16x32_bf16 v[66:69], v[142:145], v[212:215], v[66:69]
	v_mfma_f32_16x16x32_bf16 v[122:125], v[146:149], v[180:183], v[122:125]
	v_mfma_f32_16x16x32_bf16 v[126:129], v[172:175], v[180:183], v[126:129]
	v_mfma_f32_16x16x32_bf16 v[110:113], v[146:149], v[192:195], v[110:113]
	v_mfma_f32_16x16x32_bf16 v[102:105], v[172:175], v[192:195], v[102:105]
	v_mfma_f32_16x16x32_bf16 v[94:97], v[146:149], v[200:203], v[94:97]
	v_mfma_f32_16x16x32_bf16 v[86:89], v[172:175], v[200:203], v[86:89]
	v_mfma_f32_16x16x32_bf16 v[78:81], v[146:149], v[208:211], v[78:81]
	v_mfma_f32_16x16x32_bf16 v[70:73], v[172:175], v[208:211], v[70:73]
	v_mfma_f32_16x16x32_bf16 v[122:125], v[150:153], v[188:191], v[122:125]
	v_mfma_f32_16x16x32_bf16 v[126:129], v[176:179], v[188:191], v[126:129]
	v_mfma_f32_16x16x32_bf16 v[110:113], v[150:153], v[196:199], v[110:113]
	v_mfma_f32_16x16x32_bf16 v[102:105], v[176:179], v[196:199], v[102:105]
	v_mfma_f32_16x16x32_bf16 v[94:97], v[150:153], v[204:207], v[94:97]
	v_mfma_f32_16x16x32_bf16 v[86:89], v[176:179], v[204:207], v[86:89]
	v_mfma_f32_16x16x32_bf16 v[78:81], v[150:153], v[212:215], v[78:81]
	v_mfma_f32_16x16x32_bf16 v[70:73], v[176:179], v[212:215], v[70:73]
	s_barrier
	s_add_i32 s28, s33, s36
	s_add_i32 m0, s28, 0xffffff80
	ds_read_b128 v[180:183], v185 offset:49152
	ds_read_b128 v[188:191], v185 offset:50176
	ds_read_b128 v[192:195], v185 offset:51200
	ds_read_b128 v[196:199], v185 offset:52224
	ds_read_b128 v[200:203], v185 offset:53248
	ds_read_b128 v[204:207], v185 offset:54272
	ds_read_b128 v[208:211], v185 offset:55296
	ds_read_b128 v[212:215], v185 offset:56320
	global_load_lds_dwordx4 v156, s[24:25] offset:128
	s_add_i32 m0, s28, 0x1f80
	s_add_i32 s28, s42, s36
	global_load_lds_dwordx4 v160, s[24:25] offset:128
	s_add_u32 s24, s24, 0x100080
	s_addc_u32 s25, s25, 0
	s_mov_b32 m0, s28
	s_nop 0
	global_load_lds_dwordx4 v156, s[24:25]
	s_add_i32 m0, s28, 0x2000
	s_nop 0
	global_load_lds_dwordx4 v160, s[24:25]
	s_mov_b32 m0, s46
	s_nop 0
	global_load_lds_dwordx4 v154, s[100:101]
	s_mov_b32 m0, s47
	s_nop 0
	global_load_lds_dwordx4 v158, s[100:101]
	s_waitcnt vmcnt(8)
	s_waitcnt lgkmcnt(0)
	s_barrier
	s_waitcnt lgkmcnt(0)
	v_mfma_f32_16x16x32_bf16 v[58:61], v[130:133], v[180:183], v[58:61]
	v_mfma_f32_16x16x32_bf16 v[54:57], v[138:141], v[180:183], v[54:57]
	v_mfma_f32_16x16x32_bf16 v[42:45], v[130:133], v[192:195], v[42:45]
	v_mfma_f32_16x16x32_bf16 v[34:37], v[138:141], v[192:195], v[34:37]
	v_mfma_f32_16x16x32_bf16 v[26:29], v[130:133], v[200:203], v[26:29]
	v_mfma_f32_16x16x32_bf16 v[18:21], v[138:141], v[200:203], v[18:21]
	v_mfma_f32_16x16x32_bf16 v[6:9], v[130:133], v[208:211], v[6:9]
	v_mfma_f32_16x16x32_bf16 v[2:5], v[138:141], v[208:211], v[2:5]
	v_mfma_f32_16x16x32_bf16 v[58:61], v[134:137], v[188:191], v[58:61]
	v_mfma_f32_16x16x32_bf16 v[54:57], v[142:145], v[188:191], v[54:57]
	v_mfma_f32_16x16x32_bf16 v[42:45], v[134:137], v[196:199], v[42:45]
	v_mfma_f32_16x16x32_bf16 v[34:37], v[142:145], v[196:199], v[34:37]
	v_mfma_f32_16x16x32_bf16 v[26:29], v[134:137], v[204:207], v[26:29]
	v_mfma_f32_16x16x32_bf16 v[18:21], v[142:145], v[204:207], v[18:21]
	v_mfma_f32_16x16x32_bf16 v[6:9], v[134:137], v[212:215], v[6:9]
	v_mfma_f32_16x16x32_bf16 v[2:5], v[142:145], v[212:215], v[2:5]
	v_mfma_f32_16x16x32_bf16 v[62:65], v[146:149], v[180:183], v[62:65]
	v_mfma_f32_16x16x32_bf16 v[50:53], v[172:175], v[180:183], v[50:53]
	v_mfma_f32_16x16x32_bf16 v[46:49], v[146:149], v[192:195], v[46:49]
	v_mfma_f32_16x16x32_bf16 v[38:41], v[172:175], v[192:195], v[38:41]
	v_mfma_f32_16x16x32_bf16 v[30:33], v[146:149], v[200:203], v[30:33]
	v_mfma_f32_16x16x32_bf16 v[22:25], v[172:175], v[200:203], v[22:25]
	v_mfma_f32_16x16x32_bf16 v[10:13], v[146:149], v[208:211], v[10:13]
	v_mfma_f32_16x16x32_bf16 v[14:17], v[172:175], v[208:211], v[14:17]
	v_mfma_f32_16x16x32_bf16 v[62:65], v[150:153], v[188:191], v[62:65]
	v_mfma_f32_16x16x32_bf16 v[50:53], v[176:179], v[188:191], v[50:53]
	v_mfma_f32_16x16x32_bf16 v[46:49], v[150:153], v[196:199], v[46:49]
	v_mfma_f32_16x16x32_bf16 v[38:41], v[176:179], v[196:199], v[38:41]
	v_mfma_f32_16x16x32_bf16 v[30:33], v[150:153], v[204:207], v[30:33]
	v_mfma_f32_16x16x32_bf16 v[22:25], v[176:179], v[204:207], v[22:25]
	v_mfma_f32_16x16x32_bf16 v[10:13], v[150:153], v[212:215], v[10:13]
	v_mfma_f32_16x16x32_bf16 v[14:17], v[176:179], v[212:215], v[14:17]
	s_barrier
	s_add_i32 s68, s68, 2
	s_add_u32 s26, s26, 0x100
	s_addc_u32 s27, s27, 0
	s_add_u32 s66, s66, 0x100
	s_addc_u32 s67, s67, 0
	s_cmp_gt_u32 s68, 61
	s_cbranch_scc0 .LBB0_1039
	s_and_b64 vcc, exec, s[10:11]
	s_cbranch_vccz .LBB0_1042
	s_barrier

; #define PG8_STAGE(bufoff, gbase, voff) do { _Pragma("unroll") for (int _i = 0; _i < 2; ++_i) \
;         __builtin_amdgcn_global_load_lds((const unsigned*)((const char*)(gbase) + (voff)[_i]), (PG8_LAS unsigned*)(lds + (bufoff) + ldsw + _i * 8192), 16, 0, 0); } while (0)
; #define PG8_LDA(dst, b, h) do { _Pragma("unroll") for (int m = 0; m < 4; ++m) _Pragma("unroll") for (int k = 0; k < 2; ++k) dst[m][k] = *(const PG8_LAS bf16x8*)(lds + PG8_SA(b, h) + aoff + m * 2048 + k * 1024); } while (0)
; #define PG8_LDB(dst, b, h) do { _Pragma("unroll") for (int n = 0; n < 2; ++n) _Pragma("unroll") for (int k = 0; k < 2; ++k) dst[n][k] = *(const PG8_LAS bf16x8*)(lds + PG8_SB(b, h) + boff + n * 2048 + k * 1024); } while (0)
; #define PG8_MMA(ai, bj, At, Bt) do { __builtin_amdgcn_s_setprio(1); _Pragma("unroll") for (int m = 0; m < 4; ++m) _Pragma("unroll") for (int n = 0; n < 2; ++n) _Pragma("unroll") for (int k = 0; k < 2; ++k) \
;         acc[ai][bj][m][n] = __builtin_amdgcn_mfma_f32_16x16x32_bf16(Bt[n][k], At[m][k], acc[ai][bj][m][n], 0, 0, 0); __builtin_amdgcn_s_setprio(0); } while (0)
; #define PG8_WAIT_V(n) asm volatile("s_waitcnt vmcnt(" #n ")" ::: "memory")
; #define PG8_WAIT_L(n) asm volatile("s_waitcnt lgkmcnt(" #n ")" ::: "memory")
; template <class Epi, class Sched, bool ALIGN_EPI = false, bool SP2 = false>
; __device__ __forceinline__ void gemm_phase(PG8_LAS unsigned char* lds, const Gemm g, const Sched& S, const Epi& E) {
;     ...
;             const bool last = (t == nt - 2);
;             const char* a1 = cA + (size_t)(t + 1) * kstep;
;             const char* a2 = last ? nA : cA + (size_t)(t + 2) * kstep; const char* b2 = last ? nB : cB + (size_t)(t + 2) * kstep;
;             const char* a3 = a2 + kstep; const char* b3 = b2 + kstep;
;             if (last && has_next) S.a_ready(nxt);
;             if constexpr (SP2) {
;             PG8_LDB(B0, 0, 0); PG8_LDB(B1, 0, 1); PG8_SCHED; PG8_LDA(At, 0, 0); PG8_STAGE(PG8_SA(1, 1), a1 + hstep, voffA);
;             PG8_WAIT_V(8); PG8_WAIT_L(0); PG8_BAR; PG8_MMA(0, 0, At, B0); PG8_MMA(0, 1, At, B1); PG8_BAR; PG8_SCHED;
;             PG8_LDA(At, 0, 1); PG8_STAGE(PG8_SB(0, 0), b2, voffB); PG8_STAGE(PG8_SB(0, 1), b2 + hstep, voffB); PG8_STAGE(PG8_SA(0, 0), a2, voffA);
;             PG8_WAIT_V(8); PG8_WAIT_L(0); PG8_BAR; PG8_MMA(1, 0, At, B0); PG8_MMA(1, 1, At, B1); PG8_BAR; PG8_SCHED;
.LBB0_1126:
	ds_read_b128 v[160:163], v241 offset:0
	ds_read_b128 v[166:169], v241 offset:1024
	ds_read_b128 v[170:173], v241 offset:2048
	ds_read_b128 v[174:177], v241 offset:3072
	ds_read_b128 v[178:181], v241 offset:16384
	ds_read_b128 v[182:185], v241 offset:17408
	ds_read_b128 v[186:189], v241 offset:18432
	ds_read_b128 v[190:193], v241 offset:19456
	s_add_u32 s22, s24, 0xfff00080
	s_addc_u32 s23, s25, -1
	s_cmp_eq_u32 s68, 60
	s_cselect_b32 s27, s15, s23
	s_cselect_b32 s26, s64, s22
	s_cselect_b32 s23, s13, s67
	s_cselect_b32 s22, s65, s66
	s_add_i32 m0, s21, 0xc000
	ds_read_b128 v[194:197], v155
	ds_read_b128 v[198:201], v155 offset:1024
	ds_read_b128 v[202:205], v155 offset:2048
	ds_read_b128 v[206:209], v155 offset:3072
	ds_read_b128 v[210:213], v155 offset:4096
	ds_read_b128 v[214:217], v155 offset:5120
	ds_read_b128 v[218:221], v155 offset:6144
	ds_read_b128 v[222:225], v155 offset:7168
	global_load_lds_dwordx4 v138, s[24:25]
	s_add_i32 m0, s21, 0xe000
	s_nop 0
	global_load_lds_dwordx4 v140, s[24:25]
	s_waitcnt vmcnt(8)
	s_waitcnt lgkmcnt(0)
	s_barrier
	s_waitcnt lgkmcnt(0)
	v_mfma_f32_16x16x32_bf16 v[122:125], v[160:163], v[194:197], v[122:125]
	v_mfma_f32_16x16x32_bf16 v[114:117], v[170:173], v[194:197], v[114:117]
	v_mfma_f32_16x16x32_bf16 v[106:109], v[160:163], v[202:205], v[106:109]
	v_mfma_f32_16x16x32_bf16 v[98:101], v[170:173], v[202:205], v[98:101]
	v_mfma_f32_16x16x32_bf16 v[90:93], v[160:163], v[210:213], v[90:93]
	v_mfma_f32_16x16x32_bf16 v[82:85], v[170:173], v[210:213], v[82:85]
	v_mfma_f32_16x16x32_bf16 v[74:77], v[160:163], v[218:221], v[74:77]
	v_mfma_f32_16x16x32_bf16 v[62:65], v[170:173], v[218:221], v[62:65]
	v_mfma_f32_16x16x32_bf16 v[122:125], v[166:169], v[198:201], v[122:125]
	v_mfma_f32_16x16x32_bf16 v[114:117], v[174:177], v[198:201], v[114:117]
	v_mfma_f32_16x16x32_bf16 v[106:109], v[166:169], v[206:209], v[106:109]
	v_mfma_f32_16x16x32_bf16 v[98:101], v[174:177], v[206:209], v[98:101]
	v_mfma_f32_16x16x32_bf16 v[90:93], v[166:169], v[214:217], v[90:93]
	v_mfma_f32_16x16x32_bf16 v[82:85], v[174:177], v[214:217], v[82:85]
	v_mfma_f32_16x16x32_bf16 v[74:77], v[166:169], v[222:225], v[74:77]
	v_mfma_f32_16x16x32_bf16 v[62:65], v[174:177], v[222:225], v[62:65]
	v_mfma_f32_16x16x32_bf16 v[126:129], v[178:181], v[194:197], v[126:129]
	v_mfma_f32_16x16x32_bf16 v[118:121], v[186:189], v[194:197], v[118:121]
	v_mfma_f32_16x16x32_bf16 v[110:113], v[178:181], v[202:205], v[110:113]
	v_mfma_f32_16x16x32_bf16 v[102:105], v[186:189], v[202:205], v[102:105]
	v_mfma_f32_16x16x32_bf16 v[94:97], v[178:181], v[210:213], v[94:97]
	v_mfma_f32_16x16x32_bf16 v[86:89], v[186:189], v[210:213], v[86:89]
	v_mfma_f32_16x16x32_bf16 v[78:81], v[178:181], v[218:221], v[78:81]
	v_mfma_f32_16x16x32_bf16 v[70:73], v[186:189], v[218:221], v[70:73]
	v_mfma_f32_16x16x32_bf16 v[126:129], v[182:185], v[198:201], v[126:129]
	v_mfma_f32_16x16x32_bf16 v[118:121], v[190:193], v[198:201], v[118:121]
	v_mfma_f32_16x16x32_bf16 v[110:113], v[182:185], v[206:209], v[110:113]
	v_mfma_f32_16x16x32_bf16 v[102:105], v[190:193], v[206:209], v[102:105]
	v_mfma_f32_16x16x32_bf16 v[94:97], v[182:185], v[214:217], v[94:97]
	v_mfma_f32_16x16x32_bf16 v[86:89], v[190:193], v[214:217], v[86:89]
	v_mfma_f32_16x16x32_bf16 v[78:81], v[182:185], v[222:225], v[78:81]
	v_mfma_f32_16x16x32_bf16 v[70:73], v[190:193], v[222:225], v[70:73]
	s_barrier
	s_add_i32 s33, s52, s29
	s_mov_b32 m0, s33
	ds_read_b128 v[194:197], v155 offset:16384
	ds_read_b128 v[198:201], v155 offset:17408
	ds_read_b128 v[202:205], v155 offset:18432
	ds_read_b128 v[206:209], v155 offset:19456
	ds_read_b128 v[210:213], v155 offset:20480
	ds_read_b128 v[214:217], v155 offset:21504
	ds_read_b128 v[218:221], v155 offset:22528
	ds_read_b128 v[222:225], v155 offset:23552
	global_load_lds_dwordx4 v132, s[22:23]
	s_add_i32 m0, s33, 0x2000
	s_add_u32 s72, s22, 0x100000
	s_addc_u32 s73, s23, 0
	s_add_i32 s33, s53, s29
	global_load_lds_dwordx4 v136, s[22:23]
	s_mov_b32 m0, s33
	s_add_u32 s100, s26, 0x80
	s_addc_u32 s101, s27, 0
	global_load_lds_dwordx4 v132, s[72:73]
	s_add_i32 m0, s33, 0x2000
	s_nop 0
	global_load_lds_dwordx4 v136, s[72:73]
	s_mov_b32 m0, s21
	s_nop 0
	global_load_lds_dwordx4 v130, s[26:27]
	s_mov_b32 m0, s36
	s_nop 0
	global_load_lds_dwordx4 v134, s[26:27]
	s_waitcnt vmcnt(8)
	s_waitcnt lgkmcnt(0)
	s_barrier
	s_waitcnt lgkmcnt(0)
	v_mfma_f32_16x16x32_bf16 v[58:61], v[160:163], v[194:197], v[58:61]
	v_mfma_f32_16x16x32_bf16 v[50:53], v[170:173], v[194:197], v[50:53]
	v_mfma_f32_16x16x32_bf16 v[42:45], v[160:163], v[202:205], v[42:45]
	v_mfma_f32_16x16x32_bf16 v[34:37], v[170:173], v[202:205], v[34:37]
	v_mfma_f32_16x16x32_bf16 v[26:29], v[160:163], v[210:213], v[26:29]
	v_mfma_f32_16x16x32_bf16 v[18:21], v[170:173], v[210:213], v[18:21]
	v_mfma_f32_16x16x32_bf16 v[10:13], v[160:163], v[218:221], v[10:13]
	v_mfma_f32_16x16x32_bf16 v[2:5], v[170:173], v[218:221], v[2:5]
	v_mfma_f32_16x16x32_bf16 v[58:61], v[166:169], v[198:201], v[58:61]
	v_mfma_f32_16x16x32_bf16 v[50:53], v[174:177], v[198:201], v[50:53]
	v_mfma_f32_16x16x32_bf16 v[42:45], v[166:169], v[206:209], v[42:45]
	v_mfma_f32_16x16x32_bf16 v[34:37], v[174:177], v[206:209], v[34:37]
	v_mfma_f32_16x16x32_bf16 v[26:29], v[166:169], v[214:217], v[26:29]
	v_mfma_f32_16x16x32_bf16 v[18:21], v[174:177], v[214:217], v[18:21]
	v_mfma_f32_16x16x32_bf16 v[10:13], v[166:169], v[222:225], v[10:13]
	v_mfma_f32_16x16x32_bf16 v[2:5], v[174:177], v[222:225], v[2:5]
	v_mfma_f32_16x16x32_bf16 v[66:69], v[178:181], v[194:197], v[66:69]
	v_mfma_f32_16x16x32_bf16 v[54:57], v[186:189], v[194:197], v[54:57]
	v_mfma_f32_16x16x32_bf16 v[46:49], v[178:181], v[202:205], v[46:49]
	v_mfma_f32_16x16x32_bf16 v[38:41], v[186:189], v[202:205], v[38:41]
	v_mfma_f32_16x16x32_bf16 v[30:33], v[178:181], v[210:213], v[30:33]
	v_mfma_f32_16x16x32_bf16 v[22:25], v[186:189], v[210:213], v[22:25]
	v_mfma_f32_16x16x32_bf16 v[14:17], v[178:181], v[218:221], v[14:17]
	v_mfma_f32_16x16x32_bf16 v[6:9], v[186:189], v[218:221], v[6:9]
	v_mfma_f32_16x16x32_bf16 v[66:69], v[182:185], v[198:201], v[66:69]
	v_mfma_f32_16x16x32_bf16 v[54:57], v[190:193], v[198:201], v[54:57]
	v_mfma_f32_16x16x32_bf16 v[46:49], v[182:185], v[206:209], v[46:49]
	v_mfma_f32_16x16x32_bf16 v[38:41], v[190:193], v[206:209], v[38:41]
	v_mfma_f32_16x16x32_bf16 v[30:33], v[182:185], v[214:217], v[30:33]
	v_mfma_f32_16x16x32_bf16 v[22:25], v[190:193], v[214:217], v[22:25]
	v_mfma_f32_16x16x32_bf16 v[14:17], v[182:185], v[222:225], v[14:17]
	v_mfma_f32_16x16x32_bf16 v[6:9], v[190:193], v[222:225], v[6:9]
	s_barrier
; #define PG8_STAGE(bufoff, gbase, voff) do { _Pragma("unroll") for (int _i = 0; _i < 2; ++_i) \
;         __builtin_amdgcn_global_load_lds((const unsigned*)((const char*)(gbase) + (voff)[_i]), (PG8_LAS unsigned*)(lds + (bufoff) + ldsw + _i * 8192), 16, 0, 0); } while (0)
; #define PG8_LDA(dst, b, h) do { _Pragma("unroll") for (int m = 0; m < 4; ++m) _Pragma("unroll") for (int k = 0; k < 2; ++k) dst[m][k] = *(const PG8_LAS bf16x8*)(lds + PG8_SA(b, h) + aoff + m * 2048 + k * 1024); } while (0)
; #define PG8_LDB(dst, b, h) do { _Pragma("unroll") for (int n = 0; n < 2; ++n) _Pragma("unroll") for (int k = 0; k < 2; ++k) dst[n][k] = *(const PG8_LAS bf16x8*)(lds + PG8_SB(b, h) + boff + n * 2048 + k * 1024); } while (0)
; #define PG8_MMA(ai, bj, At, Bt) do { __builtin_amdgcn_s_setprio(1); _Pragma("unroll") for (int m = 0; m < 4; ++m) _Pragma("unroll") for (int n = 0; n < 2; ++n) _Pragma("unroll") for (int k = 0; k < 2; ++k) \
;         acc[ai][bj][m][n] = __builtin_amdgcn_mfma_f32_16x16x32_bf16(Bt[n][k], At[m][k], acc[ai][bj][m][n], 0, 0, 0); __builtin_amdgcn_s_setprio(0); } while (0)
; #define PG8_WAIT_V(n) asm volatile("s_waitcnt vmcnt(" #n ")" ::: "memory")
; #define PG8_WAIT_L(n) asm volatile("s_waitcnt lgkmcnt(" #n ")" ::: "memory")
; #define PG8_BAR __builtin_amdgcn_s_barrier()
; #define PG8_SCHED __builtin_amdgcn_sched_barrier(0)
; template <class Epi, class Sched, bool ALIGN_EPI = false, bool SP2 = false>
; __device__ __forceinline__ void gemm_phase(PG8_LAS unsigned char* lds, const Gemm g, const Sched& S, const Epi& E) {
;     ...
;             PG8_LDB(B0, 1, 0); PG8_LDB(B1, 1, 1); PG8_SCHED; PG8_LDA(At, 1, 0); PG8_STAGE(PG8_SA(0, 1), a2 + hstep, voffA);
;             PG8_WAIT_V(8); PG8_WAIT_L(0); PG8_BAR; PG8_MMA(0, 0, At, B0); PG8_MMA(0, 1, At, B1); PG8_BAR; PG8_SCHED;
;             PG8_LDA(At, 1, 1); PG8_STAGE(PG8_SB(1, 0), b3, voffB); PG8_STAGE(PG8_SB(1, 1), b3 + hstep, voffB); PG8_STAGE(PG8_SA(1, 0), a3, voffA);
;             PG8_WAIT_V(8); PG8_WAIT_L(0); PG8_BAR; PG8_MMA(1, 0, At, B0); PG8_MMA(1, 1, At, B1); PG8_BAR; PG8_SCHED;
	s_add_i32 s33, 0, 0x18000
	s_add_i32 s42, 0, 0x1c000
	ds_read_b128 v[160:163], v241 offset:32768
	ds_read_b128 v[166:169], v241 offset:33792
	ds_read_b128 v[170:173], v241 offset:34816
	ds_read_b128 v[174:177], v241 offset:35840
	ds_read_b128 v[178:181], v241 offset:49152
	ds_read_b128 v[182:185], v241 offset:50176
	ds_read_b128 v[186:189], v241 offset:51200
	ds_read_b128 v[190:193], v241 offset:52224
	s_add_u32 s26, s26, 0x100000
	s_addc_u32 s27, s27, 0
	s_mov_b32 m0, s37
	ds_read_b128 v[194:197], v155 offset:32768
	ds_read_b128 v[198:201], v155 offset:33792
	ds_read_b128 v[202:205], v155 offset:34816
	ds_read_b128 v[206:209], v155 offset:35840
	ds_read_b128 v[210:213], v155 offset:36864
	ds_read_b128 v[214:217], v155 offset:37888
	ds_read_b128 v[218:221], v155 offset:38912
	ds_read_b128 v[222:225], v155 offset:39936
	global_load_lds_dwordx4 v130, s[26:27]
	s_mov_b32 m0, s40
	s_nop 0
	global_load_lds_dwordx4 v134, s[26:27]
	s_waitcnt vmcnt(8)
	s_waitcnt lgkmcnt(0)
	s_barrier
	s_waitcnt lgkmcnt(0)
	v_mfma_f32_16x16x32_bf16 v[122:125], v[160:163], v[194:197], v[122:125]
	v_mfma_f32_16x16x32_bf16 v[114:117], v[170:173], v[194:197], v[114:117]
	v_mfma_f32_16x16x32_bf16 v[106:109], v[160:163], v[202:205], v[106:109]
	v_mfma_f32_16x16x32_bf16 v[98:101], v[170:173], v[202:205], v[98:101]
	v_mfma_f32_16x16x32_bf16 v[90:93], v[160:163], v[210:213], v[90:93]
	v_mfma_f32_16x16x32_bf16 v[82:85], v[170:173], v[210:213], v[82:85]
	v_mfma_f32_16x16x32_bf16 v[74:77], v[160:163], v[218:221], v[74:77]
	v_mfma_f32_16x16x32_bf16 v[62:65], v[170:173], v[218:221], v[62:65]
	v_mfma_f32_16x16x32_bf16 v[122:125], v[166:169], v[198:201], v[122:125]
	v_mfma_f32_16x16x32_bf16 v[114:117], v[174:177], v[198:201], v[114:117]
	v_mfma_f32_16x16x32_bf16 v[106:109], v[166:169], v[206:209], v[106:109]
	v_mfma_f32_16x16x32_bf16 v[98:101], v[174:177], v[206:209], v[98:101]
	v_mfma_f32_16x16x32_bf16 v[90:93], v[166:169], v[214:217], v[90:93]
	v_mfma_f32_16x16x32_bf16 v[82:85], v[174:177], v[214:217], v[82:85]
	v_mfma_f32_16x16x32_bf16 v[74:77], v[166:169], v[222:225], v[74:77]
	v_mfma_f32_16x16x32_bf16 v[62:65], v[174:177], v[222:225], v[62:65]
	v_mfma_f32_16x16x32_bf16 v[126:129], v[178:181], v[194:197], v[126:129]
	v_mfma_f32_16x16x32_bf16 v[118:121], v[186:189], v[194:197], v[118:121]
	v_mfma_f32_16x16x32_bf16 v[110:113], v[178:181], v[202:205], v[110:113]
	v_mfma_f32_16x16x32_bf16 v[102:105], v[186:189], v[202:205], v[102:105]
	v_mfma_f32_16x16x32_bf16 v[94:97], v[178:181], v[210:213], v[94:97]
	v_mfma_f32_16x16x32_bf16 v[86:89], v[186:189], v[210:213], v[86:89]
	v_mfma_f32_16x16x32_bf16 v[78:81], v[178:181], v[218:221], v[78:81]
	v_mfma_f32_16x16x32_bf16 v[70:73], v[186:189], v[218:221], v[70:73]
	v_mfma_f32_16x16x32_bf16 v[126:129], v[182:185], v[198:201], v[126:129]
	v_mfma_f32_16x16x32_bf16 v[118:121], v[190:193], v[198:201], v[118:121]
	v_mfma_f32_16x16x32_bf16 v[110:113], v[182:185], v[206:209], v[110:113]
	v_mfma_f32_16x16x32_bf16 v[102:105], v[190:193], v[206:209], v[102:105]
	v_mfma_f32_16x16x32_bf16 v[94:97], v[182:185], v[214:217], v[94:97]
	v_mfma_f32_16x16x32_bf16 v[86:89], v[190:193], v[214:217], v[86:89]
	v_mfma_f32_16x16x32_bf16 v[78:81], v[182:185], v[222:225], v[78:81]
	v_mfma_f32_16x16x32_bf16 v[70:73], v[190:193], v[222:225], v[70:73]
	s_barrier
	s_add_i32 s26, s33, s29
	s_add_i32 m0, s26, 0xffffff80
	ds_read_b128 v[194:197], v155 offset:49152
	ds_read_b128 v[198:201], v155 offset:50176
	ds_read_b128 v[202:205], v155 offset:51200
	ds_read_b128 v[206:209], v155 offset:52224
	ds_read_b128 v[210:213], v155 offset:53248
	ds_read_b128 v[214:217], v155 offset:54272
	ds_read_b128 v[218:221], v155 offset:55296
	ds_read_b128 v[222:225], v155 offset:56320
	global_load_lds_dwordx4 v132, s[22:23] offset:128
	s_add_i32 m0, s26, 0x1f80
	s_add_i32 s26, s42, s29
	global_load_lds_dwordx4 v136, s[22:23] offset:128
	s_add_u32 s22, s22, 0x100080
	s_addc_u32 s23, s23, 0
	s_mov_b32 m0, s26
	s_nop 0
	global_load_lds_dwordx4 v132, s[22:23]
	s_add_i32 m0, s26, 0x2000
	s_nop 0
	global_load_lds_dwordx4 v136, s[22:23]
	s_mov_b32 m0, s46
	s_nop 0
	global_load_lds_dwordx4 v130, s[100:101]
	s_mov_b32 m0, s47
	s_nop 0
	global_load_lds_dwordx4 v134, s[100:101]
	s_waitcnt vmcnt(8)
	s_waitcnt lgkmcnt(0)
	s_barrier
	s_waitcnt lgkmcnt(0)
	v_mfma_f32_16x16x32_bf16 v[58:61], v[160:163], v[194:197], v[58:61]
	v_mfma_f32_16x16x32_bf16 v[50:53], v[170:173], v[194:197], v[50:53]
	v_mfma_f32_16x16x32_bf16 v[42:45], v[160:163], v[202:205], v[42:45]
	v_mfma_f32_16x16x32_bf16 v[34:37], v[170:173], v[202:205], v[34:37]
	v_mfma_f32_16x16x32_bf16 v[26:29], v[160:163], v[210:213], v[26:29]
	v_mfma_f32_16x16x32_bf16 v[18:21], v[170:173], v[210:213], v[18:21]
	v_mfma_f32_16x16x32_bf16 v[10:13], v[160:163], v[218:221], v[10:13]
	v_mfma_f32_16x16x32_bf16 v[2:5], v[170:173], v[218:221], v[2:5]
	v_mfma_f32_16x16x32_bf16 v[58:61], v[166:169], v[198:201], v[58:61]
	v_mfma_f32_16x16x32_bf16 v[50:53], v[174:177], v[198:201], v[50:53]
	v_mfma_f32_16x16x32_bf16 v[42:45], v[166:169], v[206:209], v[42:45]
	v_mfma_f32_16x16x32_bf16 v[34:37], v[174:177], v[206:209], v[34:37]
	v_mfma_f32_16x16x32_bf16 v[26:29], v[166:169], v[214:217], v[26:29]
	v_mfma_f32_16x16x32_bf16 v[18:21], v[174:177], v[214:217], v[18:21]
	v_mfma_f32_16x16x32_bf16 v[10:13], v[166:169], v[222:225], v[10:13]
	v_mfma_f32_16x16x32_bf16 v[2:5], v[174:177], v[222:225], v[2:5]
	v_mfma_f32_16x16x32_bf16 v[66:69], v[178:181], v[194:197], v[66:69]
	v_mfma_f32_16x16x32_bf16 v[54:57], v[186:189], v[194:197], v[54:57]
	v_mfma_f32_16x16x32_bf16 v[46:49], v[178:181], v[202:205], v[46:49]
	v_mfma_f32_16x16x32_bf16 v[38:41], v[186:189], v[202:205], v[38:41]
	v_mfma_f32_16x16x32_bf16 v[30:33], v[178:181], v[210:213], v[30:33]
	v_mfma_f32_16x16x32_bf16 v[22:25], v[186:189], v[210:213], v[22:25]
	v_mfma_f32_16x16x32_bf16 v[14:17], v[178:181], v[218:221], v[14:17]
	v_mfma_f32_16x16x32_bf16 v[6:9], v[186:189], v[218:221], v[6:9]
	v_mfma_f32_16x16x32_bf16 v[66:69], v[182:185], v[198:201], v[66:69]
	v_mfma_f32_16x16x32_bf16 v[54:57], v[190:193], v[198:201], v[54:57]
	v_mfma_f32_16x16x32_bf16 v[46:49], v[182:185], v[206:209], v[46:49]
	v_mfma_f32_16x16x32_bf16 v[38:41], v[190:193], v[206:209], v[38:41]
	v_mfma_f32_16x16x32_bf16 v[30:33], v[182:185], v[214:217], v[30:33]
	v_mfma_f32_16x16x32_bf16 v[22:25], v[190:193], v[214:217], v[22:25]
	v_mfma_f32_16x16x32_bf16 v[14:17], v[182:185], v[222:225], v[14:17]
	v_mfma_f32_16x16x32_bf16 v[6:9], v[190:193], v[222:225], v[6:9]
	s_barrier
	s_add_i32 s68, s68, 2
	s_add_u32 s24, s24, 0x100
	s_addc_u32 s25, s25, 0
	s_add_u32 s66, s66, 0x100
	s_addc_u32 s67, s67, 0
	s_cmp_gt_u32 s68, 61
	s_cbranch_scc0 .LBB0_1126
	s_and_b64 vcc, exec, s[8:9]
	s_cbranch_vccz .LBB0_1129
	s_barrier

; #define PG8_STAGE(bufoff, gbase, voff) do { _Pragma("unroll") for (int _i = 0; _i < 2; ++_i) \
;         __builtin_amdgcn_global_load_lds((const unsigned*)((const char*)(gbase) + (voff)[_i]), (PG8_LAS unsigned*)(lds + (bufoff) + ldsw + _i * 8192), 16, 0, 0); } while (0)
; #define PG8_LDA(dst, b, h) do { _Pragma("unroll") for (int m = 0; m < 4; ++m) _Pragma("unroll") for (int k = 0; k < 2; ++k) dst[m][k] = *(const PG8_LAS bf16x8*)(lds + PG8_SA(b, h) + aoff + m * 2048 + k * 1024); } while (0)
; #define PG8_LDB(dst, b, h) do { _Pragma("unroll") for (int n = 0; n < 2; ++n) _Pragma("unroll") for (int k = 0; k < 2; ++k) dst[n][k] = *(const PG8_LAS bf16x8*)(lds + PG8_SB(b, h) + boff + n * 2048 + k * 1024); } while (0)
; #define PG8_MMA(ai, bj, At, Bt) do { __builtin_amdgcn_s_setprio(1); _Pragma("unroll") for (int m = 0; m < 4; ++m) _Pragma("unroll") for (int n = 0; n < 2; ++n) _Pragma("unroll") for (int k = 0; k < 2; ++k) \
;         acc[ai][bj][m][n] = __builtin_amdgcn_mfma_f32_16x16x32_bf16(Bt[n][k], At[m][k], acc[ai][bj][m][n], 0, 0, 0); __builtin_amdgcn_s_setprio(0); } while (0)
; #define PG8_WAIT_V(n) asm volatile("s_waitcnt vmcnt(" #n ")" ::: "memory")
; #define PG8_WAIT_L(n) asm volatile("s_waitcnt lgkmcnt(" #n ")" ::: "memory")
; template <class Epi, class Sched, bool ALIGN_EPI = false, bool SP2 = false>
; __device__ __forceinline__ void gemm_phase(PG8_LAS unsigned char* lds, const Gemm g, const Sched& S, const Epi& E) {
;     ...
;             const bool last = (t == nt - 2);
;             const char* a1 = cA + (size_t)(t + 1) * kstep;
;             const char* a2 = last ? nA : cA + (size_t)(t + 2) * kstep; const char* b2 = last ? nB : cB + (size_t)(t + 2) * kstep;
;             const char* a3 = a2 + kstep; const char* b3 = b2 + kstep;
;             if (last && has_next) S.a_ready(nxt);
;             if constexpr (SP2) {
;             PG8_LDB(B0, 0, 0); PG8_LDB(B1, 0, 1); PG8_SCHED; PG8_LDA(At, 0, 0); PG8_STAGE(PG8_SA(1, 1), a1 + hstep, voffA);
;             PG8_WAIT_V(8); PG8_WAIT_L(0); PG8_BAR; PG8_MMA(0, 0, At, B0); PG8_MMA(0, 1, At, B1); PG8_BAR; PG8_SCHED;
;             PG8_LDA(At, 0, 1); PG8_STAGE(PG8_SB(0, 0), b2, voffB); PG8_STAGE(PG8_SB(0, 1), b2 + hstep, voffB); PG8_STAGE(PG8_SA(0, 0), a2, voffA);
;             PG8_WAIT_V(8); PG8_WAIT_L(0); PG8_BAR; PG8_MMA(1, 0, At, B0); PG8_MMA(1, 1, At, B1); PG8_BAR; PG8_SCHED;
.LBB0_1245:
	ds_read_b128 v[130:133], v241 offset:0
	ds_read_b128 v[134:137], v241 offset:1024
	ds_read_b128 v[138:141], v241 offset:2048
	ds_read_b128 v[142:145], v241 offset:3072
	ds_read_b128 v[146:149], v241 offset:16384
	ds_read_b128 v[150:153], v241 offset:17408
	ds_read_b128 v[172:175], v241 offset:18432
	ds_read_b128 v[176:179], v241 offset:19456
	s_add_u32 s16, s18, 0xffd50080
	s_addc_u32 s17, s19, -1
	s_cmpk_eq_i32 s64, 0xa8
	s_cselect_b32 s21, s5, s17
	s_cselect_b32 s20, s4, s16
	s_cselect_b32 s17, s15, s63
	s_cselect_b32 s16, s14, s62
	s_add_i32 m0, s25, 0xc000
	ds_read_b128 v[180:183], v185
	ds_read_b128 v[188:191], v185 offset:1024
	ds_read_b128 v[192:195], v185 offset:2048
	ds_read_b128 v[196:199], v185 offset:3072
	ds_read_b128 v[200:203], v185 offset:4096
	ds_read_b128 v[204:207], v185 offset:5120
	ds_read_b128 v[208:211], v185 offset:6144
	ds_read_b128 v[212:215], v185 offset:7168
	global_load_lds_dwordx4 v162, s[18:19]
	s_add_i32 m0, s25, 0xe000
	s_nop 0
	global_load_lds_dwordx4 v166, s[18:19]
	s_waitcnt vmcnt(8)
	s_waitcnt lgkmcnt(0)
	s_barrier
	s_waitcnt lgkmcnt(0)
	v_mfma_f32_16x16x32_bf16 v[114:117], v[130:133], v[180:183], v[114:117]
	v_mfma_f32_16x16x32_bf16 v[118:121], v[138:141], v[180:183], v[118:121]
	v_mfma_f32_16x16x32_bf16 v[106:109], v[130:133], v[192:195], v[106:109]
	v_mfma_f32_16x16x32_bf16 v[98:101], v[138:141], v[192:195], v[98:101]
	v_mfma_f32_16x16x32_bf16 v[90:93], v[130:133], v[200:203], v[90:93]
	v_mfma_f32_16x16x32_bf16 v[82:85], v[138:141], v[200:203], v[82:85]
	v_mfma_f32_16x16x32_bf16 v[74:77], v[130:133], v[208:211], v[74:77]
	v_mfma_f32_16x16x32_bf16 v[66:69], v[138:141], v[208:211], v[66:69]
	v_mfma_f32_16x16x32_bf16 v[114:117], v[134:137], v[188:191], v[114:117]
	v_mfma_f32_16x16x32_bf16 v[118:121], v[142:145], v[188:191], v[118:121]
	v_mfma_f32_16x16x32_bf16 v[106:109], v[134:137], v[196:199], v[106:109]
	v_mfma_f32_16x16x32_bf16 v[98:101], v[142:145], v[196:199], v[98:101]
	v_mfma_f32_16x16x32_bf16 v[90:93], v[134:137], v[204:207], v[90:93]
	v_mfma_f32_16x16x32_bf16 v[82:85], v[142:145], v[204:207], v[82:85]
	v_mfma_f32_16x16x32_bf16 v[74:77], v[134:137], v[212:215], v[74:77]
	v_mfma_f32_16x16x32_bf16 v[66:69], v[142:145], v[212:215], v[66:69]
	v_mfma_f32_16x16x32_bf16 v[122:125], v[146:149], v[180:183], v[122:125]
	v_mfma_f32_16x16x32_bf16 v[126:129], v[172:175], v[180:183], v[126:129]
	v_mfma_f32_16x16x32_bf16 v[110:113], v[146:149], v[192:195], v[110:113]
	v_mfma_f32_16x16x32_bf16 v[102:105], v[172:175], v[192:195], v[102:105]
	v_mfma_f32_16x16x32_bf16 v[94:97], v[146:149], v[200:203], v[94:97]
	v_mfma_f32_16x16x32_bf16 v[86:89], v[172:175], v[200:203], v[86:89]
	v_mfma_f32_16x16x32_bf16 v[78:81], v[146:149], v[208:211], v[78:81]
	v_mfma_f32_16x16x32_bf16 v[70:73], v[172:175], v[208:211], v[70:73]
	v_mfma_f32_16x16x32_bf16 v[122:125], v[150:153], v[188:191], v[122:125]
	v_mfma_f32_16x16x32_bf16 v[126:129], v[176:179], v[188:191], v[126:129]
	v_mfma_f32_16x16x32_bf16 v[110:113], v[150:153], v[196:199], v[110:113]
	v_mfma_f32_16x16x32_bf16 v[102:105], v[176:179], v[196:199], v[102:105]
	v_mfma_f32_16x16x32_bf16 v[94:97], v[150:153], v[204:207], v[94:97]
	v_mfma_f32_16x16x32_bf16 v[86:89], v[176:179], v[204:207], v[86:89]
	v_mfma_f32_16x16x32_bf16 v[78:81], v[150:153], v[212:215], v[78:81]
	v_mfma_f32_16x16x32_bf16 v[70:73], v[176:179], v[212:215], v[70:73]
	s_barrier
	s_add_i32 s33, s40, s24
	s_mov_b32 m0, s33
	ds_read_b128 v[180:183], v185 offset:16384
	ds_read_b128 v[188:191], v185 offset:17408
	ds_read_b128 v[192:195], v185 offset:18432
	ds_read_b128 v[196:199], v185 offset:19456
	ds_read_b128 v[200:203], v185 offset:20480
	ds_read_b128 v[204:207], v185 offset:21504
	ds_read_b128 v[208:211], v185 offset:22528
	ds_read_b128 v[212:215], v185 offset:23552
	global_load_lds_dwordx4 v156, s[16:17]
	s_add_i32 m0, s33, 0x2000
	s_add_u32 s66, s16, 0x2b0000
	s_addc_u32 s67, s17, 0
	s_add_i32 s33, s41, s24
	global_load_lds_dwordx4 v160, s[16:17]
	s_mov_b32 m0, s33
	s_add_u32 s100, s20, 0x80
	s_addc_u32 s101, s21, 0
	global_load_lds_dwordx4 v156, s[66:67]
	s_add_i32 m0, s33, 0x2000
	s_nop 0
	global_load_lds_dwordx4 v160, s[66:67]
	s_mov_b32 m0, s25
	s_nop 0
	global_load_lds_dwordx4 v154, s[20:21]
	s_mov_b32 m0, s26
	s_nop 0
	global_load_lds_dwordx4 v158, s[20:21]
	s_waitcnt vmcnt(8)
	s_waitcnt lgkmcnt(0)
	s_barrier
	s_waitcnt lgkmcnt(0)
	v_mfma_f32_16x16x32_bf16 v[58:61], v[130:133], v[180:183], v[58:61]
	v_mfma_f32_16x16x32_bf16 v[54:57], v[138:141], v[180:183], v[54:57]
	v_mfma_f32_16x16x32_bf16 v[42:45], v[130:133], v[192:195], v[42:45]
	v_mfma_f32_16x16x32_bf16 v[34:37], v[138:141], v[192:195], v[34:37]
	v_mfma_f32_16x16x32_bf16 v[26:29], v[130:133], v[200:203], v[26:29]
	v_mfma_f32_16x16x32_bf16 v[18:21], v[138:141], v[200:203], v[18:21]
	v_mfma_f32_16x16x32_bf16 v[6:9], v[130:133], v[208:211], v[6:9]
	v_mfma_f32_16x16x32_bf16 v[2:5], v[138:141], v[208:211], v[2:5]
	v_mfma_f32_16x16x32_bf16 v[58:61], v[134:137], v[188:191], v[58:61]
	v_mfma_f32_16x16x32_bf16 v[54:57], v[142:145], v[188:191], v[54:57]
	v_mfma_f32_16x16x32_bf16 v[42:45], v[134:137], v[196:199], v[42:45]
	v_mfma_f32_16x16x32_bf16 v[34:37], v[142:145], v[196:199], v[34:37]
	v_mfma_f32_16x16x32_bf16 v[26:29], v[134:137], v[204:207], v[26:29]
	v_mfma_f32_16x16x32_bf16 v[18:21], v[142:145], v[204:207], v[18:21]
	v_mfma_f32_16x16x32_bf16 v[6:9], v[134:137], v[212:215], v[6:9]
	v_mfma_f32_16x16x32_bf16 v[2:5], v[142:145], v[212:215], v[2:5]
	v_mfma_f32_16x16x32_bf16 v[62:65], v[146:149], v[180:183], v[62:65]
	v_mfma_f32_16x16x32_bf16 v[50:53], v[172:175], v[180:183], v[50:53]
	v_mfma_f32_16x16x32_bf16 v[46:49], v[146:149], v[192:195], v[46:49]
	v_mfma_f32_16x16x32_bf16 v[38:41], v[172:175], v[192:195], v[38:41]
	v_mfma_f32_16x16x32_bf16 v[30:33], v[146:149], v[200:203], v[30:33]
	v_mfma_f32_16x16x32_bf16 v[22:25], v[172:175], v[200:203], v[22:25]
	v_mfma_f32_16x16x32_bf16 v[10:13], v[146:149], v[208:211], v[10:13]
	v_mfma_f32_16x16x32_bf16 v[14:17], v[172:175], v[208:211], v[14:17]
	v_mfma_f32_16x16x32_bf16 v[62:65], v[150:153], v[188:191], v[62:65]
	v_mfma_f32_16x16x32_bf16 v[50:53], v[176:179], v[188:191], v[50:53]
	v_mfma_f32_16x16x32_bf16 v[46:49], v[150:153], v[196:199], v[46:49]
	v_mfma_f32_16x16x32_bf16 v[38:41], v[176:179], v[196:199], v[38:41]
	v_mfma_f32_16x16x32_bf16 v[30:33], v[150:153], v[204:207], v[30:33]
	v_mfma_f32_16x16x32_bf16 v[22:25], v[176:179], v[204:207], v[22:25]
	v_mfma_f32_16x16x32_bf16 v[10:13], v[150:153], v[212:215], v[10:13]
	v_mfma_f32_16x16x32_bf16 v[14:17], v[176:179], v[212:215], v[14:17]
	s_barrier
; #define PG8_STAGE(bufoff, gbase, voff) do { _Pragma("unroll") for (int _i = 0; _i < 2; ++_i) \
;         __builtin_amdgcn_global_load_lds((const unsigned*)((const char*)(gbase) + (voff)[_i]), (PG8_LAS unsigned*)(lds + (bufoff) + ldsw + _i * 8192), 16, 0, 0); } while (0)
; #define PG8_LDA(dst, b, h) do { _Pragma("unroll") for (int m = 0; m < 4; ++m) _Pragma("unroll") for (int k = 0; k < 2; ++k) dst[m][k] = *(const PG8_LAS bf16x8*)(lds + PG8_SA(b, h) + aoff + m * 2048 + k * 1024); } while (0)
; #define PG8_LDB(dst, b, h) do { _Pragma("unroll") for (int n = 0; n < 2; ++n) _Pragma("unroll") for (int k = 0; k < 2; ++k) dst[n][k] = *(const PG8_LAS bf16x8*)(lds + PG8_SB(b, h) + boff + n * 2048 + k * 1024); } while (0)
; #define PG8_MMA(ai, bj, At, Bt) do { __builtin_amdgcn_s_setprio(1); _Pragma("unroll") for (int m = 0; m < 4; ++m) _Pragma("unroll") for (int n = 0; n < 2; ++n) _Pragma("unroll") for (int k = 0; k < 2; ++k) \
;         acc[ai][bj][m][n] = __builtin_amdgcn_mfma_f32_16x16x32_bf16(Bt[n][k], At[m][k], acc[ai][bj][m][n], 0, 0, 0); __builtin_amdgcn_s_setprio(0); } while (0)
; #define PG8_WAIT_V(n) asm volatile("s_waitcnt vmcnt(" #n ")" ::: "memory")
; #define PG8_WAIT_L(n) asm volatile("s_waitcnt lgkmcnt(" #n ")" ::: "memory")
; #define PG8_BAR __builtin_amdgcn_s_barrier()
; #define PG8_SCHED __builtin_amdgcn_sched_barrier(0)
; template <class Epi, class Sched, bool ALIGN_EPI = false, bool SP2 = false>
; __device__ __forceinline__ void gemm_phase(PG8_LAS unsigned char* lds, const Gemm g, const Sched& S, const Epi& E) {
;     ...
;             PG8_LDB(B0, 1, 0); PG8_LDB(B1, 1, 1); PG8_SCHED; PG8_LDA(At, 1, 0); PG8_STAGE(PG8_SA(0, 1), a2 + hstep, voffA);
;             PG8_WAIT_V(8); PG8_WAIT_L(0); PG8_BAR; PG8_MMA(0, 0, At, B0); PG8_MMA(0, 1, At, B1); PG8_BAR; PG8_SCHED;
;             PG8_LDA(At, 1, 1); PG8_STAGE(PG8_SB(1, 0), b3, voffB); PG8_STAGE(PG8_SB(1, 1), b3 + hstep, voffB); PG8_STAGE(PG8_SA(1, 0), a3, voffA);
;             PG8_WAIT_V(8); PG8_WAIT_L(0); PG8_BAR; PG8_MMA(1, 0, At, B0); PG8_MMA(1, 1, At, B1); PG8_BAR; PG8_SCHED;
	s_add_i32 s33, 0, 0x18000
	s_add_i32 s42, 0, 0x1c000
	ds_read_b128 v[130:133], v241 offset:32768
	ds_read_b128 v[134:137], v241 offset:33792
	ds_read_b128 v[138:141], v241 offset:34816
	ds_read_b128 v[142:145], v241 offset:35840
	ds_read_b128 v[146:149], v241 offset:49152
	ds_read_b128 v[150:153], v241 offset:50176
	ds_read_b128 v[172:175], v241 offset:51200
	ds_read_b128 v[176:179], v241 offset:52224
	s_add_u32 s20, s20, 0x2b0000
	s_addc_u32 s21, s21, 0
	s_mov_b32 m0, s27
	ds_read_b128 v[180:183], v185 offset:32768
	ds_read_b128 v[188:191], v185 offset:33792
	ds_read_b128 v[192:195], v185 offset:34816
	ds_read_b128 v[196:199], v185 offset:35840
	ds_read_b128 v[200:203], v185 offset:36864
	ds_read_b128 v[204:207], v185 offset:37888
	ds_read_b128 v[208:211], v185 offset:38912
	ds_read_b128 v[212:215], v185 offset:39936
	global_load_lds_dwordx4 v154, s[20:21]
	s_mov_b32 m0, s28
	s_nop 0
	global_load_lds_dwordx4 v158, s[20:21]
	s_waitcnt vmcnt(8)
	s_waitcnt lgkmcnt(0)
	s_barrier
	s_waitcnt lgkmcnt(0)
	v_mfma_f32_16x16x32_bf16 v[114:117], v[130:133], v[180:183], v[114:117]
	v_mfma_f32_16x16x32_bf16 v[118:121], v[138:141], v[180:183], v[118:121]
	v_mfma_f32_16x16x32_bf16 v[106:109], v[130:133], v[192:195], v[106:109]
	v_mfma_f32_16x16x32_bf16 v[98:101], v[138:141], v[192:195], v[98:101]
	v_mfma_f32_16x16x32_bf16 v[90:93], v[130:133], v[200:203], v[90:93]
	v_mfma_f32_16x16x32_bf16 v[82:85], v[138:141], v[200:203], v[82:85]
	v_mfma_f32_16x16x32_bf16 v[74:77], v[130:133], v[208:211], v[74:77]
	v_mfma_f32_16x16x32_bf16 v[66:69], v[138:141], v[208:211], v[66:69]
	v_mfma_f32_16x16x32_bf16 v[114:117], v[134:137], v[188:191], v[114:117]
	v_mfma_f32_16x16x32_bf16 v[118:121], v[142:145], v[188:191], v[118:121]
	v_mfma_f32_16x16x32_bf16 v[106:109], v[134:137], v[196:199], v[106:109]
	v_mfma_f32_16x16x32_bf16 v[98:101], v[142:145], v[196:199], v[98:101]
	v_mfma_f32_16x16x32_bf16 v[90:93], v[134:137], v[204:207], v[90:93]
	v_mfma_f32_16x16x32_bf16 v[82:85], v[142:145], v[204:207], v[82:85]
	v_mfma_f32_16x16x32_bf16 v[74:77], v[134:137], v[212:215], v[74:77]
	v_mfma_f32_16x16x32_bf16 v[66:69], v[142:145], v[212:215], v[66:69]
	v_mfma_f32_16x16x32_bf16 v[122:125], v[146:149], v[180:183], v[122:125]
	v_mfma_f32_16x16x32_bf16 v[126:129], v[172:175], v[180:183], v[126:129]
	v_mfma_f32_16x16x32_bf16 v[110:113], v[146:149], v[192:195], v[110:113]
	v_mfma_f32_16x16x32_bf16 v[102:105], v[172:175], v[192:195], v[102:105]
	v_mfma_f32_16x16x32_bf16 v[94:97], v[146:149], v[200:203], v[94:97]
	v_mfma_f32_16x16x32_bf16 v[86:89], v[172:175], v[200:203], v[86:89]
	v_mfma_f32_16x16x32_bf16 v[78:81], v[146:149], v[208:211], v[78:81]
	v_mfma_f32_16x16x32_bf16 v[70:73], v[172:175], v[208:211], v[70:73]
	v_mfma_f32_16x16x32_bf16 v[122:125], v[150:153], v[188:191], v[122:125]
	v_mfma_f32_16x16x32_bf16 v[126:129], v[176:179], v[188:191], v[126:129]
	v_mfma_f32_16x16x32_bf16 v[110:113], v[150:153], v[196:199], v[110:113]
	v_mfma_f32_16x16x32_bf16 v[102:105], v[176:179], v[196:199], v[102:105]
	v_mfma_f32_16x16x32_bf16 v[94:97], v[150:153], v[204:207], v[94:97]
	v_mfma_f32_16x16x32_bf16 v[86:89], v[176:179], v[204:207], v[86:89]
	v_mfma_f32_16x16x32_bf16 v[78:81], v[150:153], v[212:215], v[78:81]
	v_mfma_f32_16x16x32_bf16 v[70:73], v[176:179], v[212:215], v[70:73]
	s_barrier
	s_add_i32 s20, s33, s24
	s_add_i32 m0, s20, 0xffffff80
	ds_read_b128 v[180:183], v185 offset:49152
	ds_read_b128 v[188:191], v185 offset:50176
	ds_read_b128 v[192:195], v185 offset:51200
	ds_read_b128 v[196:199], v185 offset:52224
	ds_read_b128 v[200:203], v185 offset:53248
	ds_read_b128 v[204:207], v185 offset:54272
	ds_read_b128 v[208:211], v185 offset:55296
	ds_read_b128 v[212:215], v185 offset:56320
	global_load_lds_dwordx4 v156, s[16:17] offset:128
	s_add_i32 m0, s20, 0x1f80
	s_add_i32 s20, s42, s24
	global_load_lds_dwordx4 v160, s[16:17] offset:128
	s_add_u32 s16, s16, 0x2b0080
	s_addc_u32 s17, s17, 0
	s_mov_b32 m0, s20
	s_nop 0
	global_load_lds_dwordx4 v156, s[16:17]
	s_add_i32 m0, s20, 0x2000
	s_nop 0
	global_load_lds_dwordx4 v160, s[16:17]
	s_mov_b32 m0, s34
	s_nop 0
	global_load_lds_dwordx4 v154, s[100:101]
	s_mov_b32 m0, s35
	s_nop 0
	global_load_lds_dwordx4 v158, s[100:101]
	s_waitcnt vmcnt(8)
	s_waitcnt lgkmcnt(0)
	s_barrier
	s_waitcnt lgkmcnt(0)
	v_mfma_f32_16x16x32_bf16 v[58:61], v[130:133], v[180:183], v[58:61]
	v_mfma_f32_16x16x32_bf16 v[54:57], v[138:141], v[180:183], v[54:57]
	v_mfma_f32_16x16x32_bf16 v[42:45], v[130:133], v[192:195], v[42:45]
	v_mfma_f32_16x16x32_bf16 v[34:37], v[138:141], v[192:195], v[34:37]
	v_mfma_f32_16x16x32_bf16 v[26:29], v[130:133], v[200:203], v[26:29]
	v_mfma_f32_16x16x32_bf16 v[18:21], v[138:141], v[200:203], v[18:21]
	v_mfma_f32_16x16x32_bf16 v[6:9], v[130:133], v[208:211], v[6:9]
	v_mfma_f32_16x16x32_bf16 v[2:5], v[138:141], v[208:211], v[2:5]
	v_mfma_f32_16x16x32_bf16 v[58:61], v[134:137], v[188:191], v[58:61]
	v_mfma_f32_16x16x32_bf16 v[54:57], v[142:145], v[188:191], v[54:57]
	v_mfma_f32_16x16x32_bf16 v[42:45], v[134:137], v[196:199], v[42:45]
	v_mfma_f32_16x16x32_bf16 v[34:37], v[142:145], v[196:199], v[34:37]
	v_mfma_f32_16x16x32_bf16 v[26:29], v[134:137], v[204:207], v[26:29]
	v_mfma_f32_16x16x32_bf16 v[18:21], v[142:145], v[204:207], v[18:21]
	v_mfma_f32_16x16x32_bf16 v[6:9], v[134:137], v[212:215], v[6:9]
	v_mfma_f32_16x16x32_bf16 v[2:5], v[142:145], v[212:215], v[2:5]
	v_mfma_f32_16x16x32_bf16 v[62:65], v[146:149], v[180:183], v[62:65]
	v_mfma_f32_16x16x32_bf16 v[50:53], v[172:175], v[180:183], v[50:53]
	v_mfma_f32_16x16x32_bf16 v[46:49], v[146:149], v[192:195], v[46:49]
	v_mfma_f32_16x16x32_bf16 v[38:41], v[172:175], v[192:195], v[38:41]
	v_mfma_f32_16x16x32_bf16 v[30:33], v[146:149], v[200:203], v[30:33]
	v_mfma_f32_16x16x32_bf16 v[22:25], v[172:175], v[200:203], v[22:25]
	v_mfma_f32_16x16x32_bf16 v[10:13], v[146:149], v[208:211], v[10:13]
	v_mfma_f32_16x16x32_bf16 v[14:17], v[172:175], v[208:211], v[14:17]
	v_mfma_f32_16x16x32_bf16 v[62:65], v[150:153], v[188:191], v[62:65]
	v_mfma_f32_16x16x32_bf16 v[50:53], v[176:179], v[188:191], v[50:53]
	v_mfma_f32_16x16x32_bf16 v[46:49], v[150:153], v[196:199], v[46:49]
	v_mfma_f32_16x16x32_bf16 v[38:41], v[176:179], v[196:199], v[38:41]
	v_mfma_f32_16x16x32_bf16 v[30:33], v[150:153], v[204:207], v[30:33]
	v_mfma_f32_16x16x32_bf16 v[22:25], v[176:179], v[204:207], v[22:25]
	v_mfma_f32_16x16x32_bf16 v[10:13], v[150:153], v[212:215], v[10:13]
	v_mfma_f32_16x16x32_bf16 v[14:17], v[176:179], v[212:215], v[14:17]
	s_barrier
	s_add_i32 s64, s64, 2
	s_add_u32 s18, s18, 0x100
	s_addc_u32 s19, s19, 0
	s_add_u32 s62, s62, 0x100
	s_addc_u32 s63, s63, 0
	s_cmpk_gt_u32 s64, 0xa9
	s_cbranch_scc0 .LBB0_1245
	s_and_b64 vcc, exec, s[12:13]
	s_cbranch_vccz .LBB0_1248
	s_barrier

; #define PG8_STAGE(bufoff, gbase, voff) do { _Pragma("unroll") for (int _i = 0; _i < 2; ++_i) \
;         __builtin_amdgcn_global_load_lds((const unsigned*)((const char*)(gbase) + (voff)[_i]), (PG8_LAS unsigned*)(lds + (bufoff) + ldsw + _i * 8192), 16, 0, 0); } while (0)
; #define PG8_LDA(dst, b, h) do { _Pragma("unroll") for (int m = 0; m < 4; ++m) _Pragma("unroll") for (int k = 0; k < 2; ++k) dst[m][k] = *(const PG8_LAS bf16x8*)(lds + PG8_SA(b, h) + aoff + m * 2048 + k * 1024); } while (0)
; #define PG8_LDB(dst, b, h) do { _Pragma("unroll") for (int n = 0; n < 2; ++n) _Pragma("unroll") for (int k = 0; k < 2; ++k) dst[n][k] = *(const PG8_LAS bf16x8*)(lds + PG8_SB(b, h) + boff + n * 2048 + k * 1024); } while (0)
; #define PG8_MMA(ai, bj, At, Bt) do { __builtin_amdgcn_s_setprio(1); _Pragma("unroll") for (int m = 0; m < 4; ++m) _Pragma("unroll") for (int n = 0; n < 2; ++n) _Pragma("unroll") for (int k = 0; k < 2; ++k) \
;         acc[ai][bj][m][n] = __builtin_amdgcn_mfma_f32_16x16x32_bf16(Bt[n][k], At[m][k], acc[ai][bj][m][n], 0, 0, 0); __builtin_amdgcn_s_setprio(0); } while (0)
; #define PG8_WAIT_V(n) asm volatile("s_waitcnt vmcnt(" #n ")" ::: "memory")
; #define PG8_WAIT_L(n) asm volatile("s_waitcnt lgkmcnt(" #n ")" ::: "memory")
; template <class Epi, class Sched, bool ALIGN_EPI = false, bool SP2 = false>
; __device__ __forceinline__ void gemm_phase(PG8_LAS unsigned char* lds, const Gemm g, const Sched& S, const Epi& E) {
;     ...
;             const bool last = (t == nt - 2);
;             const char* a1 = cA + (size_t)(t + 1) * kstep;
;             const char* a2 = last ? nA : cA + (size_t)(t + 2) * kstep; const char* b2 = last ? nB : cB + (size_t)(t + 2) * kstep;
;             const char* a3 = a2 + kstep; const char* b3 = b2 + kstep;
;             if (last && has_next) S.a_ready(nxt);
;             if constexpr (SP2) {
;             PG8_LDB(B0, 0, 0); PG8_LDB(B1, 0, 1); PG8_SCHED; PG8_LDA(At, 0, 0); PG8_STAGE(PG8_SA(1, 1), a1 + hstep, voffA);
;             PG8_WAIT_V(8); PG8_WAIT_L(0); PG8_BAR; PG8_MMA(0, 0, At, B0); PG8_MMA(0, 1, At, B1); PG8_BAR; PG8_SCHED;
;             PG8_LDA(At, 0, 1); PG8_STAGE(PG8_SB(0, 0), b2, voffB); PG8_STAGE(PG8_SB(0, 1), b2 + hstep, voffB); PG8_STAGE(PG8_SA(0, 0), a2, voffA);
;             PG8_WAIT_V(8); PG8_WAIT_L(0); PG8_BAR; PG8_MMA(1, 0, At, B0); PG8_MMA(1, 1, At, B1); PG8_BAR; PG8_SCHED;
.LBB0_1332:
	ds_read_b128 v[148:151], v241 offset:0
	ds_read_b128 v[156:159], v241 offset:1024
	ds_read_b128 v[166:169], v241 offset:2048
	ds_read_b128 v[170:173], v241 offset:3072
	ds_read_b128 v[174:177], v241 offset:16384
	ds_read_b128 v[178:181], v241 offset:17408
	ds_read_b128 v[182:185], v241 offset:18432
	ds_read_b128 v[186:189], v241 offset:19456
	s_add_u32 s20, s22, 0xfff00080
	s_addc_u32 s21, s23, -1
	s_cmp_eq_u32 s67, 60
	s_cselect_b32 s25, s13, s21
	s_cselect_b32 s24, s63, s20
	s_cselect_b32 s21, s11, s66
	s_cselect_b32 s20, s64, s65
	s_add_i32 m0, s19, 0xc000
	ds_read_b128 v[190:193], v155
	ds_read_b128 v[194:197], v155 offset:1024
	ds_read_b128 v[198:201], v155 offset:2048
	ds_read_b128 v[202:205], v155 offset:3072
	ds_read_b128 v[206:209], v155 offset:4096
	ds_read_b128 v[210:213], v155 offset:5120
	ds_read_b128 v[214:217], v155 offset:6144
	ds_read_b128 v[218:221], v155 offset:7168
	global_load_lds_dwordx4 v138, s[22:23]
	s_add_i32 m0, s19, 0xe000
	s_nop 0
	global_load_lds_dwordx4 v140, s[22:23]
	s_waitcnt vmcnt(8)
	s_waitcnt lgkmcnt(0)
	s_barrier
	s_waitcnt lgkmcnt(0)
	v_mfma_f32_16x16x32_bf16 v[118:121], v[148:151], v[190:193], v[118:121]
	v_mfma_f32_16x16x32_bf16 v[114:117], v[166:169], v[190:193], v[114:117]
	v_mfma_f32_16x16x32_bf16 v[102:105], v[148:151], v[198:201], v[102:105]
	v_mfma_f32_16x16x32_bf16 v[98:101], v[166:169], v[198:201], v[98:101]
	v_mfma_f32_16x16x32_bf16 v[86:89], v[148:151], v[206:209], v[86:89]
	v_mfma_f32_16x16x32_bf16 v[82:85], v[166:169], v[206:209], v[82:85]
	v_mfma_f32_16x16x32_bf16 v[70:73], v[148:151], v[214:217], v[70:73]
	v_mfma_f32_16x16x32_bf16 v[66:69], v[166:169], v[214:217], v[66:69]
	v_mfma_f32_16x16x32_bf16 v[118:121], v[156:159], v[194:197], v[118:121]
	v_mfma_f32_16x16x32_bf16 v[114:117], v[170:173], v[194:197], v[114:117]
	v_mfma_f32_16x16x32_bf16 v[102:105], v[156:159], v[202:205], v[102:105]
	v_mfma_f32_16x16x32_bf16 v[98:101], v[170:173], v[202:205], v[98:101]
	v_mfma_f32_16x16x32_bf16 v[86:89], v[156:159], v[210:213], v[86:89]
	v_mfma_f32_16x16x32_bf16 v[82:85], v[170:173], v[210:213], v[82:85]
	v_mfma_f32_16x16x32_bf16 v[70:73], v[156:159], v[218:221], v[70:73]
	v_mfma_f32_16x16x32_bf16 v[66:69], v[170:173], v[218:221], v[66:69]
	v_mfma_f32_16x16x32_bf16 v[126:129], v[174:177], v[190:193], v[126:129]
	v_mfma_f32_16x16x32_bf16 v[122:125], v[182:185], v[190:193], v[122:125]
	v_mfma_f32_16x16x32_bf16 v[110:113], v[174:177], v[198:201], v[110:113]
	v_mfma_f32_16x16x32_bf16 v[106:109], v[182:185], v[198:201], v[106:109]
	v_mfma_f32_16x16x32_bf16 v[94:97], v[174:177], v[206:209], v[94:97]
	v_mfma_f32_16x16x32_bf16 v[90:93], v[182:185], v[206:209], v[90:93]
	v_mfma_f32_16x16x32_bf16 v[78:81], v[174:177], v[214:217], v[78:81]
	v_mfma_f32_16x16x32_bf16 v[74:77], v[182:185], v[214:217], v[74:77]
	v_mfma_f32_16x16x32_bf16 v[126:129], v[178:181], v[194:197], v[126:129]
	v_mfma_f32_16x16x32_bf16 v[122:125], v[186:189], v[194:197], v[122:125]
	v_mfma_f32_16x16x32_bf16 v[110:113], v[178:181], v[202:205], v[110:113]
	v_mfma_f32_16x16x32_bf16 v[106:109], v[186:189], v[202:205], v[106:109]
	v_mfma_f32_16x16x32_bf16 v[94:97], v[178:181], v[210:213], v[94:97]
	v_mfma_f32_16x16x32_bf16 v[90:93], v[186:189], v[210:213], v[90:93]
	v_mfma_f32_16x16x32_bf16 v[78:81], v[178:181], v[218:221], v[78:81]
	v_mfma_f32_16x16x32_bf16 v[74:77], v[186:189], v[218:221], v[74:77]
	s_barrier
	s_add_i32 s33, s47, s28
	s_mov_b32 m0, s33
	ds_read_b128 v[190:193], v155 offset:16384
	ds_read_b128 v[194:197], v155 offset:17408
	ds_read_b128 v[198:201], v155 offset:18432
	ds_read_b128 v[202:205], v155 offset:19456
	ds_read_b128 v[206:209], v155 offset:20480
	ds_read_b128 v[210:213], v155 offset:21504
	ds_read_b128 v[214:217], v155 offset:22528
	ds_read_b128 v[218:221], v155 offset:23552
	global_load_lds_dwordx4 v132, s[20:21]
	s_add_i32 m0, s33, 0x2000
	s_add_u32 s68, s20, 0x100000
	s_addc_u32 s69, s21, 0
	s_add_i32 s33, s52, s28
	global_load_lds_dwordx4 v136, s[20:21]
	s_mov_b32 m0, s33
	s_add_u32 s100, s24, 0x80
	s_addc_u32 s101, s25, 0
	global_load_lds_dwordx4 v132, s[68:69]
	s_add_i32 m0, s33, 0x2000
	s_nop 0
	global_load_lds_dwordx4 v136, s[68:69]
	s_mov_b32 m0, s19
	s_nop 0
	global_load_lds_dwordx4 v130, s[24:25]
	s_mov_b32 m0, s35
	s_nop 0
	global_load_lds_dwordx4 v134, s[24:25]
	s_waitcnt vmcnt(8)
	s_waitcnt lgkmcnt(0)
	s_barrier
	s_waitcnt lgkmcnt(0)
	v_mfma_f32_16x16x32_bf16 v[54:57], v[148:151], v[190:193], v[54:57]
	v_mfma_f32_16x16x32_bf16 v[50:53], v[166:169], v[190:193], v[50:53]
	v_mfma_f32_16x16x32_bf16 v[38:41], v[148:151], v[198:201], v[38:41]
	v_mfma_f32_16x16x32_bf16 v[34:37], v[166:169], v[198:201], v[34:37]
	v_mfma_f32_16x16x32_bf16 v[22:25], v[148:151], v[206:209], v[22:25]
	v_mfma_f32_16x16x32_bf16 v[18:21], v[166:169], v[206:209], v[18:21]
	v_mfma_f32_16x16x32_bf16 v[6:9], v[148:151], v[214:217], v[6:9]
	v_mfma_f32_16x16x32_bf16 v[2:5], v[166:169], v[214:217], v[2:5]
	v_mfma_f32_16x16x32_bf16 v[54:57], v[156:159], v[194:197], v[54:57]
	v_mfma_f32_16x16x32_bf16 v[50:53], v[170:173], v[194:197], v[50:53]
	v_mfma_f32_16x16x32_bf16 v[38:41], v[156:159], v[202:205], v[38:41]
	v_mfma_f32_16x16x32_bf16 v[34:37], v[170:173], v[202:205], v[34:37]
	v_mfma_f32_16x16x32_bf16 v[22:25], v[156:159], v[210:213], v[22:25]
	v_mfma_f32_16x16x32_bf16 v[18:21], v[170:173], v[210:213], v[18:21]
	v_mfma_f32_16x16x32_bf16 v[6:9], v[156:159], v[218:221], v[6:9]
	v_mfma_f32_16x16x32_bf16 v[2:5], v[170:173], v[218:221], v[2:5]
	v_mfma_f32_16x16x32_bf16 v[62:65], v[174:177], v[190:193], v[62:65]
	v_mfma_f32_16x16x32_bf16 v[58:61], v[182:185], v[190:193], v[58:61]
	v_mfma_f32_16x16x32_bf16 v[46:49], v[174:177], v[198:201], v[46:49]
	v_mfma_f32_16x16x32_bf16 v[42:45], v[182:185], v[198:201], v[42:45]
	v_mfma_f32_16x16x32_bf16 v[30:33], v[174:177], v[206:209], v[30:33]
	v_mfma_f32_16x16x32_bf16 v[26:29], v[182:185], v[206:209], v[26:29]
	v_mfma_f32_16x16x32_bf16 v[10:13], v[174:177], v[214:217], v[10:13]
	v_mfma_f32_16x16x32_bf16 v[14:17], v[182:185], v[214:217], v[14:17]
	v_mfma_f32_16x16x32_bf16 v[62:65], v[178:181], v[194:197], v[62:65]
	v_mfma_f32_16x16x32_bf16 v[58:61], v[186:189], v[194:197], v[58:61]
	v_mfma_f32_16x16x32_bf16 v[46:49], v[178:181], v[202:205], v[46:49]
	v_mfma_f32_16x16x32_bf16 v[42:45], v[186:189], v[202:205], v[42:45]
	v_mfma_f32_16x16x32_bf16 v[30:33], v[178:181], v[210:213], v[30:33]
	v_mfma_f32_16x16x32_bf16 v[26:29], v[186:189], v[210:213], v[26:29]
	v_mfma_f32_16x16x32_bf16 v[10:13], v[178:181], v[218:221], v[10:13]
	v_mfma_f32_16x16x32_bf16 v[14:17], v[186:189], v[218:221], v[14:17]
	s_barrier
; #define PG8_STAGE(bufoff, gbase, voff) do { _Pragma("unroll") for (int _i = 0; _i < 2; ++_i) \
;         __builtin_amdgcn_global_load_lds((const unsigned*)((const char*)(gbase) + (voff)[_i]), (PG8_LAS unsigned*)(lds + (bufoff) + ldsw + _i * 8192), 16, 0, 0); } while (0)
; #define PG8_LDA(dst, b, h) do { _Pragma("unroll") for (int m = 0; m < 4; ++m) _Pragma("unroll") for (int k = 0; k < 2; ++k) dst[m][k] = *(const PG8_LAS bf16x8*)(lds + PG8_SA(b, h) + aoff + m * 2048 + k * 1024); } while (0)
; #define PG8_LDB(dst, b, h) do { _Pragma("unroll") for (int n = 0; n < 2; ++n) _Pragma("unroll") for (int k = 0; k < 2; ++k) dst[n][k] = *(const PG8_LAS bf16x8*)(lds + PG8_SB(b, h) + boff + n * 2048 + k * 1024); } while (0)
; #define PG8_MMA(ai, bj, At, Bt) do { __builtin_amdgcn_s_setprio(1); _Pragma("unroll") for (int m = 0; m < 4; ++m) _Pragma("unroll") for (int n = 0; n < 2; ++n) _Pragma("unroll") for (int k = 0; k < 2; ++k) \
;         acc[ai][bj][m][n] = __builtin_amdgcn_mfma_f32_16x16x32_bf16(Bt[n][k], At[m][k], acc[ai][bj][m][n], 0, 0, 0); __builtin_amdgcn_s_setprio(0); } while (0)
; #define PG8_WAIT_V(n) asm volatile("s_waitcnt vmcnt(" #n ")" ::: "memory")
; #define PG8_WAIT_L(n) asm volatile("s_waitcnt lgkmcnt(" #n ")" ::: "memory")
; #define PG8_BAR __builtin_amdgcn_s_barrier()
; #define PG8_SCHED __builtin_amdgcn_sched_barrier(0)
; template <class Epi, class Sched, bool ALIGN_EPI = false, bool SP2 = false>
; __device__ __forceinline__ void gemm_phase(PG8_LAS unsigned char* lds, const Gemm g, const Sched& S, const Epi& E) {
;     ...
;             PG8_LDB(B0, 1, 0); PG8_LDB(B1, 1, 1); PG8_SCHED; PG8_LDA(At, 1, 0); PG8_STAGE(PG8_SA(0, 1), a2 + hstep, voffA);
;             PG8_WAIT_V(8); PG8_WAIT_L(0); PG8_BAR; PG8_MMA(0, 0, At, B0); PG8_MMA(0, 1, At, B1); PG8_BAR; PG8_SCHED;
;             PG8_LDA(At, 1, 1); PG8_STAGE(PG8_SB(1, 0), b3, voffB); PG8_STAGE(PG8_SB(1, 1), b3 + hstep, voffB); PG8_STAGE(PG8_SA(1, 0), a3, voffA);
;             PG8_WAIT_V(8); PG8_WAIT_L(0); PG8_BAR; PG8_MMA(1, 0, At, B0); PG8_MMA(1, 1, At, B1); PG8_BAR; PG8_SCHED;
	s_add_i32 s33, 0, 0x18000
	s_add_i32 s42, 0, 0x1c000
	ds_read_b128 v[148:151], v241 offset:32768
	ds_read_b128 v[156:159], v241 offset:33792
	ds_read_b128 v[166:169], v241 offset:34816
	ds_read_b128 v[170:173], v241 offset:35840
	ds_read_b128 v[174:177], v241 offset:49152
	ds_read_b128 v[178:181], v241 offset:50176
	ds_read_b128 v[182:185], v241 offset:51200
	ds_read_b128 v[186:189], v241 offset:52224
	s_add_u32 s24, s24, 0x100000
	s_addc_u32 s25, s25, 0
	s_mov_b32 m0, s36
	ds_read_b128 v[190:193], v155 offset:32768
	ds_read_b128 v[194:197], v155 offset:33792
	ds_read_b128 v[198:201], v155 offset:34816
	ds_read_b128 v[202:205], v155 offset:35840
	ds_read_b128 v[206:209], v155 offset:36864
	ds_read_b128 v[210:213], v155 offset:37888
	ds_read_b128 v[214:217], v155 offset:38912
	ds_read_b128 v[218:221], v155 offset:39936
	global_load_lds_dwordx4 v130, s[24:25]
	s_mov_b32 m0, s37
	s_nop 0
	global_load_lds_dwordx4 v134, s[24:25]
	s_waitcnt vmcnt(8)
	s_waitcnt lgkmcnt(0)
	s_barrier
	s_waitcnt lgkmcnt(0)
	v_mfma_f32_16x16x32_bf16 v[118:121], v[148:151], v[190:193], v[118:121]
	v_mfma_f32_16x16x32_bf16 v[114:117], v[166:169], v[190:193], v[114:117]
	v_mfma_f32_16x16x32_bf16 v[102:105], v[148:151], v[198:201], v[102:105]
	v_mfma_f32_16x16x32_bf16 v[98:101], v[166:169], v[198:201], v[98:101]
	v_mfma_f32_16x16x32_bf16 v[86:89], v[148:151], v[206:209], v[86:89]
	v_mfma_f32_16x16x32_bf16 v[82:85], v[166:169], v[206:209], v[82:85]
	v_mfma_f32_16x16x32_bf16 v[70:73], v[148:151], v[214:217], v[70:73]
	v_mfma_f32_16x16x32_bf16 v[66:69], v[166:169], v[214:217], v[66:69]
	v_mfma_f32_16x16x32_bf16 v[118:121], v[156:159], v[194:197], v[118:121]
	v_mfma_f32_16x16x32_bf16 v[114:117], v[170:173], v[194:197], v[114:117]
	v_mfma_f32_16x16x32_bf16 v[102:105], v[156:159], v[202:205], v[102:105]
	v_mfma_f32_16x16x32_bf16 v[98:101], v[170:173], v[202:205], v[98:101]
	v_mfma_f32_16x16x32_bf16 v[86:89], v[156:159], v[210:213], v[86:89]
	v_mfma_f32_16x16x32_bf16 v[82:85], v[170:173], v[210:213], v[82:85]
	v_mfma_f32_16x16x32_bf16 v[70:73], v[156:159], v[218:221], v[70:73]
	v_mfma_f32_16x16x32_bf16 v[66:69], v[170:173], v[218:221], v[66:69]
	v_mfma_f32_16x16x32_bf16 v[126:129], v[174:177], v[190:193], v[126:129]
	v_mfma_f32_16x16x32_bf16 v[122:125], v[182:185], v[190:193], v[122:125]
	v_mfma_f32_16x16x32_bf16 v[110:113], v[174:177], v[198:201], v[110:113]
	v_mfma_f32_16x16x32_bf16 v[106:109], v[182:185], v[198:201], v[106:109]
	v_mfma_f32_16x16x32_bf16 v[94:97], v[174:177], v[206:209], v[94:97]
	v_mfma_f32_16x16x32_bf16 v[90:93], v[182:185], v[206:209], v[90:93]
	v_mfma_f32_16x16x32_bf16 v[78:81], v[174:177], v[214:217], v[78:81]
	v_mfma_f32_16x16x32_bf16 v[74:77], v[182:185], v[214:217], v[74:77]
	v_mfma_f32_16x16x32_bf16 v[126:129], v[178:181], v[194:197], v[126:129]
	v_mfma_f32_16x16x32_bf16 v[122:125], v[186:189], v[194:197], v[122:125]
	v_mfma_f32_16x16x32_bf16 v[110:113], v[178:181], v[202:205], v[110:113]
	v_mfma_f32_16x16x32_bf16 v[106:109], v[186:189], v[202:205], v[106:109]
	v_mfma_f32_16x16x32_bf16 v[94:97], v[178:181], v[210:213], v[94:97]
	v_mfma_f32_16x16x32_bf16 v[90:93], v[186:189], v[210:213], v[90:93]
	v_mfma_f32_16x16x32_bf16 v[78:81], v[178:181], v[218:221], v[78:81]
	v_mfma_f32_16x16x32_bf16 v[74:77], v[186:189], v[218:221], v[74:77]
	s_barrier
	s_add_i32 s24, s33, s28
	s_add_i32 m0, s24, 0xffffff80
	ds_read_b128 v[190:193], v155 offset:49152
	ds_read_b128 v[194:197], v155 offset:50176
	ds_read_b128 v[198:201], v155 offset:51200
	ds_read_b128 v[202:205], v155 offset:52224
	ds_read_b128 v[206:209], v155 offset:53248
	ds_read_b128 v[210:213], v155 offset:54272
	ds_read_b128 v[214:217], v155 offset:55296
	ds_read_b128 v[218:221], v155 offset:56320
	global_load_lds_dwordx4 v132, s[20:21] offset:128
	s_add_i32 m0, s24, 0x1f80
	s_add_i32 s24, s42, s28
	global_load_lds_dwordx4 v136, s[20:21] offset:128
	s_add_u32 s20, s20, 0x100080
	s_addc_u32 s21, s21, 0
	s_mov_b32 m0, s24
	s_nop 0
	global_load_lds_dwordx4 v132, s[20:21]
	s_add_i32 m0, s24, 0x2000
	s_nop 0
	global_load_lds_dwordx4 v136, s[20:21]
	s_mov_b32 m0, s43
	s_nop 0
	global_load_lds_dwordx4 v130, s[100:101]
	s_mov_b32 m0, s46
	s_nop 0
	global_load_lds_dwordx4 v134, s[100:101]
	s_waitcnt vmcnt(8)
	s_waitcnt lgkmcnt(0)
	s_barrier
	s_waitcnt lgkmcnt(0)
	v_mfma_f32_16x16x32_bf16 v[54:57], v[148:151], v[190:193], v[54:57]
	v_mfma_f32_16x16x32_bf16 v[50:53], v[166:169], v[190:193], v[50:53]
	v_mfma_f32_16x16x32_bf16 v[38:41], v[148:151], v[198:201], v[38:41]
	v_mfma_f32_16x16x32_bf16 v[34:37], v[166:169], v[198:201], v[34:37]
	v_mfma_f32_16x16x32_bf16 v[22:25], v[148:151], v[206:209], v[22:25]
	v_mfma_f32_16x16x32_bf16 v[18:21], v[166:169], v[206:209], v[18:21]
	v_mfma_f32_16x16x32_bf16 v[6:9], v[148:151], v[214:217], v[6:9]
	v_mfma_f32_16x16x32_bf16 v[2:5], v[166:169], v[214:217], v[2:5]
	v_mfma_f32_16x16x32_bf16 v[54:57], v[156:159], v[194:197], v[54:57]
	v_mfma_f32_16x16x32_bf16 v[50:53], v[170:173], v[194:197], v[50:53]
	v_mfma_f32_16x16x32_bf16 v[38:41], v[156:159], v[202:205], v[38:41]
	v_mfma_f32_16x16x32_bf16 v[34:37], v[170:173], v[202:205], v[34:37]
	v_mfma_f32_16x16x32_bf16 v[22:25], v[156:159], v[210:213], v[22:25]
	v_mfma_f32_16x16x32_bf16 v[18:21], v[170:173], v[210:213], v[18:21]
	v_mfma_f32_16x16x32_bf16 v[6:9], v[156:159], v[218:221], v[6:9]
	v_mfma_f32_16x16x32_bf16 v[2:5], v[170:173], v[218:221], v[2:5]
	v_mfma_f32_16x16x32_bf16 v[62:65], v[174:177], v[190:193], v[62:65]
	v_mfma_f32_16x16x32_bf16 v[58:61], v[182:185], v[190:193], v[58:61]
	v_mfma_f32_16x16x32_bf16 v[46:49], v[174:177], v[198:201], v[46:49]
	v_mfma_f32_16x16x32_bf16 v[42:45], v[182:185], v[198:201], v[42:45]
	v_mfma_f32_16x16x32_bf16 v[30:33], v[174:177], v[206:209], v[30:33]
	v_mfma_f32_16x16x32_bf16 v[26:29], v[182:185], v[206:209], v[26:29]
	v_mfma_f32_16x16x32_bf16 v[10:13], v[174:177], v[214:217], v[10:13]
	v_mfma_f32_16x16x32_bf16 v[14:17], v[182:185], v[214:217], v[14:17]
	v_mfma_f32_16x16x32_bf16 v[62:65], v[178:181], v[194:197], v[62:65]
	v_mfma_f32_16x16x32_bf16 v[58:61], v[186:189], v[194:197], v[58:61]
	v_mfma_f32_16x16x32_bf16 v[46:49], v[178:181], v[202:205], v[46:49]
	v_mfma_f32_16x16x32_bf16 v[42:45], v[186:189], v[202:205], v[42:45]
	v_mfma_f32_16x16x32_bf16 v[30:33], v[178:181], v[210:213], v[30:33]
	v_mfma_f32_16x16x32_bf16 v[26:29], v[186:189], v[210:213], v[26:29]
	v_mfma_f32_16x16x32_bf16 v[10:13], v[178:181], v[218:221], v[10:13]
	v_mfma_f32_16x16x32_bf16 v[14:17], v[186:189], v[218:221], v[14:17]
	s_barrier
	s_add_i32 s67, s67, 2
	s_add_u32 s22, s22, 0x100
	s_addc_u32 s23, s23, 0
	s_add_u32 s65, s65, 0x100
	s_addc_u32 s66, s66, 0
	s_cmp_gt_u32 s67, 61
	s_cbranch_scc0 .LBB0_1332
	s_and_b64 vcc, exec, s[8:9]
	s_cbranch_vccz .LBB0_1335
	s_barrier

; #define PG8_STAGE(bufoff, gbase, voff) do { _Pragma("unroll") for (int _i = 0; _i < 2; ++_i) \
;         __builtin_amdgcn_global_load_lds((const unsigned*)((const char*)(gbase) + (voff)[_i]), (PG8_LAS unsigned*)(lds + (bufoff) + ldsw + _i * 8192), 16, 0, 0); } while (0)
; #define PG8_LDA(dst, b, h) do { _Pragma("unroll") for (int m = 0; m < 4; ++m) _Pragma("unroll") for (int k = 0; k < 2; ++k) dst[m][k] = *(const PG8_LAS bf16x8*)(lds + PG8_SA(b, h) + aoff + m * 2048 + k * 1024); } while (0)
; #define PG8_LDB(dst, b, h) do { _Pragma("unroll") for (int n = 0; n < 2; ++n) _Pragma("unroll") for (int k = 0; k < 2; ++k) dst[n][k] = *(const PG8_LAS bf16x8*)(lds + PG8_SB(b, h) + boff + n * 2048 + k * 1024); } while (0)
; #define PG8_MMA(ai, bj, At, Bt) do { __builtin_amdgcn_s_setprio(1); _Pragma("unroll") for (int m = 0; m < 4; ++m) _Pragma("unroll") for (int n = 0; n < 2; ++n) _Pragma("unroll") for (int k = 0; k < 2; ++k) \
;         acc[ai][bj][m][n] = __builtin_amdgcn_mfma_f32_16x16x32_bf16(Bt[n][k], At[m][k], acc[ai][bj][m][n], 0, 0, 0); __builtin_amdgcn_s_setprio(0); } while (0)
; #define PG8_WAIT_V(n) asm volatile("s_waitcnt vmcnt(" #n ")" ::: "memory")
; #define PG8_WAIT_L(n) asm volatile("s_waitcnt lgkmcnt(" #n ")" ::: "memory")
; template <class Epi, class Sched, bool ALIGN_EPI = false, bool SP2 = false>
; __device__ __forceinline__ void gemm_phase(PG8_LAS unsigned char* lds, const Gemm g, const Sched& S, const Epi& E) {
;     ...
;             const bool last = (t == nt - 2);
;             const char* a1 = cA + (size_t)(t + 1) * kstep;
;             const char* a2 = last ? nA : cA + (size_t)(t + 2) * kstep; const char* b2 = last ? nB : cB + (size_t)(t + 2) * kstep;
;             const char* a3 = a2 + kstep; const char* b3 = b2 + kstep;
;             if (last && has_next) S.a_ready(nxt);
;             if constexpr (SP2) {
;             PG8_LDB(B0, 0, 0); PG8_LDB(B1, 0, 1); PG8_SCHED; PG8_LDA(At, 0, 0); PG8_STAGE(PG8_SA(1, 1), a1 + hstep, voffA);
;             PG8_WAIT_V(8); PG8_WAIT_L(0); PG8_BAR; PG8_MMA(0, 0, At, B0); PG8_MMA(0, 1, At, B1); PG8_BAR; PG8_SCHED;
;             PG8_LDA(At, 0, 1); PG8_STAGE(PG8_SB(0, 0), b2, voffB); PG8_STAGE(PG8_SB(0, 1), b2 + hstep, voffB); PG8_STAGE(PG8_SA(0, 0), a2, voffA);
;             PG8_WAIT_V(8); PG8_WAIT_L(0); PG8_BAR; PG8_MMA(1, 0, At, B0); PG8_MMA(1, 1, At, B1); PG8_BAR; PG8_SCHED;
.LBB0_1595:
	ds_read_b128 v[130:133], v241 offset:0
	ds_read_b128 v[134:137], v241 offset:1024
	ds_read_b128 v[138:141], v241 offset:2048
	ds_read_b128 v[142:145], v241 offset:3072
	ds_read_b128 v[146:149], v241 offset:16384
	ds_read_b128 v[150:153], v241 offset:17408
	ds_read_b128 v[172:175], v241 offset:18432
	ds_read_b128 v[176:179], v241 offset:19456
	s_add_u32 s24, s26, 0xfff00080
	s_addc_u32 s25, s27, -1
	s_cmp_eq_u32 s62, 60
	s_cselect_b32 s29, s15, s25
	s_cselect_b32 s28, s21, s24
	s_cselect_b32 s25, s13, s53
	s_cselect_b32 s24, s51, s52
	s_add_i32 m0, s23, 0xc000
	ds_read_b128 v[180:183], v185
	ds_read_b128 v[188:191], v185 offset:1024
	ds_read_b128 v[192:195], v185 offset:2048
	ds_read_b128 v[196:199], v185 offset:3072
	ds_read_b128 v[200:203], v185 offset:4096
	ds_read_b128 v[204:207], v185 offset:5120
	ds_read_b128 v[208:211], v185 offset:6144
	ds_read_b128 v[212:215], v185 offset:7168
	global_load_lds_dwordx4 v162, s[26:27]
	s_add_i32 m0, s23, 0xe000
	s_nop 0
	global_load_lds_dwordx4 v166, s[26:27]
	s_waitcnt vmcnt(8)
	s_waitcnt lgkmcnt(0)
	s_barrier
	s_waitcnt lgkmcnt(0)
	v_mfma_f32_16x16x32_bf16 v[114:117], v[130:133], v[180:183], v[114:117]
	v_mfma_f32_16x16x32_bf16 v[118:121], v[138:141], v[180:183], v[118:121]
	v_mfma_f32_16x16x32_bf16 v[106:109], v[130:133], v[192:195], v[106:109]
	v_mfma_f32_16x16x32_bf16 v[98:101], v[138:141], v[192:195], v[98:101]
	v_mfma_f32_16x16x32_bf16 v[90:93], v[130:133], v[200:203], v[90:93]
	v_mfma_f32_16x16x32_bf16 v[82:85], v[138:141], v[200:203], v[82:85]
	v_mfma_f32_16x16x32_bf16 v[74:77], v[130:133], v[208:211], v[74:77]
	v_mfma_f32_16x16x32_bf16 v[66:69], v[138:141], v[208:211], v[66:69]
	v_mfma_f32_16x16x32_bf16 v[114:117], v[134:137], v[188:191], v[114:117]
	v_mfma_f32_16x16x32_bf16 v[118:121], v[142:145], v[188:191], v[118:121]
	v_mfma_f32_16x16x32_bf16 v[106:109], v[134:137], v[196:199], v[106:109]
	v_mfma_f32_16x16x32_bf16 v[98:101], v[142:145], v[196:199], v[98:101]
	v_mfma_f32_16x16x32_bf16 v[90:93], v[134:137], v[204:207], v[90:93]
	v_mfma_f32_16x16x32_bf16 v[82:85], v[142:145], v[204:207], v[82:85]
	v_mfma_f32_16x16x32_bf16 v[74:77], v[134:137], v[212:215], v[74:77]
	v_mfma_f32_16x16x32_bf16 v[66:69], v[142:145], v[212:215], v[66:69]
	v_mfma_f32_16x16x32_bf16 v[122:125], v[146:149], v[180:183], v[122:125]
	v_mfma_f32_16x16x32_bf16 v[126:129], v[172:175], v[180:183], v[126:129]
	v_mfma_f32_16x16x32_bf16 v[110:113], v[146:149], v[192:195], v[110:113]
	v_mfma_f32_16x16x32_bf16 v[102:105], v[172:175], v[192:195], v[102:105]
	v_mfma_f32_16x16x32_bf16 v[94:97], v[146:149], v[200:203], v[94:97]
	v_mfma_f32_16x16x32_bf16 v[86:89], v[172:175], v[200:203], v[86:89]
	v_mfma_f32_16x16x32_bf16 v[78:81], v[146:149], v[208:211], v[78:81]
	v_mfma_f32_16x16x32_bf16 v[70:73], v[172:175], v[208:211], v[70:73]
	v_mfma_f32_16x16x32_bf16 v[122:125], v[150:153], v[188:191], v[122:125]
	v_mfma_f32_16x16x32_bf16 v[126:129], v[176:179], v[188:191], v[126:129]
	v_mfma_f32_16x16x32_bf16 v[110:113], v[150:153], v[196:199], v[110:113]
	v_mfma_f32_16x16x32_bf16 v[102:105], v[176:179], v[196:199], v[102:105]
	v_mfma_f32_16x16x32_bf16 v[94:97], v[150:153], v[204:207], v[94:97]
	v_mfma_f32_16x16x32_bf16 v[86:89], v[176:179], v[204:207], v[86:89]
	v_mfma_f32_16x16x32_bf16 v[78:81], v[150:153], v[212:215], v[78:81]
	v_mfma_f32_16x16x32_bf16 v[70:73], v[176:179], v[212:215], v[70:73]
	s_barrier
	s_add_i32 s33, s48, s36
	s_mov_b32 m0, s33
	ds_read_b128 v[180:183], v185 offset:16384
	ds_read_b128 v[188:191], v185 offset:17408
	ds_read_b128 v[192:195], v185 offset:18432
	ds_read_b128 v[196:199], v185 offset:19456
	ds_read_b128 v[200:203], v185 offset:20480
	ds_read_b128 v[204:207], v185 offset:21504
	ds_read_b128 v[208:211], v185 offset:22528
	ds_read_b128 v[212:215], v185 offset:23552
	global_load_lds_dwordx4 v156, s[24:25]
	s_add_i32 m0, s33, 0x2000
	s_add_u32 s64, s24, 0x100000
	s_addc_u32 s65, s25, 0
	s_add_i32 s33, s49, s36
	global_load_lds_dwordx4 v160, s[24:25]
	s_mov_b32 m0, s33
	s_add_u32 s100, s28, 0x80
	s_addc_u32 s101, s29, 0
	global_load_lds_dwordx4 v156, s[64:65]
	s_add_i32 m0, s33, 0x2000
	s_nop 0
	global_load_lds_dwordx4 v160, s[64:65]
	s_mov_b32 m0, s23
	s_nop 0
	global_load_lds_dwordx4 v154, s[28:29]
	s_mov_b32 m0, s37
	s_nop 0
	global_load_lds_dwordx4 v158, s[28:29]
	s_waitcnt vmcnt(8)
	s_waitcnt lgkmcnt(0)
	s_barrier
	s_waitcnt lgkmcnt(0)
	v_mfma_f32_16x16x32_bf16 v[58:61], v[130:133], v[180:183], v[58:61]
	v_mfma_f32_16x16x32_bf16 v[54:57], v[138:141], v[180:183], v[54:57]
	v_mfma_f32_16x16x32_bf16 v[42:45], v[130:133], v[192:195], v[42:45]
	v_mfma_f32_16x16x32_bf16 v[34:37], v[138:141], v[192:195], v[34:37]
	v_mfma_f32_16x16x32_bf16 v[26:29], v[130:133], v[200:203], v[26:29]
	v_mfma_f32_16x16x32_bf16 v[18:21], v[138:141], v[200:203], v[18:21]
	v_mfma_f32_16x16x32_bf16 v[6:9], v[130:133], v[208:211], v[6:9]
	v_mfma_f32_16x16x32_bf16 v[2:5], v[138:141], v[208:211], v[2:5]
	v_mfma_f32_16x16x32_bf16 v[58:61], v[134:137], v[188:191], v[58:61]
	v_mfma_f32_16x16x32_bf16 v[54:57], v[142:145], v[188:191], v[54:57]
	v_mfma_f32_16x16x32_bf16 v[42:45], v[134:137], v[196:199], v[42:45]
	v_mfma_f32_16x16x32_bf16 v[34:37], v[142:145], v[196:199], v[34:37]
	v_mfma_f32_16x16x32_bf16 v[26:29], v[134:137], v[204:207], v[26:29]
	v_mfma_f32_16x16x32_bf16 v[18:21], v[142:145], v[204:207], v[18:21]
	v_mfma_f32_16x16x32_bf16 v[6:9], v[134:137], v[212:215], v[6:9]
	v_mfma_f32_16x16x32_bf16 v[2:5], v[142:145], v[212:215], v[2:5]
	v_mfma_f32_16x16x32_bf16 v[62:65], v[146:149], v[180:183], v[62:65]
	v_mfma_f32_16x16x32_bf16 v[50:53], v[172:175], v[180:183], v[50:53]
	v_mfma_f32_16x16x32_bf16 v[46:49], v[146:149], v[192:195], v[46:49]
	v_mfma_f32_16x16x32_bf16 v[38:41], v[172:175], v[192:195], v[38:41]
	v_mfma_f32_16x16x32_bf16 v[30:33], v[146:149], v[200:203], v[30:33]
	v_mfma_f32_16x16x32_bf16 v[22:25], v[172:175], v[200:203], v[22:25]
	v_mfma_f32_16x16x32_bf16 v[10:13], v[146:149], v[208:211], v[10:13]
	v_mfma_f32_16x16x32_bf16 v[14:17], v[172:175], v[208:211], v[14:17]
	v_mfma_f32_16x16x32_bf16 v[62:65], v[150:153], v[188:191], v[62:65]
	v_mfma_f32_16x16x32_bf16 v[50:53], v[176:179], v[188:191], v[50:53]
	v_mfma_f32_16x16x32_bf16 v[46:49], v[150:153], v[196:199], v[46:49]
	v_mfma_f32_16x16x32_bf16 v[38:41], v[176:179], v[196:199], v[38:41]
	v_mfma_f32_16x16x32_bf16 v[30:33], v[150:153], v[204:207], v[30:33]
	v_mfma_f32_16x16x32_bf16 v[22:25], v[176:179], v[204:207], v[22:25]
	v_mfma_f32_16x16x32_bf16 v[10:13], v[150:153], v[212:215], v[10:13]
	v_mfma_f32_16x16x32_bf16 v[14:17], v[176:179], v[212:215], v[14:17]
	s_barrier
; #define PG8_STAGE(bufoff, gbase, voff) do { _Pragma("unroll") for (int _i = 0; _i < 2; ++_i) \
;         __builtin_amdgcn_global_load_lds((const unsigned*)((const char*)(gbase) + (voff)[_i]), (PG8_LAS unsigned*)(lds + (bufoff) + ldsw + _i * 8192), 16, 0, 0); } while (0)
; #define PG8_LDA(dst, b, h) do { _Pragma("unroll") for (int m = 0; m < 4; ++m) _Pragma("unroll") for (int k = 0; k < 2; ++k) dst[m][k] = *(const PG8_LAS bf16x8*)(lds + PG8_SA(b, h) + aoff + m * 2048 + k * 1024); } while (0)
; #define PG8_LDB(dst, b, h) do { _Pragma("unroll") for (int n = 0; n < 2; ++n) _Pragma("unroll") for (int k = 0; k < 2; ++k) dst[n][k] = *(const PG8_LAS bf16x8*)(lds + PG8_SB(b, h) + boff + n * 2048 + k * 1024); } while (0)
; #define PG8_MMA(ai, bj, At, Bt) do { __builtin_amdgcn_s_setprio(1); _Pragma("unroll") for (int m = 0; m < 4; ++m) _Pragma("unroll") for (int n = 0; n < 2; ++n) _Pragma("unroll") for (int k = 0; k < 2; ++k) \
;         acc[ai][bj][m][n] = __builtin_amdgcn_mfma_f32_16x16x32_bf16(Bt[n][k], At[m][k], acc[ai][bj][m][n], 0, 0, 0); __builtin_amdgcn_s_setprio(0); } while (0)
; #define PG8_WAIT_V(n) asm volatile("s_waitcnt vmcnt(" #n ")" ::: "memory")
; #define PG8_WAIT_L(n) asm volatile("s_waitcnt lgkmcnt(" #n ")" ::: "memory")
; #define PG8_BAR __builtin_amdgcn_s_barrier()
; #define PG8_SCHED __builtin_amdgcn_sched_barrier(0)
; template <class Epi, class Sched, bool ALIGN_EPI = false, bool SP2 = false>
; __device__ __forceinline__ void gemm_phase(PG8_LAS unsigned char* lds, const Gemm g, const Sched& S, const Epi& E) {
;     ...
;             PG8_LDB(B0, 1, 0); PG8_LDB(B1, 1, 1); PG8_SCHED; PG8_LDA(At, 1, 0); PG8_STAGE(PG8_SA(0, 1), a2 + hstep, voffA);
;             PG8_WAIT_V(8); PG8_WAIT_L(0); PG8_BAR; PG8_MMA(0, 0, At, B0); PG8_MMA(0, 1, At, B1); PG8_BAR; PG8_SCHED;
;             PG8_LDA(At, 1, 1); PG8_STAGE(PG8_SB(1, 0), b3, voffB); PG8_STAGE(PG8_SB(1, 1), b3 + hstep, voffB); PG8_STAGE(PG8_SA(1, 0), a3, voffA);
;             PG8_WAIT_V(8); PG8_WAIT_L(0); PG8_BAR; PG8_MMA(1, 0, At, B0); PG8_MMA(1, 1, At, B1); PG8_BAR; PG8_SCHED;
	s_add_i32 s33, 0, 0x18000
	s_add_i32 s42, 0, 0x1c000
	ds_read_b128 v[130:133], v241 offset:32768
	ds_read_b128 v[134:137], v241 offset:33792
	ds_read_b128 v[138:141], v241 offset:34816
	ds_read_b128 v[142:145], v241 offset:35840
	ds_read_b128 v[146:149], v241 offset:49152
	ds_read_b128 v[150:153], v241 offset:50176
	ds_read_b128 v[172:175], v241 offset:51200
	ds_read_b128 v[176:179], v241 offset:52224
	s_add_u32 s28, s28, 0x100000
	s_addc_u32 s29, s29, 0
	s_mov_b32 m0, s40
	ds_read_b128 v[180:183], v185 offset:32768
	ds_read_b128 v[188:191], v185 offset:33792
	ds_read_b128 v[192:195], v185 offset:34816
	ds_read_b128 v[196:199], v185 offset:35840
	ds_read_b128 v[200:203], v185 offset:36864
	ds_read_b128 v[204:207], v185 offset:37888
	ds_read_b128 v[208:211], v185 offset:38912
	ds_read_b128 v[212:215], v185 offset:39936
	global_load_lds_dwordx4 v154, s[28:29]
	s_mov_b32 m0, s41
	s_nop 0
	global_load_lds_dwordx4 v158, s[28:29]
	s_waitcnt vmcnt(8)
	s_waitcnt lgkmcnt(0)
	s_barrier
	s_waitcnt lgkmcnt(0)
	v_mfma_f32_16x16x32_bf16 v[114:117], v[130:133], v[180:183], v[114:117]
	v_mfma_f32_16x16x32_bf16 v[118:121], v[138:141], v[180:183], v[118:121]
	v_mfma_f32_16x16x32_bf16 v[106:109], v[130:133], v[192:195], v[106:109]
	v_mfma_f32_16x16x32_bf16 v[98:101], v[138:141], v[192:195], v[98:101]
	v_mfma_f32_16x16x32_bf16 v[90:93], v[130:133], v[200:203], v[90:93]
	v_mfma_f32_16x16x32_bf16 v[82:85], v[138:141], v[200:203], v[82:85]
	v_mfma_f32_16x16x32_bf16 v[74:77], v[130:133], v[208:211], v[74:77]
	v_mfma_f32_16x16x32_bf16 v[66:69], v[138:141], v[208:211], v[66:69]
	v_mfma_f32_16x16x32_bf16 v[114:117], v[134:137], v[188:191], v[114:117]
	v_mfma_f32_16x16x32_bf16 v[118:121], v[142:145], v[188:191], v[118:121]
	v_mfma_f32_16x16x32_bf16 v[106:109], v[134:137], v[196:199], v[106:109]
	v_mfma_f32_16x16x32_bf16 v[98:101], v[142:145], v[196:199], v[98:101]
	v_mfma_f32_16x16x32_bf16 v[90:93], v[134:137], v[204:207], v[90:93]
	v_mfma_f32_16x16x32_bf16 v[82:85], v[142:145], v[204:207], v[82:85]
	v_mfma_f32_16x16x32_bf16 v[74:77], v[134:137], v[212:215], v[74:77]
	v_mfma_f32_16x16x32_bf16 v[66:69], v[142:145], v[212:215], v[66:69]
	v_mfma_f32_16x16x32_bf16 v[122:125], v[146:149], v[180:183], v[122:125]
	v_mfma_f32_16x16x32_bf16 v[126:129], v[172:175], v[180:183], v[126:129]
	v_mfma_f32_16x16x32_bf16 v[110:113], v[146:149], v[192:195], v[110:113]
	v_mfma_f32_16x16x32_bf16 v[102:105], v[172:175], v[192:195], v[102:105]
	v_mfma_f32_16x16x32_bf16 v[94:97], v[146:149], v[200:203], v[94:97]
	v_mfma_f32_16x16x32_bf16 v[86:89], v[172:175], v[200:203], v[86:89]
	v_mfma_f32_16x16x32_bf16 v[78:81], v[146:149], v[208:211], v[78:81]
	v_mfma_f32_16x16x32_bf16 v[70:73], v[172:175], v[208:211], v[70:73]
	v_mfma_f32_16x16x32_bf16 v[122:125], v[150:153], v[188:191], v[122:125]
	v_mfma_f32_16x16x32_bf16 v[126:129], v[176:179], v[188:191], v[126:129]
	v_mfma_f32_16x16x32_bf16 v[110:113], v[150:153], v[196:199], v[110:113]
	v_mfma_f32_16x16x32_bf16 v[102:105], v[176:179], v[196:199], v[102:105]
	v_mfma_f32_16x16x32_bf16 v[94:97], v[150:153], v[204:207], v[94:97]
	v_mfma_f32_16x16x32_bf16 v[86:89], v[176:179], v[204:207], v[86:89]
	v_mfma_f32_16x16x32_bf16 v[78:81], v[150:153], v[212:215], v[78:81]
	v_mfma_f32_16x16x32_bf16 v[70:73], v[176:179], v[212:215], v[70:73]
	s_barrier
	s_add_i32 s28, s33, s36
	s_add_i32 m0, s28, 0xffffff80
	ds_read_b128 v[180:183], v185 offset:49152
	ds_read_b128 v[188:191], v185 offset:50176
	ds_read_b128 v[192:195], v185 offset:51200
	ds_read_b128 v[196:199], v185 offset:52224
	ds_read_b128 v[200:203], v185 offset:53248
	ds_read_b128 v[204:207], v185 offset:54272
	ds_read_b128 v[208:211], v185 offset:55296
	ds_read_b128 v[212:215], v185 offset:56320
	global_load_lds_dwordx4 v156, s[24:25] offset:128
	s_add_i32 m0, s28, 0x1f80
	s_add_i32 s28, s42, s36
	global_load_lds_dwordx4 v160, s[24:25] offset:128
	s_add_u32 s24, s24, 0x100080
	s_addc_u32 s25, s25, 0
	s_mov_b32 m0, s28
	s_nop 0
	global_load_lds_dwordx4 v156, s[24:25]
	s_add_i32 m0, s28, 0x2000
	s_nop 0
	global_load_lds_dwordx4 v160, s[24:25]
	s_mov_b32 m0, s44
	s_nop 0
	global_load_lds_dwordx4 v154, s[100:101]
	s_mov_b32 m0, s45
	s_nop 0
	global_load_lds_dwordx4 v158, s[100:101]
	s_waitcnt vmcnt(8)
	s_waitcnt lgkmcnt(0)
	s_barrier
	s_waitcnt lgkmcnt(0)
	v_mfma_f32_16x16x32_bf16 v[58:61], v[130:133], v[180:183], v[58:61]
	v_mfma_f32_16x16x32_bf16 v[54:57], v[138:141], v[180:183], v[54:57]
	v_mfma_f32_16x16x32_bf16 v[42:45], v[130:133], v[192:195], v[42:45]
	v_mfma_f32_16x16x32_bf16 v[34:37], v[138:141], v[192:195], v[34:37]
	v_mfma_f32_16x16x32_bf16 v[26:29], v[130:133], v[200:203], v[26:29]
	v_mfma_f32_16x16x32_bf16 v[18:21], v[138:141], v[200:203], v[18:21]
	v_mfma_f32_16x16x32_bf16 v[6:9], v[130:133], v[208:211], v[6:9]
	v_mfma_f32_16x16x32_bf16 v[2:5], v[138:141], v[208:211], v[2:5]
	v_mfma_f32_16x16x32_bf16 v[58:61], v[134:137], v[188:191], v[58:61]
	v_mfma_f32_16x16x32_bf16 v[54:57], v[142:145], v[188:191], v[54:57]
	v_mfma_f32_16x16x32_bf16 v[42:45], v[134:137], v[196:199], v[42:45]
	v_mfma_f32_16x16x32_bf16 v[34:37], v[142:145], v[196:199], v[34:37]
	v_mfma_f32_16x16x32_bf16 v[26:29], v[134:137], v[204:207], v[26:29]
	v_mfma_f32_16x16x32_bf16 v[18:21], v[142:145], v[204:207], v[18:21]
	v_mfma_f32_16x16x32_bf16 v[6:9], v[134:137], v[212:215], v[6:9]
	v_mfma_f32_16x16x32_bf16 v[2:5], v[142:145], v[212:215], v[2:5]
	v_mfma_f32_16x16x32_bf16 v[62:65], v[146:149], v[180:183], v[62:65]
	v_mfma_f32_16x16x32_bf16 v[50:53], v[172:175], v[180:183], v[50:53]
	v_mfma_f32_16x16x32_bf16 v[46:49], v[146:149], v[192:195], v[46:49]
	v_mfma_f32_16x16x32_bf16 v[38:41], v[172:175], v[192:195], v[38:41]
	v_mfma_f32_16x16x32_bf16 v[30:33], v[146:149], v[200:203], v[30:33]
	v_mfma_f32_16x16x32_bf16 v[22:25], v[172:175], v[200:203], v[22:25]
	v_mfma_f32_16x16x32_bf16 v[10:13], v[146:149], v[208:211], v[10:13]
	v_mfma_f32_16x16x32_bf16 v[14:17], v[172:175], v[208:211], v[14:17]
	v_mfma_f32_16x16x32_bf16 v[62:65], v[150:153], v[188:191], v[62:65]
	v_mfma_f32_16x16x32_bf16 v[50:53], v[176:179], v[188:191], v[50:53]
	v_mfma_f32_16x16x32_bf16 v[46:49], v[150:153], v[196:199], v[46:49]
	v_mfma_f32_16x16x32_bf16 v[38:41], v[176:179], v[196:199], v[38:41]
	v_mfma_f32_16x16x32_bf16 v[30:33], v[150:153], v[204:207], v[30:33]
	v_mfma_f32_16x16x32_bf16 v[22:25], v[176:179], v[204:207], v[22:25]
	v_mfma_f32_16x16x32_bf16 v[10:13], v[150:153], v[212:215], v[10:13]
	v_mfma_f32_16x16x32_bf16 v[14:17], v[176:179], v[212:215], v[14:17]
	s_barrier
	s_add_i32 s62, s62, 2
	s_add_u32 s26, s26, 0x100
	s_addc_u32 s27, s27, 0
	s_add_u32 s52, s52, 0x100
	s_addc_u32 s53, s53, 0
	s_cmp_gt_u32 s62, 61
	s_cbranch_scc0 .LBB0_1595
	s_and_b64 vcc, exec, s[10:11]
	s_cbranch_vccz .LBB0_1598
	s_barrier

; #define PG8_STAGE(bufoff, gbase, voff) do { _Pragma("unroll") for (int _i = 0; _i < 2; ++_i) \
;         __builtin_amdgcn_global_load_lds((const unsigned*)((const char*)(gbase) + (voff)[_i]), (PG8_LAS unsigned*)(lds + (bufoff) + ldsw + _i * 8192), 16, 0, 0); } while (0)
; #define PG8_LDA(dst, b, h) do { _Pragma("unroll") for (int m = 0; m < 4; ++m) _Pragma("unroll") for (int k = 0; k < 2; ++k) dst[m][k] = *(const PG8_LAS bf16x8*)(lds + PG8_SA(b, h) + aoff + m * 2048 + k * 1024); } while (0)
; #define PG8_LDB(dst, b, h) do { _Pragma("unroll") for (int n = 0; n < 2; ++n) _Pragma("unroll") for (int k = 0; k < 2; ++k) dst[n][k] = *(const PG8_LAS bf16x8*)(lds + PG8_SB(b, h) + boff + n * 2048 + k * 1024); } while (0)
; #define PG8_MMA(ai, bj, At, Bt) do { __builtin_amdgcn_s_setprio(1); _Pragma("unroll") for (int m = 0; m < 4; ++m) _Pragma("unroll") for (int n = 0; n < 2; ++n) _Pragma("unroll") for (int k = 0; k < 2; ++k) \
;         acc[ai][bj][m][n] = __builtin_amdgcn_mfma_f32_16x16x32_bf16(Bt[n][k], At[m][k], acc[ai][bj][m][n], 0, 0, 0); __builtin_amdgcn_s_setprio(0); } while (0)
; #define PG8_WAIT_V(n) asm volatile("s_waitcnt vmcnt(" #n ")" ::: "memory")
; #define PG8_WAIT_L(n) asm volatile("s_waitcnt lgkmcnt(" #n ")" ::: "memory")
; template <class Epi, class Sched, bool ALIGN_EPI = false, bool SP2 = false>
; __device__ __forceinline__ void gemm_phase(PG8_LAS unsigned char* lds, const Gemm g, const Sched& S, const Epi& E) {
;     ...
;             const bool last = (t == nt - 2);
;             const char* a1 = cA + (size_t)(t + 1) * kstep;
;             const char* a2 = last ? nA : cA + (size_t)(t + 2) * kstep; const char* b2 = last ? nB : cB + (size_t)(t + 2) * kstep;
;             const char* a3 = a2 + kstep; const char* b3 = b2 + kstep;
;             if (last && has_next) S.a_ready(nxt);
;             if constexpr (SP2) {
;             PG8_LDB(B0, 0, 0); PG8_LDB(B1, 0, 1); PG8_SCHED; PG8_LDA(At, 0, 0); PG8_STAGE(PG8_SA(1, 1), a1 + hstep, voffA);
;             PG8_WAIT_V(8); PG8_WAIT_L(0); PG8_BAR; PG8_MMA(0, 0, At, B0); PG8_MMA(0, 1, At, B1); PG8_BAR; PG8_SCHED;
;             PG8_LDA(At, 0, 1); PG8_STAGE(PG8_SB(0, 0), b2, voffB); PG8_STAGE(PG8_SB(0, 1), b2 + hstep, voffB); PG8_STAGE(PG8_SA(0, 0), a2, voffA);
;             PG8_WAIT_V(8); PG8_WAIT_L(0); PG8_BAR; PG8_MMA(1, 0, At, B0); PG8_MMA(1, 1, At, B1); PG8_BAR; PG8_SCHED;
.LBB0_1681:
	ds_read_b128 v[160:163], v241 offset:0
	ds_read_b128 v[166:169], v241 offset:1024
	ds_read_b128 v[170:173], v241 offset:2048
	ds_read_b128 v[174:177], v241 offset:3072
	ds_read_b128 v[178:181], v241 offset:16384
	ds_read_b128 v[182:185], v241 offset:17408
	ds_read_b128 v[186:189], v241 offset:18432
	ds_read_b128 v[190:193], v241 offset:19456
	s_add_u32 s22, s24, 0xfff00080
	s_addc_u32 s23, s25, -1
	s_cmp_eq_u32 s52, 60
	s_cselect_b32 s27, s15, s23
	s_cselect_b32 s26, s48, s22
	s_cselect_b32 s23, s13, s51
	s_cselect_b32 s22, s49, s50
	s_add_i32 m0, s21, 0xc000
	ds_read_b128 v[194:197], v155
	ds_read_b128 v[198:201], v155 offset:1024
	ds_read_b128 v[202:205], v155 offset:2048
	ds_read_b128 v[206:209], v155 offset:3072
	ds_read_b128 v[210:213], v155 offset:4096
	ds_read_b128 v[214:217], v155 offset:5120
	ds_read_b128 v[218:221], v155 offset:6144
	ds_read_b128 v[222:225], v155 offset:7168
	global_load_lds_dwordx4 v138, s[24:25]
	s_add_i32 m0, s21, 0xe000
	s_nop 0
	global_load_lds_dwordx4 v140, s[24:25]
	s_waitcnt vmcnt(8)
	s_waitcnt lgkmcnt(0)
	s_barrier
	s_waitcnt lgkmcnt(0)
	v_mfma_f32_16x16x32_bf16 v[122:125], v[160:163], v[194:197], v[122:125]
	v_mfma_f32_16x16x32_bf16 v[114:117], v[170:173], v[194:197], v[114:117]
	v_mfma_f32_16x16x32_bf16 v[106:109], v[160:163], v[202:205], v[106:109]
	v_mfma_f32_16x16x32_bf16 v[98:101], v[170:173], v[202:205], v[98:101]
	v_mfma_f32_16x16x32_bf16 v[90:93], v[160:163], v[210:213], v[90:93]
	v_mfma_f32_16x16x32_bf16 v[82:85], v[170:173], v[210:213], v[82:85]
	v_mfma_f32_16x16x32_bf16 v[74:77], v[160:163], v[218:221], v[74:77]
	v_mfma_f32_16x16x32_bf16 v[62:65], v[170:173], v[218:221], v[62:65]
	v_mfma_f32_16x16x32_bf16 v[122:125], v[166:169], v[198:201], v[122:125]
	v_mfma_f32_16x16x32_bf16 v[114:117], v[174:177], v[198:201], v[114:117]
	v_mfma_f32_16x16x32_bf16 v[106:109], v[166:169], v[206:209], v[106:109]
	v_mfma_f32_16x16x32_bf16 v[98:101], v[174:177], v[206:209], v[98:101]
	v_mfma_f32_16x16x32_bf16 v[90:93], v[166:169], v[214:217], v[90:93]
	v_mfma_f32_16x16x32_bf16 v[82:85], v[174:177], v[214:217], v[82:85]
	v_mfma_f32_16x16x32_bf16 v[74:77], v[166:169], v[222:225], v[74:77]
	v_mfma_f32_16x16x32_bf16 v[62:65], v[174:177], v[222:225], v[62:65]
	v_mfma_f32_16x16x32_bf16 v[126:129], v[178:181], v[194:197], v[126:129]
	v_mfma_f32_16x16x32_bf16 v[118:121], v[186:189], v[194:197], v[118:121]
	v_mfma_f32_16x16x32_bf16 v[110:113], v[178:181], v[202:205], v[110:113]
	v_mfma_f32_16x16x32_bf16 v[102:105], v[186:189], v[202:205], v[102:105]
	v_mfma_f32_16x16x32_bf16 v[94:97], v[178:181], v[210:213], v[94:97]
	v_mfma_f32_16x16x32_bf16 v[86:89], v[186:189], v[210:213], v[86:89]
	v_mfma_f32_16x16x32_bf16 v[78:81], v[178:181], v[218:221], v[78:81]
	v_mfma_f32_16x16x32_bf16 v[70:73], v[186:189], v[218:221], v[70:73]
	v_mfma_f32_16x16x32_bf16 v[126:129], v[182:185], v[198:201], v[126:129]
	v_mfma_f32_16x16x32_bf16 v[118:121], v[190:193], v[198:201], v[118:121]
	v_mfma_f32_16x16x32_bf16 v[110:113], v[182:185], v[206:209], v[110:113]
	v_mfma_f32_16x16x32_bf16 v[102:105], v[190:193], v[206:209], v[102:105]
	v_mfma_f32_16x16x32_bf16 v[94:97], v[182:185], v[214:217], v[94:97]
	v_mfma_f32_16x16x32_bf16 v[86:89], v[190:193], v[214:217], v[86:89]
	v_mfma_f32_16x16x32_bf16 v[78:81], v[182:185], v[222:225], v[78:81]
	v_mfma_f32_16x16x32_bf16 v[70:73], v[190:193], v[222:225], v[70:73]
	s_barrier
	s_add_i32 s33, s44, s29
	s_mov_b32 m0, s33
	ds_read_b128 v[194:197], v155 offset:16384
	ds_read_b128 v[198:201], v155 offset:17408
	ds_read_b128 v[202:205], v155 offset:18432
	ds_read_b128 v[206:209], v155 offset:19456
	ds_read_b128 v[210:213], v155 offset:20480
	ds_read_b128 v[214:217], v155 offset:21504
	ds_read_b128 v[218:221], v155 offset:22528
	ds_read_b128 v[222:225], v155 offset:23552
	global_load_lds_dwordx4 v132, s[22:23]
	s_add_i32 m0, s33, 0x2000
	s_add_u32 s62, s22, 0x100000
	s_addc_u32 s63, s23, 0
	s_add_i32 s33, s45, s29
	global_load_lds_dwordx4 v136, s[22:23]
	s_mov_b32 m0, s33
	s_add_u32 s100, s26, 0x80
	s_addc_u32 s101, s27, 0
	global_load_lds_dwordx4 v132, s[62:63]
	s_add_i32 m0, s33, 0x2000
	s_nop 0
	global_load_lds_dwordx4 v136, s[62:63]
	s_mov_b32 m0, s21
	s_nop 0
	global_load_lds_dwordx4 v130, s[26:27]
	s_mov_b32 m0, s34
	s_nop 0
	global_load_lds_dwordx4 v134, s[26:27]
	s_waitcnt vmcnt(8)
	s_waitcnt lgkmcnt(0)
	s_barrier
	s_waitcnt lgkmcnt(0)
	v_mfma_f32_16x16x32_bf16 v[58:61], v[160:163], v[194:197], v[58:61]
	v_mfma_f32_16x16x32_bf16 v[50:53], v[170:173], v[194:197], v[50:53]
	v_mfma_f32_16x16x32_bf16 v[42:45], v[160:163], v[202:205], v[42:45]
	v_mfma_f32_16x16x32_bf16 v[34:37], v[170:173], v[202:205], v[34:37]
	v_mfma_f32_16x16x32_bf16 v[26:29], v[160:163], v[210:213], v[26:29]
	v_mfma_f32_16x16x32_bf16 v[18:21], v[170:173], v[210:213], v[18:21]
	v_mfma_f32_16x16x32_bf16 v[10:13], v[160:163], v[218:221], v[10:13]
	v_mfma_f32_16x16x32_bf16 v[2:5], v[170:173], v[218:221], v[2:5]
	v_mfma_f32_16x16x32_bf16 v[58:61], v[166:169], v[198:201], v[58:61]
	v_mfma_f32_16x16x32_bf16 v[50:53], v[174:177], v[198:201], v[50:53]
	v_mfma_f32_16x16x32_bf16 v[42:45], v[166:169], v[206:209], v[42:45]
	v_mfma_f32_16x16x32_bf16 v[34:37], v[174:177], v[206:209], v[34:37]
	v_mfma_f32_16x16x32_bf16 v[26:29], v[166:169], v[214:217], v[26:29]
	v_mfma_f32_16x16x32_bf16 v[18:21], v[174:177], v[214:217], v[18:21]
	v_mfma_f32_16x16x32_bf16 v[10:13], v[166:169], v[222:225], v[10:13]
	v_mfma_f32_16x16x32_bf16 v[2:5], v[174:177], v[222:225], v[2:5]
	v_mfma_f32_16x16x32_bf16 v[66:69], v[178:181], v[194:197], v[66:69]
	v_mfma_f32_16x16x32_bf16 v[54:57], v[186:189], v[194:197], v[54:57]
	v_mfma_f32_16x16x32_bf16 v[46:49], v[178:181], v[202:205], v[46:49]
	v_mfma_f32_16x16x32_bf16 v[38:41], v[186:189], v[202:205], v[38:41]
	v_mfma_f32_16x16x32_bf16 v[30:33], v[178:181], v[210:213], v[30:33]
	v_mfma_f32_16x16x32_bf16 v[22:25], v[186:189], v[210:213], v[22:25]
	v_mfma_f32_16x16x32_bf16 v[14:17], v[178:181], v[218:221], v[14:17]
	v_mfma_f32_16x16x32_bf16 v[6:9], v[186:189], v[218:221], v[6:9]
	v_mfma_f32_16x16x32_bf16 v[66:69], v[182:185], v[198:201], v[66:69]
	v_mfma_f32_16x16x32_bf16 v[54:57], v[190:193], v[198:201], v[54:57]
	v_mfma_f32_16x16x32_bf16 v[46:49], v[182:185], v[206:209], v[46:49]
	v_mfma_f32_16x16x32_bf16 v[38:41], v[190:193], v[206:209], v[38:41]
	v_mfma_f32_16x16x32_bf16 v[30:33], v[182:185], v[214:217], v[30:33]
	v_mfma_f32_16x16x32_bf16 v[22:25], v[190:193], v[214:217], v[22:25]
	v_mfma_f32_16x16x32_bf16 v[14:17], v[182:185], v[222:225], v[14:17]
	v_mfma_f32_16x16x32_bf16 v[6:9], v[190:193], v[222:225], v[6:9]
	s_barrier
; #define PG8_STAGE(bufoff, gbase, voff) do { _Pragma("unroll") for (int _i = 0; _i < 2; ++_i) \
;         __builtin_amdgcn_global_load_lds((const unsigned*)((const char*)(gbase) + (voff)[_i]), (PG8_LAS unsigned*)(lds + (bufoff) + ldsw + _i * 8192), 16, 0, 0); } while (0)
; #define PG8_LDA(dst, b, h) do { _Pragma("unroll") for (int m = 0; m < 4; ++m) _Pragma("unroll") for (int k = 0; k < 2; ++k) dst[m][k] = *(const PG8_LAS bf16x8*)(lds + PG8_SA(b, h) + aoff + m * 2048 + k * 1024); } while (0)
; #define PG8_LDB(dst, b, h) do { _Pragma("unroll") for (int n = 0; n < 2; ++n) _Pragma("unroll") for (int k = 0; k < 2; ++k) dst[n][k] = *(const PG8_LAS bf16x8*)(lds + PG8_SB(b, h) + boff + n * 2048 + k * 1024); } while (0)
; #define PG8_MMA(ai, bj, At, Bt) do { __builtin_amdgcn_s_setprio(1); _Pragma("unroll") for (int m = 0; m < 4; ++m) _Pragma("unroll") for (int n = 0; n < 2; ++n) _Pragma("unroll") for (int k = 0; k < 2; ++k) \
;         acc[ai][bj][m][n] = __builtin_amdgcn_mfma_f32_16x16x32_bf16(Bt[n][k], At[m][k], acc[ai][bj][m][n], 0, 0, 0); __builtin_amdgcn_s_setprio(0); } while (0)
; #define PG8_WAIT_V(n) asm volatile("s_waitcnt vmcnt(" #n ")" ::: "memory")
; #define PG8_WAIT_L(n) asm volatile("s_waitcnt lgkmcnt(" #n ")" ::: "memory")
; #define PG8_BAR __builtin_amdgcn_s_barrier()
; #define PG8_SCHED __builtin_amdgcn_sched_barrier(0)
; template <class Epi, class Sched, bool ALIGN_EPI = false, bool SP2 = false>
; __device__ __forceinline__ void gemm_phase(PG8_LAS unsigned char* lds, const Gemm g, const Sched& S, const Epi& E) {
;     ...
;             PG8_LDB(B0, 1, 0); PG8_LDB(B1, 1, 1); PG8_SCHED; PG8_LDA(At, 1, 0); PG8_STAGE(PG8_SA(0, 1), a2 + hstep, voffA);
;             PG8_WAIT_V(8); PG8_WAIT_L(0); PG8_BAR; PG8_MMA(0, 0, At, B0); PG8_MMA(0, 1, At, B1); PG8_BAR; PG8_SCHED;
;             PG8_LDA(At, 1, 1); PG8_STAGE(PG8_SB(1, 0), b3, voffB); PG8_STAGE(PG8_SB(1, 1), b3 + hstep, voffB); PG8_STAGE(PG8_SA(1, 0), a3, voffA);
;             PG8_WAIT_V(8); PG8_WAIT_L(0); PG8_BAR; PG8_MMA(1, 0, At, B0); PG8_MMA(1, 1, At, B1); PG8_BAR; PG8_SCHED;
	s_add_i32 s33, 0, 0x18000
	s_add_i32 s42, 0, 0x1c000
	ds_read_b128 v[160:163], v241 offset:32768
	ds_read_b128 v[166:169], v241 offset:33792
	ds_read_b128 v[170:173], v241 offset:34816
	ds_read_b128 v[174:177], v241 offset:35840
	ds_read_b128 v[178:181], v241 offset:49152
	ds_read_b128 v[182:185], v241 offset:50176
	ds_read_b128 v[186:189], v241 offset:51200
	ds_read_b128 v[190:193], v241 offset:52224
	s_add_u32 s26, s26, 0x100000
	s_addc_u32 s27, s27, 0
	s_mov_b32 m0, s35
	ds_read_b128 v[194:197], v155 offset:32768
	ds_read_b128 v[198:201], v155 offset:33792
	ds_read_b128 v[202:205], v155 offset:34816
	ds_read_b128 v[206:209], v155 offset:35840
	ds_read_b128 v[210:213], v155 offset:36864
	ds_read_b128 v[214:217], v155 offset:37888
	ds_read_b128 v[218:221], v155 offset:38912
	ds_read_b128 v[222:225], v155 offset:39936
	global_load_lds_dwordx4 v130, s[26:27]
	s_mov_b32 m0, s36
	s_nop 0
	global_load_lds_dwordx4 v134, s[26:27]
	s_waitcnt vmcnt(8)
	s_waitcnt lgkmcnt(0)
	s_barrier
	s_waitcnt lgkmcnt(0)
	v_mfma_f32_16x16x32_bf16 v[122:125], v[160:163], v[194:197], v[122:125]
	v_mfma_f32_16x16x32_bf16 v[114:117], v[170:173], v[194:197], v[114:117]
	v_mfma_f32_16x16x32_bf16 v[106:109], v[160:163], v[202:205], v[106:109]
	v_mfma_f32_16x16x32_bf16 v[98:101], v[170:173], v[202:205], v[98:101]
	v_mfma_f32_16x16x32_bf16 v[90:93], v[160:163], v[210:213], v[90:93]
	v_mfma_f32_16x16x32_bf16 v[82:85], v[170:173], v[210:213], v[82:85]
	v_mfma_f32_16x16x32_bf16 v[74:77], v[160:163], v[218:221], v[74:77]
	v_mfma_f32_16x16x32_bf16 v[62:65], v[170:173], v[218:221], v[62:65]
	v_mfma_f32_16x16x32_bf16 v[122:125], v[166:169], v[198:201], v[122:125]
	v_mfma_f32_16x16x32_bf16 v[114:117], v[174:177], v[198:201], v[114:117]
	v_mfma_f32_16x16x32_bf16 v[106:109], v[166:169], v[206:209], v[106:109]
	v_mfma_f32_16x16x32_bf16 v[98:101], v[174:177], v[206:209], v[98:101]
	v_mfma_f32_16x16x32_bf16 v[90:93], v[166:169], v[214:217], v[90:93]
	v_mfma_f32_16x16x32_bf16 v[82:85], v[174:177], v[214:217], v[82:85]
	v_mfma_f32_16x16x32_bf16 v[74:77], v[166:169], v[222:225], v[74:77]
	v_mfma_f32_16x16x32_bf16 v[62:65], v[174:177], v[222:225], v[62:65]
	v_mfma_f32_16x16x32_bf16 v[126:129], v[178:181], v[194:197], v[126:129]
	v_mfma_f32_16x16x32_bf16 v[118:121], v[186:189], v[194:197], v[118:121]
	v_mfma_f32_16x16x32_bf16 v[110:113], v[178:181], v[202:205], v[110:113]
	v_mfma_f32_16x16x32_bf16 v[102:105], v[186:189], v[202:205], v[102:105]
	v_mfma_f32_16x16x32_bf16 v[94:97], v[178:181], v[210:213], v[94:97]
	v_mfma_f32_16x16x32_bf16 v[86:89], v[186:189], v[210:213], v[86:89]
	v_mfma_f32_16x16x32_bf16 v[78:81], v[178:181], v[218:221], v[78:81]
	v_mfma_f32_16x16x32_bf16 v[70:73], v[186:189], v[218:221], v[70:73]
	v_mfma_f32_16x16x32_bf16 v[126:129], v[182:185], v[198:201], v[126:129]
	v_mfma_f32_16x16x32_bf16 v[118:121], v[190:193], v[198:201], v[118:121]
	v_mfma_f32_16x16x32_bf16 v[110:113], v[182:185], v[206:209], v[110:113]
	v_mfma_f32_16x16x32_bf16 v[102:105], v[190:193], v[206:209], v[102:105]
	v_mfma_f32_16x16x32_bf16 v[94:97], v[182:185], v[214:217], v[94:97]
	v_mfma_f32_16x16x32_bf16 v[86:89], v[190:193], v[214:217], v[86:89]
	v_mfma_f32_16x16x32_bf16 v[78:81], v[182:185], v[222:225], v[78:81]
	v_mfma_f32_16x16x32_bf16 v[70:73], v[190:193], v[222:225], v[70:73]
	s_barrier
	s_add_i32 s26, s33, s29
	s_add_i32 m0, s26, 0xffffff80
	ds_read_b128 v[194:197], v155 offset:49152
	ds_read_b128 v[198:201], v155 offset:50176
	ds_read_b128 v[202:205], v155 offset:51200
	ds_read_b128 v[206:209], v155 offset:52224
	ds_read_b128 v[210:213], v155 offset:53248
	ds_read_b128 v[214:217], v155 offset:54272
	ds_read_b128 v[218:221], v155 offset:55296
	ds_read_b128 v[222:225], v155 offset:56320
	global_load_lds_dwordx4 v132, s[22:23] offset:128
	s_add_i32 m0, s26, 0x1f80
	s_add_i32 s26, s42, s29
	global_load_lds_dwordx4 v136, s[22:23] offset:128
	s_add_u32 s22, s22, 0x100080
	s_addc_u32 s23, s23, 0
	s_mov_b32 m0, s26
	s_nop 0
	global_load_lds_dwordx4 v132, s[22:23]
	s_add_i32 m0, s26, 0x2000
	s_nop 0
	global_load_lds_dwordx4 v136, s[22:23]
	s_mov_b32 m0, s41
	s_nop 0
	global_load_lds_dwordx4 v130, s[100:101]
	s_mov_b32 m0, s43
	s_nop 0
	global_load_lds_dwordx4 v134, s[100:101]
	s_waitcnt vmcnt(8)
	s_waitcnt lgkmcnt(0)
	s_barrier
	s_waitcnt lgkmcnt(0)
	v_mfma_f32_16x16x32_bf16 v[58:61], v[160:163], v[194:197], v[58:61]
	v_mfma_f32_16x16x32_bf16 v[50:53], v[170:173], v[194:197], v[50:53]
	v_mfma_f32_16x16x32_bf16 v[42:45], v[160:163], v[202:205], v[42:45]
	v_mfma_f32_16x16x32_bf16 v[34:37], v[170:173], v[202:205], v[34:37]
	v_mfma_f32_16x16x32_bf16 v[26:29], v[160:163], v[210:213], v[26:29]
	v_mfma_f32_16x16x32_bf16 v[18:21], v[170:173], v[210:213], v[18:21]
	v_mfma_f32_16x16x32_bf16 v[10:13], v[160:163], v[218:221], v[10:13]
	v_mfma_f32_16x16x32_bf16 v[2:5], v[170:173], v[218:221], v[2:5]
	v_mfma_f32_16x16x32_bf16 v[58:61], v[166:169], v[198:201], v[58:61]
	v_mfma_f32_16x16x32_bf16 v[50:53], v[174:177], v[198:201], v[50:53]
	v_mfma_f32_16x16x32_bf16 v[42:45], v[166:169], v[206:209], v[42:45]
	v_mfma_f32_16x16x32_bf16 v[34:37], v[174:177], v[206:209], v[34:37]
	v_mfma_f32_16x16x32_bf16 v[26:29], v[166:169], v[214:217], v[26:29]
	v_mfma_f32_16x16x32_bf16 v[18:21], v[174:177], v[214:217], v[18:21]
	v_mfma_f32_16x16x32_bf16 v[10:13], v[166:169], v[222:225], v[10:13]
	v_mfma_f32_16x16x32_bf16 v[2:5], v[174:177], v[222:225], v[2:5]
	v_mfma_f32_16x16x32_bf16 v[66:69], v[178:181], v[194:197], v[66:69]
	v_mfma_f32_16x16x32_bf16 v[54:57], v[186:189], v[194:197], v[54:57]
	v_mfma_f32_16x16x32_bf16 v[46:49], v[178:181], v[202:205], v[46:49]
	v_mfma_f32_16x16x32_bf16 v[38:41], v[186:189], v[202:205], v[38:41]
	v_mfma_f32_16x16x32_bf16 v[30:33], v[178:181], v[210:213], v[30:33]
	v_mfma_f32_16x16x32_bf16 v[22:25], v[186:189], v[210:213], v[22:25]
	v_mfma_f32_16x16x32_bf16 v[14:17], v[178:181], v[218:221], v[14:17]
	v_mfma_f32_16x16x32_bf16 v[6:9], v[186:189], v[218:221], v[6:9]
	v_mfma_f32_16x16x32_bf16 v[66:69], v[182:185], v[198:201], v[66:69]
	v_mfma_f32_16x16x32_bf16 v[54:57], v[190:193], v[198:201], v[54:57]
	v_mfma_f32_16x16x32_bf16 v[46:49], v[182:185], v[206:209], v[46:49]
	v_mfma_f32_16x16x32_bf16 v[38:41], v[190:193], v[206:209], v[38:41]
	v_mfma_f32_16x16x32_bf16 v[30:33], v[182:185], v[214:217], v[30:33]
	v_mfma_f32_16x16x32_bf16 v[22:25], v[190:193], v[214:217], v[22:25]
	v_mfma_f32_16x16x32_bf16 v[14:17], v[182:185], v[222:225], v[14:17]
	v_mfma_f32_16x16x32_bf16 v[6:9], v[190:193], v[222:225], v[6:9]
	s_barrier
	s_add_i32 s52, s52, 2
	s_add_u32 s24, s24, 0x100
	s_addc_u32 s25, s25, 0
	s_add_u32 s50, s50, 0x100
	s_addc_u32 s51, s51, 0
	s_cmp_gt_u32 s52, 61
	s_cbranch_scc0 .LBB0_1681
	s_and_b64 vcc, exec, s[8:9]
	s_cbranch_vccz .LBB0_1684
	s_barrier

; #define PG8_STAGE(bufoff, gbase, voff) do { _Pragma("unroll") for (int _i = 0; _i < 2; ++_i) \
;         __builtin_amdgcn_global_load_lds((const unsigned*)((const char*)(gbase) + (voff)[_i]), (PG8_LAS unsigned*)(lds + (bufoff) + ldsw + _i * 8192), 16, 0, 0); } while (0)
; #define PG8_LDA(dst, b, h) do { _Pragma("unroll") for (int m = 0; m < 4; ++m) _Pragma("unroll") for (int k = 0; k < 2; ++k) dst[m][k] = *(const PG8_LAS bf16x8*)(lds + PG8_SA(b, h) + aoff + m * 2048 + k * 1024); } while (0)
; #define PG8_LDB(dst, b, h) do { _Pragma("unroll") for (int n = 0; n < 2; ++n) _Pragma("unroll") for (int k = 0; k < 2; ++k) dst[n][k] = *(const PG8_LAS bf16x8*)(lds + PG8_SB(b, h) + boff + n * 2048 + k * 1024); } while (0)
; #define PG8_MMA(ai, bj, At, Bt) do { __builtin_amdgcn_s_setprio(1); _Pragma("unroll") for (int m = 0; m < 4; ++m) _Pragma("unroll") for (int n = 0; n < 2; ++n) _Pragma("unroll") for (int k = 0; k < 2; ++k) \
;         acc[ai][bj][m][n] = __builtin_amdgcn_mfma_f32_16x16x32_bf16(Bt[n][k], At[m][k], acc[ai][bj][m][n], 0, 0, 0); __builtin_amdgcn_s_setprio(0); } while (0)
; #define PG8_WAIT_V(n) asm volatile("s_waitcnt vmcnt(" #n ")" ::: "memory")
; #define PG8_WAIT_L(n) asm volatile("s_waitcnt lgkmcnt(" #n ")" ::: "memory")
; template <class Epi, class Sched, bool ALIGN_EPI = false, bool SP2 = false>
; __device__ __forceinline__ void gemm_phase(PG8_LAS unsigned char* lds, const Gemm g, const Sched& S, const Epi& E) {
;     ...
;             const bool last = (t == nt - 2);
;             const char* a1 = cA + (size_t)(t + 1) * kstep;
;             const char* a2 = last ? nA : cA + (size_t)(t + 2) * kstep; const char* b2 = last ? nB : cB + (size_t)(t + 2) * kstep;
;             const char* a3 = a2 + kstep; const char* b3 = b2 + kstep;
;             if (last && has_next) S.a_ready(nxt);
;             if constexpr (SP2) {
;             PG8_LDB(B0, 0, 0); PG8_LDB(B1, 0, 1); PG8_SCHED; PG8_LDA(At, 0, 0); PG8_STAGE(PG8_SA(1, 1), a1 + hstep, voffA);
;             PG8_WAIT_V(8); PG8_WAIT_L(0); PG8_BAR; PG8_MMA(0, 0, At, B0); PG8_MMA(0, 1, At, B1); PG8_BAR; PG8_SCHED;
;             PG8_LDA(At, 0, 1); PG8_STAGE(PG8_SB(0, 0), b2, voffB); PG8_STAGE(PG8_SB(0, 1), b2 + hstep, voffB); PG8_STAGE(PG8_SA(0, 0), a2, voffA);
;             PG8_WAIT_V(8); PG8_WAIT_L(0); PG8_BAR; PG8_MMA(1, 0, At, B0); PG8_MMA(1, 1, At, B1); PG8_BAR; PG8_SCHED;
.LBB0_1801:
	ds_read_b128 v[130:133], v241 offset:0
	ds_read_b128 v[134:137], v241 offset:1024
	ds_read_b128 v[138:141], v241 offset:2048
	ds_read_b128 v[142:145], v241 offset:3072
	ds_read_b128 v[146:149], v241 offset:16384
	ds_read_b128 v[150:153], v241 offset:17408
	ds_read_b128 v[170:173], v241 offset:18432
	ds_read_b128 v[174:177], v241 offset:19456
	s_add_u32 s16, s18, 0xffd50080
	s_addc_u32 s17, s19, -1
	s_cmpk_eq_i32 s48, 0xa8
	s_cselect_b32 s21, s5, s17
	s_cselect_b32 s20, s4, s16
	s_cselect_b32 s17, s15, s47
	s_cselect_b32 s16, s14, s46
	s_add_i32 m0, s25, 0xc000
	ds_read_b128 v[178:181], v184
	ds_read_b128 v[186:189], v184 offset:1024
	ds_read_b128 v[190:193], v184 offset:2048
	ds_read_b128 v[194:197], v184 offset:3072
	ds_read_b128 v[198:201], v184 offset:4096
	ds_read_b128 v[202:205], v184 offset:5120
	ds_read_b128 v[206:209], v184 offset:6144
	ds_read_b128 v[210:213], v184 offset:7168
	global_load_lds_dwordx4 v0, s[18:19]
	s_add_i32 m0, s25, 0xe000
	s_nop 0
	global_load_lds_dwordx4 v162, s[18:19]
	s_waitcnt vmcnt(8)
	s_waitcnt lgkmcnt(0)
	s_barrier
	s_waitcnt lgkmcnt(0)
	v_mfma_f32_16x16x32_bf16 v[114:117], v[130:133], v[178:181], v[114:117]
	v_mfma_f32_16x16x32_bf16 v[118:121], v[138:141], v[178:181], v[118:121]
	v_mfma_f32_16x16x32_bf16 v[106:109], v[130:133], v[190:193], v[106:109]
	v_mfma_f32_16x16x32_bf16 v[98:101], v[138:141], v[190:193], v[98:101]
	v_mfma_f32_16x16x32_bf16 v[90:93], v[130:133], v[198:201], v[90:93]
	v_mfma_f32_16x16x32_bf16 v[82:85], v[138:141], v[198:201], v[82:85]
	v_mfma_f32_16x16x32_bf16 v[74:77], v[130:133], v[206:209], v[74:77]
	v_mfma_f32_16x16x32_bf16 v[66:69], v[138:141], v[206:209], v[66:69]
	v_mfma_f32_16x16x32_bf16 v[114:117], v[134:137], v[186:189], v[114:117]
	v_mfma_f32_16x16x32_bf16 v[118:121], v[142:145], v[186:189], v[118:121]
	v_mfma_f32_16x16x32_bf16 v[106:109], v[134:137], v[194:197], v[106:109]
	v_mfma_f32_16x16x32_bf16 v[98:101], v[142:145], v[194:197], v[98:101]
	v_mfma_f32_16x16x32_bf16 v[90:93], v[134:137], v[202:205], v[90:93]
	v_mfma_f32_16x16x32_bf16 v[82:85], v[142:145], v[202:205], v[82:85]
	v_mfma_f32_16x16x32_bf16 v[74:77], v[134:137], v[210:213], v[74:77]
	v_mfma_f32_16x16x32_bf16 v[66:69], v[142:145], v[210:213], v[66:69]
	v_mfma_f32_16x16x32_bf16 v[122:125], v[146:149], v[178:181], v[122:125]
	v_mfma_f32_16x16x32_bf16 v[126:129], v[170:173], v[178:181], v[126:129]
	v_mfma_f32_16x16x32_bf16 v[110:113], v[146:149], v[190:193], v[110:113]
	v_mfma_f32_16x16x32_bf16 v[102:105], v[170:173], v[190:193], v[102:105]
	v_mfma_f32_16x16x32_bf16 v[94:97], v[146:149], v[198:201], v[94:97]
	v_mfma_f32_16x16x32_bf16 v[86:89], v[170:173], v[198:201], v[86:89]
	v_mfma_f32_16x16x32_bf16 v[78:81], v[146:149], v[206:209], v[78:81]
	v_mfma_f32_16x16x32_bf16 v[70:73], v[170:173], v[206:209], v[70:73]
	v_mfma_f32_16x16x32_bf16 v[122:125], v[150:153], v[186:189], v[122:125]
	v_mfma_f32_16x16x32_bf16 v[126:129], v[174:177], v[186:189], v[126:129]
	v_mfma_f32_16x16x32_bf16 v[110:113], v[150:153], v[194:197], v[110:113]
	v_mfma_f32_16x16x32_bf16 v[102:105], v[174:177], v[194:197], v[102:105]
	v_mfma_f32_16x16x32_bf16 v[94:97], v[150:153], v[202:205], v[94:97]
	v_mfma_f32_16x16x32_bf16 v[86:89], v[174:177], v[202:205], v[86:89]
	v_mfma_f32_16x16x32_bf16 v[78:81], v[150:153], v[210:213], v[78:81]
	v_mfma_f32_16x16x32_bf16 v[70:73], v[174:177], v[210:213], v[70:73]
	s_barrier
	s_add_i32 s33, s36, s24
	s_mov_b32 m0, s33
	ds_read_b128 v[178:181], v184 offset:16384
	ds_read_b128 v[186:189], v184 offset:17408
	ds_read_b128 v[190:193], v184 offset:18432
	ds_read_b128 v[194:197], v184 offset:19456
	ds_read_b128 v[198:201], v184 offset:20480
	ds_read_b128 v[202:205], v184 offset:21504
	ds_read_b128 v[206:209], v184 offset:22528
	ds_read_b128 v[210:213], v184 offset:23552
	global_load_lds_dwordx4 v156, s[16:17]
	s_add_i32 m0, s33, 0x2000
	s_add_u32 s50, s16, 0x2b0000
	s_addc_u32 s51, s17, 0
	s_add_i32 s33, s37, s24
	global_load_lds_dwordx4 v160, s[16:17]
	s_mov_b32 m0, s33
	s_add_u32 s100, s20, 0x80
	s_addc_u32 s101, s21, 0
	global_load_lds_dwordx4 v156, s[50:51]
	s_add_i32 m0, s33, 0x2000
	s_nop 0
	global_load_lds_dwordx4 v160, s[50:51]
	s_mov_b32 m0, s25
	s_nop 0
	global_load_lds_dwordx4 v154, s[20:21]
	s_mov_b32 m0, s26
	s_nop 0
	global_load_lds_dwordx4 v158, s[20:21]
	s_waitcnt vmcnt(8)
	s_waitcnt lgkmcnt(0)
	s_barrier
	s_waitcnt lgkmcnt(0)
	v_mfma_f32_16x16x32_bf16 v[58:61], v[130:133], v[178:181], v[58:61]
	v_mfma_f32_16x16x32_bf16 v[54:57], v[138:141], v[178:181], v[54:57]
	v_mfma_f32_16x16x32_bf16 v[42:45], v[130:133], v[190:193], v[42:45]
	v_mfma_f32_16x16x32_bf16 v[34:37], v[138:141], v[190:193], v[34:37]
	v_mfma_f32_16x16x32_bf16 v[26:29], v[130:133], v[198:201], v[26:29]
	v_mfma_f32_16x16x32_bf16 v[18:21], v[138:141], v[198:201], v[18:21]
	v_mfma_f32_16x16x32_bf16 v[6:9], v[130:133], v[206:209], v[6:9]
	v_mfma_f32_16x16x32_bf16 v[2:5], v[138:141], v[206:209], v[2:5]
	v_mfma_f32_16x16x32_bf16 v[58:61], v[134:137], v[186:189], v[58:61]
	v_mfma_f32_16x16x32_bf16 v[54:57], v[142:145], v[186:189], v[54:57]
	v_mfma_f32_16x16x32_bf16 v[42:45], v[134:137], v[194:197], v[42:45]
	v_mfma_f32_16x16x32_bf16 v[34:37], v[142:145], v[194:197], v[34:37]
	v_mfma_f32_16x16x32_bf16 v[26:29], v[134:137], v[202:205], v[26:29]
	v_mfma_f32_16x16x32_bf16 v[18:21], v[142:145], v[202:205], v[18:21]
	v_mfma_f32_16x16x32_bf16 v[6:9], v[134:137], v[210:213], v[6:9]
	v_mfma_f32_16x16x32_bf16 v[2:5], v[142:145], v[210:213], v[2:5]
	v_mfma_f32_16x16x32_bf16 v[62:65], v[146:149], v[178:181], v[62:65]
	v_mfma_f32_16x16x32_bf16 v[50:53], v[170:173], v[178:181], v[50:53]
	v_mfma_f32_16x16x32_bf16 v[46:49], v[146:149], v[190:193], v[46:49]
	v_mfma_f32_16x16x32_bf16 v[38:41], v[170:173], v[190:193], v[38:41]
	v_mfma_f32_16x16x32_bf16 v[30:33], v[146:149], v[198:201], v[30:33]
	v_mfma_f32_16x16x32_bf16 v[22:25], v[170:173], v[198:201], v[22:25]
	v_mfma_f32_16x16x32_bf16 v[10:13], v[146:149], v[206:209], v[10:13]
	v_mfma_f32_16x16x32_bf16 v[14:17], v[170:173], v[206:209], v[14:17]
	v_mfma_f32_16x16x32_bf16 v[62:65], v[150:153], v[186:189], v[62:65]
	v_mfma_f32_16x16x32_bf16 v[50:53], v[174:177], v[186:189], v[50:53]
	v_mfma_f32_16x16x32_bf16 v[46:49], v[150:153], v[194:197], v[46:49]
	v_mfma_f32_16x16x32_bf16 v[38:41], v[174:177], v[194:197], v[38:41]
	v_mfma_f32_16x16x32_bf16 v[30:33], v[150:153], v[202:205], v[30:33]
	v_mfma_f32_16x16x32_bf16 v[22:25], v[174:177], v[202:205], v[22:25]
	v_mfma_f32_16x16x32_bf16 v[10:13], v[150:153], v[210:213], v[10:13]
	v_mfma_f32_16x16x32_bf16 v[14:17], v[174:177], v[210:213], v[14:17]
	s_barrier
; #define PG8_STAGE(bufoff, gbase, voff) do { _Pragma("unroll") for (int _i = 0; _i < 2; ++_i) \
;         __builtin_amdgcn_global_load_lds((const unsigned*)((const char*)(gbase) + (voff)[_i]), (PG8_LAS unsigned*)(lds + (bufoff) + ldsw + _i * 8192), 16, 0, 0); } while (0)
; #define PG8_LDA(dst, b, h) do { _Pragma("unroll") for (int m = 0; m < 4; ++m) _Pragma("unroll") for (int k = 0; k < 2; ++k) dst[m][k] = *(const PG8_LAS bf16x8*)(lds + PG8_SA(b, h) + aoff + m * 2048 + k * 1024); } while (0)
; #define PG8_LDB(dst, b, h) do { _Pragma("unroll") for (int n = 0; n < 2; ++n) _Pragma("unroll") for (int k = 0; k < 2; ++k) dst[n][k] = *(const PG8_LAS bf16x8*)(lds + PG8_SB(b, h) + boff + n * 2048 + k * 1024); } while (0)
; #define PG8_MMA(ai, bj, At, Bt) do { __builtin_amdgcn_s_setprio(1); _Pragma("unroll") for (int m = 0; m < 4; ++m) _Pragma("unroll") for (int n = 0; n < 2; ++n) _Pragma("unroll") for (int k = 0; k < 2; ++k) \
;         acc[ai][bj][m][n] = __builtin_amdgcn_mfma_f32_16x16x32_bf16(Bt[n][k], At[m][k], acc[ai][bj][m][n], 0, 0, 0); __builtin_amdgcn_s_setprio(0); } while (0)
; #define PG8_WAIT_V(n) asm volatile("s_waitcnt vmcnt(" #n ")" ::: "memory")
; #define PG8_WAIT_L(n) asm volatile("s_waitcnt lgkmcnt(" #n ")" ::: "memory")
; #define PG8_BAR __builtin_amdgcn_s_barrier()
; #define PG8_SCHED __builtin_amdgcn_sched_barrier(0)
; template <class Epi, class Sched, bool ALIGN_EPI = false, bool SP2 = false>
; __device__ __forceinline__ void gemm_phase(PG8_LAS unsigned char* lds, const Gemm g, const Sched& S, const Epi& E) {
;     ...
;             PG8_LDB(B0, 1, 0); PG8_LDB(B1, 1, 1); PG8_SCHED; PG8_LDA(At, 1, 0); PG8_STAGE(PG8_SA(0, 1), a2 + hstep, voffA);
;             PG8_WAIT_V(8); PG8_WAIT_L(0); PG8_BAR; PG8_MMA(0, 0, At, B0); PG8_MMA(0, 1, At, B1); PG8_BAR; PG8_SCHED;
;             PG8_LDA(At, 1, 1); PG8_STAGE(PG8_SB(1, 0), b3, voffB); PG8_STAGE(PG8_SB(1, 1), b3 + hstep, voffB); PG8_STAGE(PG8_SA(1, 0), a3, voffA);
;             PG8_WAIT_V(8); PG8_WAIT_L(0); PG8_BAR; PG8_MMA(1, 0, At, B0); PG8_MMA(1, 1, At, B1); PG8_BAR; PG8_SCHED;
	s_add_i32 s33, 0, 0x18000
	s_add_i32 s42, 0, 0x1c000
	ds_read_b128 v[130:133], v241 offset:32768
	ds_read_b128 v[134:137], v241 offset:33792
	ds_read_b128 v[138:141], v241 offset:34816
	ds_read_b128 v[142:145], v241 offset:35840
	ds_read_b128 v[146:149], v241 offset:49152
	ds_read_b128 v[150:153], v241 offset:50176
	ds_read_b128 v[170:173], v241 offset:51200
	ds_read_b128 v[174:177], v241 offset:52224
	s_add_u32 s20, s20, 0x2b0000
	s_addc_u32 s21, s21, 0
	s_mov_b32 m0, s27
	ds_read_b128 v[178:181], v184 offset:32768
	ds_read_b128 v[186:189], v184 offset:33792
	ds_read_b128 v[190:193], v184 offset:34816
	ds_read_b128 v[194:197], v184 offset:35840
	ds_read_b128 v[198:201], v184 offset:36864
	ds_read_b128 v[202:205], v184 offset:37888
	ds_read_b128 v[206:209], v184 offset:38912
	ds_read_b128 v[210:213], v184 offset:39936
	global_load_lds_dwordx4 v154, s[20:21]
	s_mov_b32 m0, s28
	s_nop 0
	global_load_lds_dwordx4 v158, s[20:21]
	s_waitcnt vmcnt(8)
	s_waitcnt lgkmcnt(0)
	s_barrier
	s_waitcnt lgkmcnt(0)
	v_mfma_f32_16x16x32_bf16 v[114:117], v[130:133], v[178:181], v[114:117]
	v_mfma_f32_16x16x32_bf16 v[118:121], v[138:141], v[178:181], v[118:121]
	v_mfma_f32_16x16x32_bf16 v[106:109], v[130:133], v[190:193], v[106:109]
	v_mfma_f32_16x16x32_bf16 v[98:101], v[138:141], v[190:193], v[98:101]
	v_mfma_f32_16x16x32_bf16 v[90:93], v[130:133], v[198:201], v[90:93]
	v_mfma_f32_16x16x32_bf16 v[82:85], v[138:141], v[198:201], v[82:85]
	v_mfma_f32_16x16x32_bf16 v[74:77], v[130:133], v[206:209], v[74:77]
	v_mfma_f32_16x16x32_bf16 v[66:69], v[138:141], v[206:209], v[66:69]
	v_mfma_f32_16x16x32_bf16 v[114:117], v[134:137], v[186:189], v[114:117]
	v_mfma_f32_16x16x32_bf16 v[118:121], v[142:145], v[186:189], v[118:121]
	v_mfma_f32_16x16x32_bf16 v[106:109], v[134:137], v[194:197], v[106:109]
	v_mfma_f32_16x16x32_bf16 v[98:101], v[142:145], v[194:197], v[98:101]
	v_mfma_f32_16x16x32_bf16 v[90:93], v[134:137], v[202:205], v[90:93]
	v_mfma_f32_16x16x32_bf16 v[82:85], v[142:145], v[202:205], v[82:85]
	v_mfma_f32_16x16x32_bf16 v[74:77], v[134:137], v[210:213], v[74:77]
	v_mfma_f32_16x16x32_bf16 v[66:69], v[142:145], v[210:213], v[66:69]
	v_mfma_f32_16x16x32_bf16 v[122:125], v[146:149], v[178:181], v[122:125]
	v_mfma_f32_16x16x32_bf16 v[126:129], v[170:173], v[178:181], v[126:129]
	v_mfma_f32_16x16x32_bf16 v[110:113], v[146:149], v[190:193], v[110:113]
	v_mfma_f32_16x16x32_bf16 v[102:105], v[170:173], v[190:193], v[102:105]
	v_mfma_f32_16x16x32_bf16 v[94:97], v[146:149], v[198:201], v[94:97]
	v_mfma_f32_16x16x32_bf16 v[86:89], v[170:173], v[198:201], v[86:89]
	v_mfma_f32_16x16x32_bf16 v[78:81], v[146:149], v[206:209], v[78:81]
	v_mfma_f32_16x16x32_bf16 v[70:73], v[170:173], v[206:209], v[70:73]
	v_mfma_f32_16x16x32_bf16 v[122:125], v[150:153], v[186:189], v[122:125]
	v_mfma_f32_16x16x32_bf16 v[126:129], v[174:177], v[186:189], v[126:129]
	v_mfma_f32_16x16x32_bf16 v[110:113], v[150:153], v[194:197], v[110:113]
	v_mfma_f32_16x16x32_bf16 v[102:105], v[174:177], v[194:197], v[102:105]
	v_mfma_f32_16x16x32_bf16 v[94:97], v[150:153], v[202:205], v[94:97]
	v_mfma_f32_16x16x32_bf16 v[86:89], v[174:177], v[202:205], v[86:89]
	v_mfma_f32_16x16x32_bf16 v[78:81], v[150:153], v[210:213], v[78:81]
	v_mfma_f32_16x16x32_bf16 v[70:73], v[174:177], v[210:213], v[70:73]
	s_barrier
	s_add_i32 s20, s33, s24
	s_add_i32 m0, s20, 0xffffff80
	ds_read_b128 v[178:181], v184 offset:49152
	ds_read_b128 v[186:189], v184 offset:50176
	ds_read_b128 v[190:193], v184 offset:51200
	ds_read_b128 v[194:197], v184 offset:52224
	ds_read_b128 v[198:201], v184 offset:53248
	ds_read_b128 v[202:205], v184 offset:54272
	ds_read_b128 v[206:209], v184 offset:55296
	ds_read_b128 v[210:213], v184 offset:56320
	global_load_lds_dwordx4 v156, s[16:17] offset:128
	s_add_i32 m0, s20, 0x1f80
	s_add_i32 s20, s42, s24
	global_load_lds_dwordx4 v160, s[16:17] offset:128
	s_add_u32 s16, s16, 0x2b0080
	s_addc_u32 s17, s17, 0
	s_mov_b32 m0, s20
	s_nop 0
	global_load_lds_dwordx4 v156, s[16:17]
	s_add_i32 m0, s20, 0x2000
	s_nop 0
	global_load_lds_dwordx4 v160, s[16:17]
	s_mov_b32 m0, s30
	s_nop 0
	global_load_lds_dwordx4 v154, s[100:101]
	s_mov_b32 m0, s31
	s_nop 0
	global_load_lds_dwordx4 v158, s[100:101]
	s_waitcnt vmcnt(8)
	s_waitcnt lgkmcnt(0)
	s_barrier
	s_waitcnt lgkmcnt(0)
	v_mfma_f32_16x16x32_bf16 v[58:61], v[130:133], v[178:181], v[58:61]
	v_mfma_f32_16x16x32_bf16 v[54:57], v[138:141], v[178:181], v[54:57]
	v_mfma_f32_16x16x32_bf16 v[42:45], v[130:133], v[190:193], v[42:45]
	v_mfma_f32_16x16x32_bf16 v[34:37], v[138:141], v[190:193], v[34:37]
	v_mfma_f32_16x16x32_bf16 v[26:29], v[130:133], v[198:201], v[26:29]
	v_mfma_f32_16x16x32_bf16 v[18:21], v[138:141], v[198:201], v[18:21]
	v_mfma_f32_16x16x32_bf16 v[6:9], v[130:133], v[206:209], v[6:9]
	v_mfma_f32_16x16x32_bf16 v[2:5], v[138:141], v[206:209], v[2:5]
	v_mfma_f32_16x16x32_bf16 v[58:61], v[134:137], v[186:189], v[58:61]
	v_mfma_f32_16x16x32_bf16 v[54:57], v[142:145], v[186:189], v[54:57]
	v_mfma_f32_16x16x32_bf16 v[42:45], v[134:137], v[194:197], v[42:45]
	v_mfma_f32_16x16x32_bf16 v[34:37], v[142:145], v[194:197], v[34:37]
	v_mfma_f32_16x16x32_bf16 v[26:29], v[134:137], v[202:205], v[26:29]
	v_mfma_f32_16x16x32_bf16 v[18:21], v[142:145], v[202:205], v[18:21]
	v_mfma_f32_16x16x32_bf16 v[6:9], v[134:137], v[210:213], v[6:9]
	v_mfma_f32_16x16x32_bf16 v[2:5], v[142:145], v[210:213], v[2:5]
	v_mfma_f32_16x16x32_bf16 v[62:65], v[146:149], v[178:181], v[62:65]
	v_mfma_f32_16x16x32_bf16 v[50:53], v[170:173], v[178:181], v[50:53]
	v_mfma_f32_16x16x32_bf16 v[46:49], v[146:149], v[190:193], v[46:49]
	v_mfma_f32_16x16x32_bf16 v[38:41], v[170:173], v[190:193], v[38:41]
	v_mfma_f32_16x16x32_bf16 v[30:33], v[146:149], v[198:201], v[30:33]
	v_mfma_f32_16x16x32_bf16 v[22:25], v[170:173], v[198:201], v[22:25]
	v_mfma_f32_16x16x32_bf16 v[10:13], v[146:149], v[206:209], v[10:13]
	v_mfma_f32_16x16x32_bf16 v[14:17], v[170:173], v[206:209], v[14:17]
	v_mfma_f32_16x16x32_bf16 v[62:65], v[150:153], v[186:189], v[62:65]
	v_mfma_f32_16x16x32_bf16 v[50:53], v[174:177], v[186:189], v[50:53]
	v_mfma_f32_16x16x32_bf16 v[46:49], v[150:153], v[194:197], v[46:49]
	v_mfma_f32_16x16x32_bf16 v[38:41], v[174:177], v[194:197], v[38:41]
	v_mfma_f32_16x16x32_bf16 v[30:33], v[150:153], v[202:205], v[30:33]
	v_mfma_f32_16x16x32_bf16 v[22:25], v[174:177], v[202:205], v[22:25]
	v_mfma_f32_16x16x32_bf16 v[10:13], v[150:153], v[210:213], v[10:13]
	v_mfma_f32_16x16x32_bf16 v[14:17], v[174:177], v[210:213], v[14:17]
	s_barrier
	s_add_i32 s48, s48, 2
	s_add_u32 s18, s18, 0x100
	s_addc_u32 s19, s19, 0
	s_add_u32 s46, s46, 0x100
	s_addc_u32 s47, s47, 0
	s_cmpk_gt_u32 s48, 0xa9
	s_cbranch_scc0 .LBB0_1801
	s_and_b64 vcc, exec, s[12:13]
	s_cbranch_vccz .LBB0_1804
	s_barrier
